# MFMA order in K-loop blocks: the two k-steps of one accumulator back to back (bit-identical)
# speedup vs baseline: 1.0116x; 1.0116x over previous
; #define PG8_STAGE(bufoff, gbase, voff) do { _Pragma("unroll") for (int _i = 0; _i < 2; ++_i) \
;         __builtin_amdgcn_global_load_lds((const unsigned*)((const char*)(gbase) + (voff)[_i]), (PG8_LAS unsigned*)(lds + (bufoff) + ldsw + _i * 8192), 16, 0, AUX_A); } while (0)
; #define PG8_STAGEB(bufoff, gbase, voff) do { _Pragma("unroll") for (int _i = 0; _i < 2; ++_i) \
;         __builtin_amdgcn_global_load_lds((const unsigned*)((const char*)(gbase) + (voff)[_i]), (PG8_LAS unsigned*)(lds + (bufoff) + ldsw + _i * 8192), 16, 0, AUX_B); } while (0)
; #define PG8_LDA(dst, b, h) do { _Pragma("unroll") for (int m = 0; m < 4; ++m) _Pragma("unroll") for (int k = 0; k < 2; ++k) dst[m][k] = *(const PG8_LAS bf16x8*)(lds + PG8_SA(b, h) + aoff + m * 2048 + k * 1024); } while (0)
; #define PG8_LDB(dst, b, h) do { _Pragma("unroll") for (int n = 0; n < 2; ++n) _Pragma("unroll") for (int k = 0; k < 2; ++k) dst[n][k] = *(const PG8_LAS bf16x8*)(lds + PG8_SB(b, h) + boff + n * 2048 + k * 1024); } while (0)
; #define PG8_WAIT_V(n) asm volatile("s_waitcnt vmcnt(" #n ")" ::: "memory")
; #define PG8_WAIT_L(n) asm volatile("s_waitcnt lgkmcnt(" #n ")" ::: "memory")
; template <class Epi, class Sched, bool ALIGN_EPI = false, bool SP2 = false>
; __device__ __forceinline__ void gemm_phase(PG8_LAS unsigned char* lds, const Gemm g, const Sched& S, const Epi& E) {
;     ...
;         const char* nAr = has_next ? nA + (size_t)nxt.krot * kstep : PG8_KP(cA, 0, rot, nt); const char* nBr = has_next ? nB + (size_t)nxt.krot * kstep : PG8_KP(cB, 0, rot, nt);
;         for (int t = 0; t < nt; t += 2) {
;             const bool last = (t == nt - 2);
;             const char* a1 = PG8_KP(cA, t + 1, rot, nt);
;             const char* a2 = last ? nAr : PG8_KP(cA, t + 2, rot, nt); const char* b2 = last ? nBr : PG8_KP(cB, t + 2, rot, nt);
;             const char* a3 = a2 + kstep; const char* b3 = b2 + kstep;
;             if (last && has_next) S.a_ready(nxt);
;             if constexpr (SP2) {
;             PG8_LDB(B0, 0, 0); PG8_LDB(B1, 0, 1); PG8_SCHED; PG8_LDA(At, 0, 0); PG8_STAGE(PG8_SA(1, 1), a1 + hstep, voffA);
;             PG8_WAIT_V(8); PG8_WAIT_L(0); PG8_BAR; PG8_MMA(0, 0, At, B0); PG8_MMA(0, 1, At, B1); PG8_BAR; PG8_SCHED;
;             PG8_LDA(At, 0, 1); PG8_STAGEB(PG8_SB(0, 0), b2, voffB); PG8_STAGEB(PG8_SB(0, 1), b2 + hstep, voffB); PG8_STAGE(PG8_SA(0, 0), a2, voffA);
.LBB0_270:
	s_add_i32 s81, s29, 2
	s_cmp_lt_u32 s29, 30
	s_cselect_b32 s0, 0, 0xffffffe0
	s_add_i32 s0, s81, s0
	s_ashr_i32 s1, s0, 31
	s_lshl_b64 s[0:1], s[0:1], 7
	s_add_u32 s42, s40, s0
	s_addc_u32 s43, s41, s1
	s_add_u32 s0, s38, s0
	s_addc_u32 s1, s39, s1
	s_cmp_eq_u32 s29, 30
	s_cselect_b32 s59, s49, s43
	s_cselect_b32 s58, s51, s42
	s_cselect_b32 s61, vcc_lo, s1
	s_cselect_b32 s60, vcc_hi, s0
	s_add_i32 s43, 0, 0x10000
	s_add_i32 s97, s43, s70
	s_add_i32 s46, 0, 0x14000
	s_add_i32 m0, s96, 0xc000
	s_add_i32 s69, s96, 0xe000
	s_add_i32 s84, s97, 0x2000
	s_add_u32 s62, s60, 0x80000
	s_addc_u32 s63, s61, 0
	s_add_i32 s4, s46, s70
	v_add_u32_e32 v148, s43, v221
	v_add_u32_e32 v164, s46, v221
	s_add_i32 s5, s4, 0x2000
	s_add_i32 s1, 0, 0x18000
	s_add_i32 s47, 0, 0x1c000
	ds_read_b128 v[136:139], v148
	ds_read_b128 v[140:143], v148 offset:1024
	ds_read_b128 v[144:147], v148 offset:2048
	ds_read_b128 v[148:151], v148 offset:3072
	ds_read_b128 v[152:155], v164
	ds_read_b128 v[156:159], v164 offset:1024
	ds_read_b128 v[160:163], v164 offset:2048
	ds_read_b128 v[164:167], v164 offset:3072
	s_add_u32 s56, s58, 0x80000
	s_addc_u32 s57, s59, 0
	s_add_i32 s0, s1, s70
	s_add_i32 s89, s0, 0x2000
	s_add_u32 s42, s60, 0x80080
	s_addc_u32 s43, s61, 0
	s_add_i32 s46, s47, s70
	s_add_i32 s92, s46, 0x2000
	s_cmp_gt_u32 s29, 29
	ds_read_b128 v[192:195], v222
	ds_read_b128 v[196:199], v222 offset:1024
	ds_read_b128 v[200:203], v222 offset:2048
	ds_read_b128 v[224:227], v222 offset:3072
	ds_read_b128 v[228:231], v222 offset:4096
	ds_read_b128 v[232:235], v222 offset:5120
	ds_read_b128 v[236:239], v222 offset:6144
	ds_read_b128 v[240:243], v222 offset:7168
	global_load_lds_dwordx4 v[134:135], off
	s_mov_b32 m0, s69
	s_nop 0
	global_load_lds_dwordx4 v[132:133], off
	s_waitcnt vmcnt(8)
	s_waitcnt lgkmcnt(0)
	s_barrier
	s_setprio 1
	s_waitcnt lgkmcnt(0)
	v_mfma_f32_16x16x32_bf16 v[128:131], v[136:139], v[192:195], v[128:131]
	v_mfma_f32_16x16x32_bf16 v[128:131], v[140:143], v[196:199], v[128:131]
	v_mfma_f32_16x16x32_bf16 v[124:127], v[144:147], v[192:195], v[124:127]
	v_mfma_f32_16x16x32_bf16 v[124:127], v[148:151], v[196:199], v[124:127]
	v_mfma_f32_16x16x32_bf16 v[112:115], v[136:139], v[200:203], v[112:115]
	v_mfma_f32_16x16x32_bf16 v[112:115], v[140:143], v[224:227], v[112:115]
	v_mfma_f32_16x16x32_bf16 v[108:111], v[144:147], v[200:203], v[108:111]
	v_mfma_f32_16x16x32_bf16 v[108:111], v[148:151], v[224:227], v[108:111]
	v_mfma_f32_16x16x32_bf16 v[94:97], v[136:139], v[228:231], v[94:97]
	v_mfma_f32_16x16x32_bf16 v[94:97], v[140:143], v[232:235], v[94:97]
	v_mfma_f32_16x16x32_bf16 v[90:93], v[144:147], v[228:231], v[90:93]
	v_mfma_f32_16x16x32_bf16 v[90:93], v[148:151], v[232:235], v[90:93]
	v_mfma_f32_16x16x32_bf16 v[78:81], v[136:139], v[236:239], v[78:81]
	v_mfma_f32_16x16x32_bf16 v[78:81], v[140:143], v[240:243], v[78:81]
	v_mfma_f32_16x16x32_bf16 v[74:77], v[144:147], v[236:239], v[74:77]
	v_mfma_f32_16x16x32_bf16 v[74:77], v[148:151], v[240:243], v[74:77]
	s_setprio 0
	s_setprio 1
	v_mfma_f32_16x16x32_bf16 v[120:123], v[152:155], v[192:195], v[120:123]
	v_mfma_f32_16x16x32_bf16 v[120:123], v[156:159], v[196:199], v[120:123]
	v_mfma_f32_16x16x32_bf16 v[116:119], v[160:163], v[192:195], v[116:119]
	v_mfma_f32_16x16x32_bf16 v[116:119], v[164:167], v[196:199], v[116:119]
	v_mfma_f32_16x16x32_bf16 v[104:107], v[152:155], v[200:203], v[104:107]
	v_mfma_f32_16x16x32_bf16 v[104:107], v[156:159], v[224:227], v[104:107]
	v_mfma_f32_16x16x32_bf16 v[100:103], v[160:163], v[200:203], v[100:103]
	v_mfma_f32_16x16x32_bf16 v[100:103], v[164:167], v[224:227], v[100:103]
	v_mfma_f32_16x16x32_bf16 v[86:89], v[152:155], v[228:231], v[86:89]
	v_mfma_f32_16x16x32_bf16 v[86:89], v[156:159], v[232:235], v[86:89]
	v_mfma_f32_16x16x32_bf16 v[82:85], v[160:163], v[228:231], v[82:85]
	v_mfma_f32_16x16x32_bf16 v[82:85], v[164:167], v[232:235], v[82:85]
	v_mfma_f32_16x16x32_bf16 v[70:73], v[152:155], v[236:239], v[70:73]
	v_mfma_f32_16x16x32_bf16 v[70:73], v[156:159], v[240:243], v[70:73]
	v_mfma_f32_16x16x32_bf16 v[66:69], v[160:163], v[236:239], v[66:69]
	v_mfma_f32_16x16x32_bf16 v[66:69], v[164:167], v[240:243], v[66:69]
	s_setprio 0
	s_barrier
	s_mov_b32 m0, s97
	v_lshl_add_u64 v[244:245], s[60:61], 0, v[184:185]
	ds_read_b128 v[192:195], v222 offset:16384
	ds_read_b128 v[196:199], v222 offset:17408
	ds_read_b128 v[200:203], v222 offset:18432
	ds_read_b128 v[224:227], v222 offset:19456
	ds_read_b128 v[228:231], v222 offset:20480
	ds_read_b128 v[232:235], v222 offset:21504
	ds_read_b128 v[236:239], v222 offset:22528
	ds_read_b128 v[240:243], v222 offset:23552
	global_load_lds_dwordx4 v[244:245], off
	v_lshl_add_u64 v[246:247], s[60:61], 0, v[180:181]
	s_mov_b32 m0, s84
	v_lshl_add_u64 v[212:213], s[62:63], 0, v[184:185]
	global_load_lds_dwordx4 v[246:247], off
	s_mov_b32 m0, s4
	v_lshl_add_u64 v[172:173], s[58:59], 0, v[182:183]
	global_load_lds_dwordx4 v[212:213], off
	v_lshl_add_u64 v[212:213], s[62:63], 0, v[180:181]
	s_mov_b32 m0, s5
	s_nop 0
	global_load_lds_dwordx4 v[212:213], off
	v_lshl_add_u64 v[212:213], s[58:59], 0, v[186:187]
	s_mov_b32 m0, s96
	s_nop 0
	global_load_lds_dwordx4 v[212:213], off
	s_mov_b32 m0, s71
	s_nop 0
	global_load_lds_dwordx4 v[172:173], off
	s_waitcnt vmcnt(8)
	s_waitcnt lgkmcnt(0)
	s_barrier
; #define PG8_STAGE(bufoff, gbase, voff) do { _Pragma("unroll") for (int _i = 0; _i < 2; ++_i) \
;         __builtin_amdgcn_global_load_lds((const unsigned*)((const char*)(gbase) + (voff)[_i]), (PG8_LAS unsigned*)(lds + (bufoff) + ldsw + _i * 8192), 16, 0, AUX_A); } while (0)
; #define PG8_LDA(dst, b, h) do { _Pragma("unroll") for (int m = 0; m < 4; ++m) _Pragma("unroll") for (int k = 0; k < 2; ++k) dst[m][k] = *(const PG8_LAS bf16x8*)(lds + PG8_SA(b, h) + aoff + m * 2048 + k * 1024); } while (0)
; #define PG8_LDB(dst, b, h) do { _Pragma("unroll") for (int n = 0; n < 2; ++n) _Pragma("unroll") for (int k = 0; k < 2; ++k) dst[n][k] = *(const PG8_LAS bf16x8*)(lds + PG8_SB(b, h) + boff + n * 2048 + k * 1024); } while (0)
; #define PG8_MMA(ai, bj, At, Bt) do { __builtin_amdgcn_s_setprio(1); _Pragma("unroll") for (int m = 0; m < 4; ++m) _Pragma("unroll") for (int n = 0; n < 2; ++n) _Pragma("unroll") for (int k = 0; k < 2; ++k) \
;         acc[ai][bj][m][n] = __builtin_amdgcn_mfma_f32_16x16x32_bf16(Bt[n][k], At[m][k], acc[ai][bj][m][n], 0, 0, 0); __builtin_amdgcn_s_setprio(0); } while (0)
; #define PG8_WAIT_V(n) asm volatile("s_waitcnt vmcnt(" #n ")" ::: "memory")
; #define PG8_WAIT_L(n) asm volatile("s_waitcnt lgkmcnt(" #n ")" ::: "memory")
; #define PG8_BAR __builtin_amdgcn_s_barrier()
; #define PG8_SCHED __builtin_amdgcn_sched_barrier(0)
; template <class Epi, class Sched, bool ALIGN_EPI = false, bool SP2 = false>
; __device__ __forceinline__ void gemm_phase(PG8_LAS unsigned char* lds, const Gemm g, const Sched& S, const Epi& E) {
;     ...
;             PG8_WAIT_V(8); PG8_WAIT_L(0); PG8_BAR; PG8_MMA(1, 0, At, B0); PG8_MMA(1, 1, At, B1); PG8_BAR; PG8_SCHED;
;             PG8_LDB(B0, 1, 0); PG8_LDB(B1, 1, 1); PG8_SCHED; PG8_LDA(At, 1, 0); PG8_STAGE(PG8_SA(0, 1), a2 + hstep, voffA);
;             PG8_WAIT_V(8); PG8_WAIT_L(0); PG8_BAR; PG8_MMA(0, 0, At, B0); PG8_MMA(0, 1, At, B1); PG8_BAR; PG8_SCHED;
	s_setprio 1
	s_waitcnt lgkmcnt(0)
	v_mfma_f32_16x16x32_bf16 v[62:65], v[136:139], v[192:195], v[62:65]
	v_mfma_f32_16x16x32_bf16 v[62:65], v[140:143], v[196:199], v[62:65]
	v_mfma_f32_16x16x32_bf16 v[58:61], v[144:147], v[192:195], v[58:61]
	v_mfma_f32_16x16x32_bf16 v[58:61], v[148:151], v[196:199], v[58:61]
	v_mfma_f32_16x16x32_bf16 v[46:49], v[136:139], v[200:203], v[46:49]
	v_mfma_f32_16x16x32_bf16 v[46:49], v[140:143], v[224:227], v[46:49]
	v_mfma_f32_16x16x32_bf16 v[42:45], v[144:147], v[200:203], v[42:45]
	v_mfma_f32_16x16x32_bf16 v[42:45], v[148:151], v[224:227], v[42:45]
	v_mfma_f32_16x16x32_bf16 v[30:33], v[136:139], v[228:231], v[30:33]
	v_mfma_f32_16x16x32_bf16 v[30:33], v[140:143], v[232:235], v[30:33]
	v_mfma_f32_16x16x32_bf16 v[26:29], v[144:147], v[228:231], v[26:29]
	v_mfma_f32_16x16x32_bf16 v[26:29], v[148:151], v[232:235], v[26:29]
	v_mfma_f32_16x16x32_bf16 v[14:17], v[136:139], v[236:239], v[14:17]
	v_mfma_f32_16x16x32_bf16 v[14:17], v[140:143], v[240:243], v[14:17]
	v_mfma_f32_16x16x32_bf16 v[10:13], v[144:147], v[236:239], v[10:13]
	v_mfma_f32_16x16x32_bf16 v[10:13], v[148:151], v[240:243], v[10:13]
	s_setprio 0
	s_setprio 1
	v_mfma_f32_16x16x32_bf16 v[54:57], v[152:155], v[192:195], v[54:57]
	v_mfma_f32_16x16x32_bf16 v[54:57], v[156:159], v[196:199], v[54:57]
	v_mfma_f32_16x16x32_bf16 v[50:53], v[160:163], v[192:195], v[50:53]
	v_mfma_f32_16x16x32_bf16 v[50:53], v[164:167], v[196:199], v[50:53]
	v_mfma_f32_16x16x32_bf16 v[38:41], v[152:155], v[200:203], v[38:41]
	v_mfma_f32_16x16x32_bf16 v[38:41], v[156:159], v[224:227], v[38:41]
	v_mfma_f32_16x16x32_bf16 v[34:37], v[160:163], v[200:203], v[34:37]
	v_mfma_f32_16x16x32_bf16 v[34:37], v[164:167], v[224:227], v[34:37]
	v_mfma_f32_16x16x32_bf16 v[22:25], v[152:155], v[228:231], v[22:25]
	v_mfma_f32_16x16x32_bf16 v[22:25], v[156:159], v[232:235], v[22:25]
	v_mfma_f32_16x16x32_bf16 v[18:21], v[160:163], v[228:231], v[18:21]
	v_mfma_f32_16x16x32_bf16 v[18:21], v[164:167], v[232:235], v[18:21]
	v_mfma_f32_16x16x32_bf16 v[6:9], v[152:155], v[236:239], v[6:9]
	v_mfma_f32_16x16x32_bf16 v[6:9], v[156:159], v[240:243], v[6:9]
	v_mfma_f32_16x16x32_bf16 v[2:5], v[160:163], v[236:239], v[2:5]
	v_mfma_f32_16x16x32_bf16 v[2:5], v[164:167], v[240:243], v[2:5]
	s_setprio 0
	s_barrier
	v_add_u32_e32 v148, s1, v221
	v_add_u32_e32 v164, s47, v221
	ds_read_b128 v[136:139], v148
	ds_read_b128 v[140:143], v148 offset:1024
	ds_read_b128 v[144:147], v148 offset:2048
	ds_read_b128 v[148:151], v148 offset:3072
	ds_read_b128 v[152:155], v164
	ds_read_b128 v[156:159], v164 offset:1024
	ds_read_b128 v[160:163], v164 offset:2048
	ds_read_b128 v[164:167], v164 offset:3072
	s_mov_b32 m0, s33
	v_lshl_add_u64 v[168:169], s[56:57], 0, v[186:187]
	ds_read_b128 v[192:195], v222 offset:32768
	ds_read_b128 v[196:199], v222 offset:33792
	ds_read_b128 v[200:203], v222 offset:34816
	ds_read_b128 v[224:227], v222 offset:35840
	ds_read_b128 v[228:231], v222 offset:36864
	ds_read_b128 v[232:235], v222 offset:37888
	ds_read_b128 v[236:239], v222 offset:38912
	ds_read_b128 v[240:243], v222 offset:39936
	global_load_lds_dwordx4 v[168:169], off
	v_lshl_add_u64 v[168:169], s[56:57], 0, v[182:183]
	s_mov_b32 m0, s30
	s_nop 0
	global_load_lds_dwordx4 v[168:169], off
	s_waitcnt vmcnt(8)
	s_waitcnt lgkmcnt(0)
	s_barrier
	s_setprio 1
	s_waitcnt lgkmcnt(0)
	v_mfma_f32_16x16x32_bf16 v[128:131], v[136:139], v[192:195], v[128:131]
	v_mfma_f32_16x16x32_bf16 v[128:131], v[140:143], v[196:199], v[128:131]
	v_mfma_f32_16x16x32_bf16 v[124:127], v[144:147], v[192:195], v[124:127]
	v_mfma_f32_16x16x32_bf16 v[124:127], v[148:151], v[196:199], v[124:127]
	v_mfma_f32_16x16x32_bf16 v[112:115], v[136:139], v[200:203], v[112:115]
	v_mfma_f32_16x16x32_bf16 v[112:115], v[140:143], v[224:227], v[112:115]
	v_mfma_f32_16x16x32_bf16 v[108:111], v[144:147], v[200:203], v[108:111]
	v_mfma_f32_16x16x32_bf16 v[108:111], v[148:151], v[224:227], v[108:111]
	v_mfma_f32_16x16x32_bf16 v[94:97], v[136:139], v[228:231], v[94:97]
	v_mfma_f32_16x16x32_bf16 v[94:97], v[140:143], v[232:235], v[94:97]
	v_mfma_f32_16x16x32_bf16 v[90:93], v[144:147], v[228:231], v[90:93]
	v_mfma_f32_16x16x32_bf16 v[90:93], v[148:151], v[232:235], v[90:93]
	v_mfma_f32_16x16x32_bf16 v[78:81], v[136:139], v[236:239], v[78:81]
	v_mfma_f32_16x16x32_bf16 v[78:81], v[140:143], v[240:243], v[78:81]
	v_mfma_f32_16x16x32_bf16 v[74:77], v[144:147], v[236:239], v[74:77]
	v_mfma_f32_16x16x32_bf16 v[74:77], v[148:151], v[240:243], v[74:77]
	s_setprio 0
	s_setprio 1
	v_mfma_f32_16x16x32_bf16 v[120:123], v[152:155], v[192:195], v[120:123]
	v_mfma_f32_16x16x32_bf16 v[120:123], v[156:159], v[196:199], v[120:123]
	v_mfma_f32_16x16x32_bf16 v[116:119], v[160:163], v[192:195], v[116:119]
	v_mfma_f32_16x16x32_bf16 v[116:119], v[164:167], v[196:199], v[116:119]
	v_mfma_f32_16x16x32_bf16 v[104:107], v[152:155], v[200:203], v[104:107]
	v_mfma_f32_16x16x32_bf16 v[104:107], v[156:159], v[224:227], v[104:107]
	v_mfma_f32_16x16x32_bf16 v[100:103], v[160:163], v[200:203], v[100:103]
	v_mfma_f32_16x16x32_bf16 v[100:103], v[164:167], v[224:227], v[100:103]
	v_mfma_f32_16x16x32_bf16 v[86:89], v[152:155], v[228:231], v[86:89]
	v_mfma_f32_16x16x32_bf16 v[86:89], v[156:159], v[232:235], v[86:89]
	v_mfma_f32_16x16x32_bf16 v[82:85], v[160:163], v[228:231], v[82:85]
	v_mfma_f32_16x16x32_bf16 v[82:85], v[164:167], v[232:235], v[82:85]
	v_mfma_f32_16x16x32_bf16 v[70:73], v[152:155], v[236:239], v[70:73]
	v_mfma_f32_16x16x32_bf16 v[70:73], v[156:159], v[240:243], v[70:73]
	v_mfma_f32_16x16x32_bf16 v[66:69], v[160:163], v[236:239], v[66:69]
	v_mfma_f32_16x16x32_bf16 v[66:69], v[164:167], v[240:243], v[66:69]
	s_setprio 0
	s_barrier
; #define PG8_STAGE(bufoff, gbase, voff) do { _Pragma("unroll") for (int _i = 0; _i < 2; ++_i) \
;         __builtin_amdgcn_global_load_lds((const unsigned*)((const char*)(gbase) + (voff)[_i]), (PG8_LAS unsigned*)(lds + (bufoff) + ldsw + _i * 8192), 16, 0, AUX_A); } while (0)
; #define PG8_STAGEB(bufoff, gbase, voff) do { _Pragma("unroll") for (int _i = 0; _i < 2; ++_i) \
;         __builtin_amdgcn_global_load_lds((const unsigned*)((const char*)(gbase) + (voff)[_i]), (PG8_LAS unsigned*)(lds + (bufoff) + ldsw + _i * 8192), 16, 0, AUX_B); } while (0)
; template <class Epi, class Sched, bool ALIGN_EPI = false, bool SP2 = false>
; __device__ __forceinline__ void gemm_phase(PG8_LAS unsigned char* lds, const Gemm g, const Sched& S, const Epi& E) {
;     ...
;             PG8_LDA(At, 1, 1); PG8_STAGEB(PG8_SB(1, 0), b3, voffB); PG8_STAGEB(PG8_SB(1, 1), b3 + hstep, voffB); PG8_STAGE(PG8_SA(1, 0), a3, voffA);
;             PG8_WAIT_V(8); PG8_WAIT_L(0); PG8_BAR; PG8_MMA(1, 0, At, B0); PG8_MMA(1, 1, At, B1); PG8_BAR; PG8_SCHED;
;             } else {
;             PG8_LDB(B0, 0, 0); PG8_SCHED; PG8_LDA(At, 0, 0); PG8_STAGE(PG8_SA(1, 1), a1 + hstep, voffA);
;             PG8_WAIT_L(8); PG8_BAR; PG8_WAIT_L(0); PG8_MMA(0, 0, At, B0); PG8_BAR; PG8_SCHED;
;             PG8_LDB(B1, 0, 1); PG8_STAGEB(PG8_SB(0, 0), b2, voffB);
;             PG8_BAR; PG8_WAIT_L(0); PG8_MMA(0, 1, At, B1); PG8_BAR;
;             PG8_LDA(At, 0, 1); PG8_STAGE(PG8_SA(0, 0), a2, voffA);
;             PG8_BAR; PG8_WAIT_L(0); PG8_MMA(1, 0, At, B0); PG8_BAR; PG8_SCHED;
;             PG8_STAGEB(PG8_SB(0, 1), b2 + hstep, voffB);
;             PG8_WAIT_V(6); PG8_BAR; PG8_MMA(1, 1, At, B1); PG8_BAR;
;             PG8_LDB(B0, 1, 0); PG8_SCHED; PG8_LDA(At, 1, 0); PG8_STAGE(PG8_SA(0, 1), a2 + hstep, voffA);
;             PG8_WAIT_L(8); PG8_BAR; PG8_WAIT_L(0); PG8_MMA(0, 0, At, B0); PG8_BAR; PG8_SCHED;
;             PG8_LDB(B1, 1, 1); PG8_STAGEB(PG8_SB(1, 0), b3, voffB);
;             PG8_BAR; PG8_WAIT_L(0); PG8_MMA(0, 1, At, B1); PG8_BAR;
;             PG8_LDA(At, 1, 1); PG8_STAGE(PG8_SA(1, 0), a3, voffA);
;             PG8_BAR; PG8_WAIT_L(0); PG8_MMA(1, 0, At, B0); PG8_BAR; PG8_SCHED;
;             PG8_STAGEB(PG8_SB(1, 1), b3 + hstep, voffB);
;             PG8_WAIT_V(6); PG8_BAR; PG8_MMA(1, 1, At, B1); PG8_BAR;
;             }
;         }
;         if constexpr (ALIGN_EPI) { if (wr == 0) PG8_BAR; }
	s_mov_b32 m0, s0
	v_lshl_add_u64 v[168:169], v[244:245], 0, s[76:77]
	ds_read_b128 v[192:195], v222 offset:49152
	ds_read_b128 v[196:199], v222 offset:50176
	ds_read_b128 v[200:203], v222 offset:51200
	ds_read_b128 v[224:227], v222 offset:52224
	ds_read_b128 v[228:231], v222 offset:53248
	ds_read_b128 v[232:235], v222 offset:54272
	ds_read_b128 v[236:239], v222 offset:55296
	ds_read_b128 v[240:243], v222 offset:56320
	global_load_lds_dwordx4 v[168:169], off
	v_lshl_add_u64 v[168:169], v[246:247], 0, s[76:77]
	s_mov_b32 m0, s89
	s_nop 0
	global_load_lds_dwordx4 v[168:169], off
	v_lshl_add_u64 v[168:169], s[42:43], 0, v[184:185]
	s_mov_b32 m0, s46
	s_nop 0
	global_load_lds_dwordx4 v[168:169], off
	v_lshl_add_u64 v[168:169], s[42:43], 0, v[180:181]
	s_mov_b32 m0, s92
	s_nop 0
	global_load_lds_dwordx4 v[168:169], off
	v_lshl_add_u64 v[168:169], v[212:213], 0, s[76:77]
	s_mov_b32 m0, s90
	s_nop 0
	global_load_lds_dwordx4 v[168:169], off
	v_lshl_add_u64 v[168:169], v[172:173], 0, s[76:77]
	s_mov_b32 m0, s91
	s_nop 0
	global_load_lds_dwordx4 v[168:169], off
	s_waitcnt vmcnt(8)
	s_waitcnt lgkmcnt(0)
	s_barrier
	s_setprio 1
	s_waitcnt lgkmcnt(0)
	v_mfma_f32_16x16x32_bf16 v[62:65], v[136:139], v[192:195], v[62:65]
	v_mfma_f32_16x16x32_bf16 v[62:65], v[140:143], v[196:199], v[62:65]
	v_mfma_f32_16x16x32_bf16 v[58:61], v[144:147], v[192:195], v[58:61]
	v_mfma_f32_16x16x32_bf16 v[58:61], v[148:151], v[196:199], v[58:61]
	v_mfma_f32_16x16x32_bf16 v[46:49], v[136:139], v[200:203], v[46:49]
	v_mfma_f32_16x16x32_bf16 v[46:49], v[140:143], v[224:227], v[46:49]
	v_mfma_f32_16x16x32_bf16 v[42:45], v[144:147], v[200:203], v[42:45]
	v_mfma_f32_16x16x32_bf16 v[42:45], v[148:151], v[224:227], v[42:45]
	v_mfma_f32_16x16x32_bf16 v[30:33], v[136:139], v[228:231], v[30:33]
	v_mfma_f32_16x16x32_bf16 v[30:33], v[140:143], v[232:235], v[30:33]
	v_mfma_f32_16x16x32_bf16 v[26:29], v[144:147], v[228:231], v[26:29]
	v_mfma_f32_16x16x32_bf16 v[26:29], v[148:151], v[232:235], v[26:29]
	v_mfma_f32_16x16x32_bf16 v[14:17], v[136:139], v[236:239], v[14:17]
	v_mfma_f32_16x16x32_bf16 v[14:17], v[140:143], v[240:243], v[14:17]
	v_mfma_f32_16x16x32_bf16 v[10:13], v[144:147], v[236:239], v[10:13]
	v_mfma_f32_16x16x32_bf16 v[10:13], v[148:151], v[240:243], v[10:13]
	s_setprio 0
	s_setprio 1
	v_mfma_f32_16x16x32_bf16 v[54:57], v[152:155], v[192:195], v[54:57]
	v_mfma_f32_16x16x32_bf16 v[54:57], v[156:159], v[196:199], v[54:57]
	v_mfma_f32_16x16x32_bf16 v[50:53], v[160:163], v[192:195], v[50:53]
	v_mfma_f32_16x16x32_bf16 v[50:53], v[164:167], v[196:199], v[50:53]
	v_mfma_f32_16x16x32_bf16 v[38:41], v[152:155], v[200:203], v[38:41]
	v_mfma_f32_16x16x32_bf16 v[38:41], v[156:159], v[224:227], v[38:41]
	v_mfma_f32_16x16x32_bf16 v[34:37], v[160:163], v[200:203], v[34:37]
	v_mfma_f32_16x16x32_bf16 v[34:37], v[164:167], v[224:227], v[34:37]
	v_mfma_f32_16x16x32_bf16 v[22:25], v[152:155], v[228:231], v[22:25]
	v_mfma_f32_16x16x32_bf16 v[22:25], v[156:159], v[232:235], v[22:25]
	v_mfma_f32_16x16x32_bf16 v[18:21], v[160:163], v[228:231], v[18:21]
	v_mfma_f32_16x16x32_bf16 v[18:21], v[164:167], v[232:235], v[18:21]
	v_mfma_f32_16x16x32_bf16 v[6:9], v[152:155], v[236:239], v[6:9]
	v_mfma_f32_16x16x32_bf16 v[6:9], v[156:159], v[240:243], v[6:9]
	v_mfma_f32_16x16x32_bf16 v[2:5], v[160:163], v[236:239], v[2:5]
	v_mfma_f32_16x16x32_bf16 v[2:5], v[164:167], v[240:243], v[2:5]
	s_setprio 0
	s_barrier
	v_lshl_add_u64 v[132:133], v[132:133], 0, s[86:87]
	v_lshl_add_u64 v[134:135], v[134:135], 0, s[86:87]
	s_mov_b32 s29, s81
	s_cbranch_scc0 .LBB0_270
	s_and_b64 vcc, exec, s[10:11]
	s_cbranch_vccz .LBB0_273
	s_barrier

; #define PG8_STAGE(bufoff, gbase, voff) do { _Pragma("unroll") for (int _i = 0; _i < 2; ++_i) \
;         __builtin_amdgcn_global_load_lds((const unsigned*)((const char*)(gbase) + (voff)[_i]), (PG8_LAS unsigned*)(lds + (bufoff) + ldsw + _i * 8192), 16, 0, AUX_A); } while (0)
; #define PG8_STAGEB(bufoff, gbase, voff) do { _Pragma("unroll") for (int _i = 0; _i < 2; ++_i) \
;         __builtin_amdgcn_global_load_lds((const unsigned*)((const char*)(gbase) + (voff)[_i]), (PG8_LAS unsigned*)(lds + (bufoff) + ldsw + _i * 8192), 16, 0, AUX_B); } while (0)
; #define PG8_LDA(dst, b, h) do { _Pragma("unroll") for (int m = 0; m < 4; ++m) _Pragma("unroll") for (int k = 0; k < 2; ++k) dst[m][k] = *(const PG8_LAS bf16x8*)(lds + PG8_SA(b, h) + aoff + m * 2048 + k * 1024); } while (0)
; #define PG8_LDB(dst, b, h) do { _Pragma("unroll") for (int n = 0; n < 2; ++n) _Pragma("unroll") for (int k = 0; k < 2; ++k) dst[n][k] = *(const PG8_LAS bf16x8*)(lds + PG8_SB(b, h) + boff + n * 2048 + k * 1024); } while (0)
; #define PG8_WAIT_V(n) asm volatile("s_waitcnt vmcnt(" #n ")" ::: "memory")
; #define PG8_WAIT_L(n) asm volatile("s_waitcnt lgkmcnt(" #n ")" ::: "memory")
; template <class Epi, class Sched, bool ALIGN_EPI = false, bool SP2 = false>
; __device__ __forceinline__ void gemm_phase(PG8_LAS unsigned char* lds, const Gemm g, const Sched& S, const Epi& E) {
;     ...
;         const char* nAr = has_next ? nA + (size_t)nxt.krot * kstep : PG8_KP(cA, 0, rot, nt); const char* nBr = has_next ? nB + (size_t)nxt.krot * kstep : PG8_KP(cB, 0, rot, nt);
;         for (int t = 0; t < nt; t += 2) {
;             const bool last = (t == nt - 2);
;             const char* a1 = PG8_KP(cA, t + 1, rot, nt);
;             const char* a2 = last ? nAr : PG8_KP(cA, t + 2, rot, nt); const char* b2 = last ? nBr : PG8_KP(cB, t + 2, rot, nt);
;             const char* a3 = a2 + kstep; const char* b3 = b2 + kstep;
;             if (last && has_next) S.a_ready(nxt);
;             if constexpr (SP2) {
;             PG8_LDB(B0, 0, 0); PG8_LDB(B1, 0, 1); PG8_SCHED; PG8_LDA(At, 0, 0); PG8_STAGE(PG8_SA(1, 1), a1 + hstep, voffA);
;             PG8_WAIT_V(8); PG8_WAIT_L(0); PG8_BAR; PG8_MMA(0, 0, At, B0); PG8_MMA(0, 1, At, B1); PG8_BAR; PG8_SCHED;
;             PG8_LDA(At, 0, 1); PG8_STAGEB(PG8_SB(0, 0), b2, voffB); PG8_STAGEB(PG8_SB(0, 1), b2 + hstep, voffB); PG8_STAGE(PG8_SA(0, 0), a2, voffA);
.LBB0_936:
	s_add_i32 s81, s29, 2
	s_cmp_lt_u32 s29, 14
	s_cselect_b32 s0, 0, -16
	s_add_i32 s0, s81, s0
	s_ashr_i32 s1, s0, 31
	s_lshl_b64 s[0:1], s[0:1], 7
	s_add_u32 s2, s64, s0
	s_addc_u32 s46, s65, s1
	s_add_u32 s0, s26, s0
	s_addc_u32 s1, s27, s1
	s_cmp_eq_u32 s29, 14
	s_cselect_b32 s57, s15, s46
	s_cselect_b32 s56, s17, s2
	s_cselect_b32 s59, s43, s1
	s_cselect_b32 s58, s78, s0
	s_add_i32 s2, 0, 0x10000
	s_add_i32 s83, s2, s33
	s_add_i32 s46, 0, 0x14000
	s_add_i32 m0, s25, 0xc000
	s_add_i32 s82, s25, 0xe000
	s_add_i32 s84, s83, 0x2000
	s_add_u32 s60, s58, 0x40000
	s_addc_u32 s61, s59, 0
	s_add_i32 s88, s46, s33
	v_add_u32_e32 v160, s2, v99
	v_add_u32_e32 v166, s46, v99
	s_add_i32 s89, s88, 0x2000
	s_add_i32 s90, 0, 0x18000
	s_add_i32 s91, 0, 0x1c000
	ds_read_b128 v[22:25], v160
	ds_read_b128 v[34:37], v160 offset:1024
	ds_read_b128 v[38:41], v160 offset:2048
	ds_read_b128 v[160:163], v160 offset:3072
	ds_read_b128 v[180:183], v166
	ds_read_b128 v[184:187], v166 offset:1024
	ds_read_b128 v[188:191], v166 offset:2048
	ds_read_b128 v[192:195], v166 offset:3072
	s_add_u32 s54, s56, 0x40000
	s_addc_u32 s55, s57, 0
	s_add_i32 s1, s90, s33
	s_add_i32 s0, s1, 0x2000
	s_add_u32 s52, s58, 0x40080
	s_addc_u32 s53, s59, 0
	s_add_i32 s47, s91, s33
	s_add_i32 s46, s47, 0x2000
	s_cmp_gt_u32 s29, 13
	ds_read_b128 v[196:199], v165
	ds_read_b128 v[200:203], v165 offset:1024
	ds_read_b128 v[222:225], v165 offset:2048
	ds_read_b128 v[226:229], v165 offset:3072
	ds_read_b128 v[230:233], v165 offset:4096
	ds_read_b128 v[234:237], v165 offset:5120
	ds_read_b128 v[238:241], v165 offset:6144
	ds_read_b128 v[242:245], v165 offset:7168
	global_load_lds_dwordx4 v[16:17], off
	s_mov_b32 m0, s82
	s_nop 0
	global_load_lds_dwordx4 v[14:15], off
	s_waitcnt vmcnt(8)
	s_waitcnt lgkmcnt(0)
	s_barrier
	s_setprio 1
	s_waitcnt lgkmcnt(0)
	v_mfma_f32_16x16x32_bf16 v[144:147], v[22:25], v[196:199], v[144:147]
	v_mfma_f32_16x16x32_bf16 v[144:147], v[34:37], v[200:203], v[144:147]
	v_mfma_f32_16x16x32_bf16 v[140:143], v[38:41], v[196:199], v[140:143]
	v_mfma_f32_16x16x32_bf16 v[140:143], v[160:163], v[200:203], v[140:143]
	v_mfma_f32_16x16x32_bf16 v[128:131], v[22:25], v[222:225], v[128:131]
	v_mfma_f32_16x16x32_bf16 v[128:131], v[34:37], v[226:229], v[128:131]
	v_mfma_f32_16x16x32_bf16 v[124:127], v[38:41], v[222:225], v[124:127]
	v_mfma_f32_16x16x32_bf16 v[124:127], v[160:163], v[226:229], v[124:127]
	v_mfma_f32_16x16x32_bf16 v[112:115], v[22:25], v[230:233], v[112:115]
	v_mfma_f32_16x16x32_bf16 v[112:115], v[34:37], v[234:237], v[112:115]
	v_mfma_f32_16x16x32_bf16 v[108:111], v[38:41], v[230:233], v[108:111]
	v_mfma_f32_16x16x32_bf16 v[108:111], v[160:163], v[234:237], v[108:111]
	v_mfma_f32_16x16x32_bf16 v[94:97], v[22:25], v[238:241], v[94:97]
	v_mfma_f32_16x16x32_bf16 v[94:97], v[34:37], v[242:245], v[94:97]
	v_mfma_f32_16x16x32_bf16 v[90:93], v[38:41], v[238:241], v[90:93]
	v_mfma_f32_16x16x32_bf16 v[90:93], v[160:163], v[242:245], v[90:93]
	s_setprio 0
	s_setprio 1
	v_mfma_f32_16x16x32_bf16 v[136:139], v[180:183], v[196:199], v[136:139]
	v_mfma_f32_16x16x32_bf16 v[136:139], v[184:187], v[200:203], v[136:139]
	v_mfma_f32_16x16x32_bf16 v[132:135], v[188:191], v[196:199], v[132:135]
	v_mfma_f32_16x16x32_bf16 v[132:135], v[192:195], v[200:203], v[132:135]
	v_mfma_f32_16x16x32_bf16 v[120:123], v[180:183], v[222:225], v[120:123]
	v_mfma_f32_16x16x32_bf16 v[120:123], v[184:187], v[226:229], v[120:123]
	v_mfma_f32_16x16x32_bf16 v[116:119], v[188:191], v[222:225], v[116:119]
	v_mfma_f32_16x16x32_bf16 v[116:119], v[192:195], v[226:229], v[116:119]
	v_mfma_f32_16x16x32_bf16 v[104:107], v[180:183], v[230:233], v[104:107]
	v_mfma_f32_16x16x32_bf16 v[104:107], v[184:187], v[234:237], v[104:107]
	v_mfma_f32_16x16x32_bf16 v[100:103], v[188:191], v[230:233], v[100:103]
	v_mfma_f32_16x16x32_bf16 v[100:103], v[192:195], v[234:237], v[100:103]
	v_mfma_f32_16x16x32_bf16 v[86:89], v[180:183], v[238:241], v[86:89]
	v_mfma_f32_16x16x32_bf16 v[86:89], v[184:187], v[242:245], v[86:89]
	v_mfma_f32_16x16x32_bf16 v[82:85], v[188:191], v[238:241], v[82:85]
	v_mfma_f32_16x16x32_bf16 v[82:85], v[192:195], v[242:245], v[82:85]
	s_setprio 0
	s_barrier
	s_mov_b32 m0, s83
	v_lshl_add_u64 v[166:167], s[58:59], 0, v[150:151]
	ds_read_b128 v[196:199], v165 offset:16384
	ds_read_b128 v[200:203], v165 offset:17408
	ds_read_b128 v[222:225], v165 offset:18432
	ds_read_b128 v[226:229], v165 offset:19456
	ds_read_b128 v[230:233], v165 offset:20480
	ds_read_b128 v[234:237], v165 offset:21504
	ds_read_b128 v[238:241], v165 offset:22528
	ds_read_b128 v[242:245], v165 offset:23552
	global_load_lds_dwordx4 v[166:167], off
	v_lshl_add_u64 v[168:169], s[58:59], 0, v[154:155]
	s_mov_b32 m0, s84
	v_lshl_add_u64 v[172:173], s[60:61], 0, v[150:151]
	global_load_lds_dwordx4 v[168:169], off
	s_mov_b32 m0, s88
	v_lshl_add_u64 v[212:213], s[56:57], 0, v[152:153]
	global_load_lds_dwordx4 v[172:173], off
	v_lshl_add_u64 v[172:173], s[60:61], 0, v[154:155]
	s_mov_b32 m0, s89
	s_nop 0
	global_load_lds_dwordx4 v[172:173], off
	v_lshl_add_u64 v[172:173], s[56:57], 0, v[148:149]
	s_mov_b32 m0, s25
	s_nop 0
	global_load_lds_dwordx4 v[172:173], off
	s_mov_b32 m0, s62
	s_nop 0
	global_load_lds_dwordx4 v[212:213], off
	s_waitcnt vmcnt(8)
	s_waitcnt lgkmcnt(0)
	s_barrier
; #define PG8_STAGE(bufoff, gbase, voff) do { _Pragma("unroll") for (int _i = 0; _i < 2; ++_i) \
;         __builtin_amdgcn_global_load_lds((const unsigned*)((const char*)(gbase) + (voff)[_i]), (PG8_LAS unsigned*)(lds + (bufoff) + ldsw + _i * 8192), 16, 0, AUX_A); } while (0)
; #define PG8_LDA(dst, b, h) do { _Pragma("unroll") for (int m = 0; m < 4; ++m) _Pragma("unroll") for (int k = 0; k < 2; ++k) dst[m][k] = *(const PG8_LAS bf16x8*)(lds + PG8_SA(b, h) + aoff + m * 2048 + k * 1024); } while (0)
; #define PG8_LDB(dst, b, h) do { _Pragma("unroll") for (int n = 0; n < 2; ++n) _Pragma("unroll") for (int k = 0; k < 2; ++k) dst[n][k] = *(const PG8_LAS bf16x8*)(lds + PG8_SB(b, h) + boff + n * 2048 + k * 1024); } while (0)
; #define PG8_MMA(ai, bj, At, Bt) do { __builtin_amdgcn_s_setprio(1); _Pragma("unroll") for (int m = 0; m < 4; ++m) _Pragma("unroll") for (int n = 0; n < 2; ++n) _Pragma("unroll") for (int k = 0; k < 2; ++k) \
;         acc[ai][bj][m][n] = __builtin_amdgcn_mfma_f32_16x16x32_bf16(Bt[n][k], At[m][k], acc[ai][bj][m][n], 0, 0, 0); __builtin_amdgcn_s_setprio(0); } while (0)
; #define PG8_WAIT_V(n) asm volatile("s_waitcnt vmcnt(" #n ")" ::: "memory")
; #define PG8_WAIT_L(n) asm volatile("s_waitcnt lgkmcnt(" #n ")" ::: "memory")
; #define PG8_BAR __builtin_amdgcn_s_barrier()
; #define PG8_SCHED __builtin_amdgcn_sched_barrier(0)
; template <class Epi, class Sched, bool ALIGN_EPI = false, bool SP2 = false>
; __device__ __forceinline__ void gemm_phase(PG8_LAS unsigned char* lds, const Gemm g, const Sched& S, const Epi& E) {
;     ...
;             PG8_WAIT_V(8); PG8_WAIT_L(0); PG8_BAR; PG8_MMA(1, 0, At, B0); PG8_MMA(1, 1, At, B1); PG8_BAR; PG8_SCHED;
;             PG8_LDB(B0, 1, 0); PG8_LDB(B1, 1, 1); PG8_SCHED; PG8_LDA(At, 1, 0); PG8_STAGE(PG8_SA(0, 1), a2 + hstep, voffA);
;             PG8_WAIT_V(8); PG8_WAIT_L(0); PG8_BAR; PG8_MMA(0, 0, At, B0); PG8_MMA(0, 1, At, B1); PG8_BAR; PG8_SCHED;
	s_setprio 1
	s_waitcnt lgkmcnt(0)
	v_mfma_f32_16x16x32_bf16 v[78:81], v[22:25], v[196:199], v[78:81]
	v_mfma_f32_16x16x32_bf16 v[78:81], v[34:37], v[200:203], v[78:81]
	v_mfma_f32_16x16x32_bf16 v[74:77], v[38:41], v[196:199], v[74:77]
	v_mfma_f32_16x16x32_bf16 v[74:77], v[160:163], v[200:203], v[74:77]
	v_mfma_f32_16x16x32_bf16 v[62:65], v[22:25], v[222:225], v[62:65]
	v_mfma_f32_16x16x32_bf16 v[62:65], v[34:37], v[226:229], v[62:65]
	v_mfma_f32_16x16x32_bf16 v[58:61], v[38:41], v[222:225], v[58:61]
	v_mfma_f32_16x16x32_bf16 v[58:61], v[160:163], v[226:229], v[58:61]
	v_mfma_f32_16x16x32_bf16 v[46:49], v[22:25], v[230:233], v[46:49]
	v_mfma_f32_16x16x32_bf16 v[46:49], v[34:37], v[234:237], v[46:49]
	v_mfma_f32_16x16x32_bf16 v[42:45], v[38:41], v[230:233], v[42:45]
	v_mfma_f32_16x16x32_bf16 v[42:45], v[160:163], v[234:237], v[42:45]
	v_mfma_f32_16x16x32_bf16 v[18:21], v[22:25], v[238:241], v[18:21]
	v_mfma_f32_16x16x32_bf16 v[18:21], v[34:37], v[242:245], v[18:21]
	v_mfma_f32_16x16x32_bf16 v[10:13], v[38:41], v[238:241], v[10:13]
	v_mfma_f32_16x16x32_bf16 v[10:13], v[160:163], v[242:245], v[10:13]
	s_setprio 0
	s_setprio 1
	v_mfma_f32_16x16x32_bf16 v[50:53], v[188:191], v[222:225], v[50:53]
	v_mfma_f32_16x16x32_bf16 v[30:33], v[180:183], v[230:233], v[30:33]
	v_mfma_f32_16x16x32_bf16 v[26:29], v[188:191], v[230:233], v[26:29]
	v_mfma_f32_16x16x32_bf16 v[6:9], v[180:183], v[238:241], v[6:9]
	v_mfma_f32_16x16x32_bf16 v[2:5], v[188:191], v[238:241], v[2:5]
	v_mfma_f32_16x16x32_bf16 v[22:25], v[180:183], v[196:199], v[70:73]
	v_mfma_f32_16x16x32_bf16 v[34:37], v[188:191], v[196:199], v[66:69]
	v_mfma_f32_16x16x32_bf16 v[38:41], v[180:183], v[222:225], v[54:57]
	v_mfma_f32_16x16x32_bf16 v[50:53], v[192:195], v[226:229], v[50:53]
	v_mfma_f32_16x16x32_bf16 v[30:33], v[184:187], v[234:237], v[30:33]
	v_mfma_f32_16x16x32_bf16 v[26:29], v[192:195], v[234:237], v[26:29]
	v_mfma_f32_16x16x32_bf16 v[6:9], v[184:187], v[242:245], v[6:9]
	v_mfma_f32_16x16x32_bf16 v[2:5], v[192:195], v[242:245], v[2:5]
	v_mfma_f32_16x16x32_bf16 v[22:25], v[184:187], v[200:203], v[22:25]
	v_mfma_f32_16x16x32_bf16 v[34:37], v[192:195], v[200:203], v[34:37]
	v_mfma_f32_16x16x32_bf16 v[38:41], v[184:187], v[226:229], v[38:41]
	s_setprio 0
	s_barrier
	v_add_u32_e32 v160, s90, v99
	v_add_u32_e32 v192, s91, v99
	ds_read_b128 v[54:57], v160
	ds_read_b128 v[66:69], v160 offset:1024
	ds_read_b128 v[70:73], v160 offset:2048
	ds_read_b128 v[160:163], v160 offset:3072
	ds_read_b128 v[180:183], v192
	ds_read_b128 v[184:187], v192 offset:1024
	ds_read_b128 v[188:191], v192 offset:2048
	ds_read_b128 v[192:195], v192 offset:3072
	s_mov_b32 m0, s63
	v_lshl_add_u64 v[246:247], s[54:55], 0, v[148:149]
	ds_read_b128 v[196:199], v165 offset:32768
	ds_read_b128 v[200:203], v165 offset:33792
	ds_read_b128 v[222:225], v165 offset:34816
	ds_read_b128 v[226:229], v165 offset:35840
	ds_read_b128 v[230:233], v165 offset:36864
	ds_read_b128 v[234:237], v165 offset:37888
	ds_read_b128 v[238:241], v165 offset:38912
	ds_read_b128 v[242:245], v165 offset:39936
	global_load_lds_dwordx4 v[246:247], off
	v_lshl_add_u64 v[246:247], s[54:55], 0, v[152:153]
	s_mov_b32 m0, s69
	s_nop 0
	global_load_lds_dwordx4 v[246:247], off
	s_waitcnt vmcnt(8)
	s_waitcnt lgkmcnt(0)
	s_barrier
	s_setprio 1
	s_waitcnt lgkmcnt(0)
	v_mfma_f32_16x16x32_bf16 v[144:147], v[54:57], v[196:199], v[144:147]
	v_mfma_f32_16x16x32_bf16 v[144:147], v[66:69], v[200:203], v[144:147]
	v_mfma_f32_16x16x32_bf16 v[140:143], v[70:73], v[196:199], v[140:143]
	v_mfma_f32_16x16x32_bf16 v[140:143], v[160:163], v[200:203], v[140:143]
	v_mfma_f32_16x16x32_bf16 v[128:131], v[54:57], v[222:225], v[128:131]
	v_mfma_f32_16x16x32_bf16 v[128:131], v[66:69], v[226:229], v[128:131]
	v_mfma_f32_16x16x32_bf16 v[124:127], v[70:73], v[222:225], v[124:127]
	v_mfma_f32_16x16x32_bf16 v[124:127], v[160:163], v[226:229], v[124:127]
	v_mfma_f32_16x16x32_bf16 v[112:115], v[54:57], v[230:233], v[112:115]
	v_mfma_f32_16x16x32_bf16 v[112:115], v[66:69], v[234:237], v[112:115]
	v_mfma_f32_16x16x32_bf16 v[108:111], v[70:73], v[230:233], v[108:111]
	v_mfma_f32_16x16x32_bf16 v[108:111], v[160:163], v[234:237], v[108:111]
	v_mfma_f32_16x16x32_bf16 v[94:97], v[54:57], v[238:241], v[94:97]
	v_mfma_f32_16x16x32_bf16 v[94:97], v[66:69], v[242:245], v[94:97]
	v_mfma_f32_16x16x32_bf16 v[90:93], v[70:73], v[238:241], v[90:93]
	v_mfma_f32_16x16x32_bf16 v[90:93], v[160:163], v[242:245], v[90:93]
	s_setprio 0
	s_setprio 1
	v_mfma_f32_16x16x32_bf16 v[136:139], v[180:183], v[196:199], v[136:139]
	v_mfma_f32_16x16x32_bf16 v[136:139], v[184:187], v[200:203], v[136:139]
	v_mfma_f32_16x16x32_bf16 v[132:135], v[188:191], v[196:199], v[132:135]
	v_mfma_f32_16x16x32_bf16 v[132:135], v[192:195], v[200:203], v[132:135]
	v_mfma_f32_16x16x32_bf16 v[120:123], v[180:183], v[222:225], v[120:123]
	v_mfma_f32_16x16x32_bf16 v[120:123], v[184:187], v[226:229], v[120:123]
	v_mfma_f32_16x16x32_bf16 v[116:119], v[188:191], v[222:225], v[116:119]
	v_mfma_f32_16x16x32_bf16 v[116:119], v[192:195], v[226:229], v[116:119]
	v_mfma_f32_16x16x32_bf16 v[104:107], v[180:183], v[230:233], v[104:107]
	v_mfma_f32_16x16x32_bf16 v[104:107], v[184:187], v[234:237], v[104:107]
	v_mfma_f32_16x16x32_bf16 v[100:103], v[188:191], v[230:233], v[100:103]
	v_mfma_f32_16x16x32_bf16 v[100:103], v[192:195], v[234:237], v[100:103]
	v_mfma_f32_16x16x32_bf16 v[86:89], v[180:183], v[238:241], v[86:89]
	v_mfma_f32_16x16x32_bf16 v[86:89], v[184:187], v[242:245], v[86:89]
	v_mfma_f32_16x16x32_bf16 v[82:85], v[188:191], v[238:241], v[82:85]
	v_mfma_f32_16x16x32_bf16 v[82:85], v[192:195], v[242:245], v[82:85]
	s_setprio 0
	s_barrier
; #define PG8_STAGE(bufoff, gbase, voff) do { _Pragma("unroll") for (int _i = 0; _i < 2; ++_i) \
;         __builtin_amdgcn_global_load_lds((const unsigned*)((const char*)(gbase) + (voff)[_i]), (PG8_LAS unsigned*)(lds + (bufoff) + ldsw + _i * 8192), 16, 0, AUX_A); } while (0)
; #define PG8_STAGEB(bufoff, gbase, voff) do { _Pragma("unroll") for (int _i = 0; _i < 2; ++_i) \
;         __builtin_amdgcn_global_load_lds((const unsigned*)((const char*)(gbase) + (voff)[_i]), (PG8_LAS unsigned*)(lds + (bufoff) + ldsw + _i * 8192), 16, 0, AUX_B); } while (0)
; template <class Epi, class Sched, bool ALIGN_EPI = false, bool SP2 = false>
; __device__ __forceinline__ void gemm_phase(PG8_LAS unsigned char* lds, const Gemm g, const Sched& S, const Epi& E) {
;     ...
;             PG8_LDA(At, 1, 1); PG8_STAGEB(PG8_SB(1, 0), b3, voffB); PG8_STAGEB(PG8_SB(1, 1), b3 + hstep, voffB); PG8_STAGE(PG8_SA(1, 0), a3, voffA);
;             PG8_WAIT_V(8); PG8_WAIT_L(0); PG8_BAR; PG8_MMA(1, 0, At, B0); PG8_MMA(1, 1, At, B1); PG8_BAR; PG8_SCHED;
;             } else {
;             PG8_LDB(B0, 0, 0); PG8_SCHED; PG8_LDA(At, 0, 0); PG8_STAGE(PG8_SA(1, 1), a1 + hstep, voffA);
;             PG8_WAIT_L(8); PG8_BAR; PG8_WAIT_L(0); PG8_MMA(0, 0, At, B0); PG8_BAR; PG8_SCHED;
;             PG8_LDB(B1, 0, 1); PG8_STAGEB(PG8_SB(0, 0), b2, voffB);
;             PG8_BAR; PG8_WAIT_L(0); PG8_MMA(0, 1, At, B1); PG8_BAR;
;             PG8_LDA(At, 0, 1); PG8_STAGE(PG8_SA(0, 0), a2, voffA);
;             PG8_BAR; PG8_WAIT_L(0); PG8_MMA(1, 0, At, B0); PG8_BAR; PG8_SCHED;
;             PG8_STAGEB(PG8_SB(0, 1), b2 + hstep, voffB);
;             PG8_WAIT_V(6); PG8_BAR; PG8_MMA(1, 1, At, B1); PG8_BAR;
;             PG8_LDB(B0, 1, 0); PG8_SCHED; PG8_LDA(At, 1, 0); PG8_STAGE(PG8_SA(0, 1), a2 + hstep, voffA);
;             PG8_WAIT_L(8); PG8_BAR; PG8_WAIT_L(0); PG8_MMA(0, 0, At, B0); PG8_BAR; PG8_SCHED;
;             PG8_LDB(B1, 1, 1); PG8_STAGEB(PG8_SB(1, 0), b3, voffB);
;             PG8_BAR; PG8_WAIT_L(0); PG8_MMA(0, 1, At, B1); PG8_BAR;
;             PG8_LDA(At, 1, 1); PG8_STAGE(PG8_SA(1, 0), a3, voffA);
;             PG8_BAR; PG8_WAIT_L(0); PG8_MMA(1, 0, At, B0); PG8_BAR; PG8_SCHED;
;             PG8_STAGEB(PG8_SB(1, 1), b3 + hstep, voffB);
;             PG8_WAIT_V(6); PG8_BAR; PG8_MMA(1, 1, At, B1); PG8_BAR;
;             }
;         }
;         if constexpr (ALIGN_EPI) { if (wr == 0) PG8_BAR; }
	s_mov_b32 m0, s1
	v_lshl_add_u64 v[166:167], v[166:167], 0, s[76:77]
	ds_read_b128 v[196:199], v165 offset:49152
	ds_read_b128 v[200:203], v165 offset:50176
	ds_read_b128 v[222:225], v165 offset:51200
	ds_read_b128 v[226:229], v165 offset:52224
	ds_read_b128 v[230:233], v165 offset:53248
	ds_read_b128 v[234:237], v165 offset:54272
	ds_read_b128 v[238:241], v165 offset:55296
	ds_read_b128 v[242:245], v165 offset:56320
	global_load_lds_dwordx4 v[166:167], off
	v_lshl_add_u64 v[166:167], v[168:169], 0, s[76:77]
	s_mov_b32 m0, s0
	s_nop 0
	global_load_lds_dwordx4 v[166:167], off
	v_lshl_add_u64 v[166:167], s[52:53], 0, v[150:151]
	s_mov_b32 m0, s47
	s_nop 0
	global_load_lds_dwordx4 v[166:167], off
	v_lshl_add_u64 v[166:167], s[52:53], 0, v[154:155]
	s_mov_b32 m0, s46
	s_nop 0
	global_load_lds_dwordx4 v[166:167], off
	v_lshl_add_u64 v[166:167], v[172:173], 0, s[76:77]
	s_mov_b32 m0, s70
	s_nop 0
	global_load_lds_dwordx4 v[166:167], off
	v_lshl_add_u64 v[166:167], v[212:213], 0, s[76:77]
	s_mov_b32 m0, s71
	s_nop 0
	global_load_lds_dwordx4 v[166:167], off
	s_waitcnt vmcnt(8)
	s_waitcnt lgkmcnt(0)
	s_barrier
	s_setprio 1
	s_waitcnt lgkmcnt(0)
	v_mfma_f32_16x16x32_bf16 v[78:81], v[54:57], v[196:199], v[78:81]
	v_mfma_f32_16x16x32_bf16 v[78:81], v[66:69], v[200:203], v[78:81]
	v_mfma_f32_16x16x32_bf16 v[74:77], v[70:73], v[196:199], v[74:77]
	v_mfma_f32_16x16x32_bf16 v[74:77], v[160:163], v[200:203], v[74:77]
	v_mfma_f32_16x16x32_bf16 v[62:65], v[54:57], v[222:225], v[62:65]
	v_mfma_f32_16x16x32_bf16 v[62:65], v[66:69], v[226:229], v[62:65]
	v_mfma_f32_16x16x32_bf16 v[58:61], v[70:73], v[222:225], v[58:61]
	v_mfma_f32_16x16x32_bf16 v[58:61], v[160:163], v[226:229], v[58:61]
	v_mfma_f32_16x16x32_bf16 v[46:49], v[54:57], v[230:233], v[46:49]
	v_mfma_f32_16x16x32_bf16 v[46:49], v[66:69], v[234:237], v[46:49]
	v_mfma_f32_16x16x32_bf16 v[42:45], v[70:73], v[230:233], v[42:45]
	v_mfma_f32_16x16x32_bf16 v[42:45], v[160:163], v[234:237], v[42:45]
	v_mfma_f32_16x16x32_bf16 v[18:21], v[54:57], v[238:241], v[18:21]
	v_mfma_f32_16x16x32_bf16 v[18:21], v[66:69], v[242:245], v[18:21]
	v_mfma_f32_16x16x32_bf16 v[10:13], v[70:73], v[238:241], v[10:13]
	v_mfma_f32_16x16x32_bf16 v[10:13], v[160:163], v[242:245], v[10:13]
	s_setprio 0
	s_setprio 1
	v_mfma_f32_16x16x32_bf16 v[22:25], v[180:183], v[196:199], v[22:25]
	v_mfma_f32_16x16x32_bf16 v[70:73], v[184:187], v[200:203], v[22:25]
	v_mfma_f32_16x16x32_bf16 v[22:25], v[188:191], v[196:199], v[34:37]
	v_mfma_f32_16x16x32_bf16 v[66:69], v[192:195], v[200:203], v[22:25]
	v_mfma_f32_16x16x32_bf16 v[22:25], v[180:183], v[222:225], v[38:41]
	v_mfma_f32_16x16x32_bf16 v[54:57], v[184:187], v[226:229], v[22:25]
	v_mfma_f32_16x16x32_bf16 v[22:25], v[188:191], v[222:225], v[50:53]
	v_mfma_f32_16x16x32_bf16 v[50:53], v[192:195], v[226:229], v[22:25]
	v_mfma_f32_16x16x32_bf16 v[22:25], v[180:183], v[230:233], v[30:33]
	v_mfma_f32_16x16x32_bf16 v[30:33], v[184:187], v[234:237], v[22:25]
	v_mfma_f32_16x16x32_bf16 v[22:25], v[188:191], v[230:233], v[26:29]
	v_mfma_f32_16x16x32_bf16 v[6:9], v[180:183], v[238:241], v[6:9]
	v_mfma_f32_16x16x32_bf16 v[2:5], v[188:191], v[238:241], v[2:5]
	v_mfma_f32_16x16x32_bf16 v[26:29], v[192:195], v[234:237], v[22:25]
	v_mfma_f32_16x16x32_bf16 v[6:9], v[184:187], v[242:245], v[6:9]
	v_mfma_f32_16x16x32_bf16 v[2:5], v[192:195], v[242:245], v[2:5]
	s_setprio 0
	s_barrier
	v_lshl_add_u64 v[14:15], v[14:15], 0, s[86:87]
	v_lshl_add_u64 v[16:17], v[16:17], 0, s[86:87]
	s_mov_b32 s29, s81
	s_cbranch_scc0 .LBB0_936
	s_and_b64 vcc, exec, s[12:13]
	s_cbranch_vccz .LBB0_939
	s_barrier

; #define PG8_STAGE(bufoff, gbase, voff) do { _Pragma("unroll") for (int _i = 0; _i < 2; ++_i) \
;         __builtin_amdgcn_global_load_lds((const unsigned*)((const char*)(gbase) + (voff)[_i]), (PG8_LAS unsigned*)(lds + (bufoff) + ldsw + _i * 8192), 16, 0, AUX_A); } while (0)
; #define PG8_STAGEB(bufoff, gbase, voff) do { _Pragma("unroll") for (int _i = 0; _i < 2; ++_i) \
;         __builtin_amdgcn_global_load_lds((const unsigned*)((const char*)(gbase) + (voff)[_i]), (PG8_LAS unsigned*)(lds + (bufoff) + ldsw + _i * 8192), 16, 0, AUX_B); } while (0)
; #define PG8_LDA(dst, b, h) do { _Pragma("unroll") for (int m = 0; m < 4; ++m) _Pragma("unroll") for (int k = 0; k < 2; ++k) dst[m][k] = *(const PG8_LAS bf16x8*)(lds + PG8_SA(b, h) + aoff + m * 2048 + k * 1024); } while (0)
; #define PG8_LDB(dst, b, h) do { _Pragma("unroll") for (int n = 0; n < 2; ++n) _Pragma("unroll") for (int k = 0; k < 2; ++k) dst[n][k] = *(const PG8_LAS bf16x8*)(lds + PG8_SB(b, h) + boff + n * 2048 + k * 1024); } while (0)
; #define PG8_WAIT_V(n) asm volatile("s_waitcnt vmcnt(" #n ")" ::: "memory")
; #define PG8_WAIT_L(n) asm volatile("s_waitcnt lgkmcnt(" #n ")" ::: "memory")
; template <class Epi, class Sched, bool ALIGN_EPI = false, bool SP2 = false>
; __device__ __forceinline__ void gemm_phase(PG8_LAS unsigned char* lds, const Gemm g, const Sched& S, const Epi& E) {
;     ...
;         const char* nAr = has_next ? nA + (size_t)nxt.krot * kstep : PG8_KP(cA, 0, rot, nt); const char* nBr = has_next ? nB + (size_t)nxt.krot * kstep : PG8_KP(cB, 0, rot, nt);
;         for (int t = 0; t < nt; t += 2) {
;             const bool last = (t == nt - 2);
;             const char* a1 = PG8_KP(cA, t + 1, rot, nt);
;             const char* a2 = last ? nAr : PG8_KP(cA, t + 2, rot, nt); const char* b2 = last ? nBr : PG8_KP(cB, t + 2, rot, nt);
;             const char* a3 = a2 + kstep; const char* b3 = b2 + kstep;
;             if (last && has_next) S.a_ready(nxt);
;             if constexpr (SP2) {
;             PG8_LDB(B0, 0, 0); PG8_LDB(B1, 0, 1); PG8_SCHED; PG8_LDA(At, 0, 0); PG8_STAGE(PG8_SA(1, 1), a1 + hstep, voffA);
;             PG8_WAIT_V(8); PG8_WAIT_L(0); PG8_BAR; PG8_MMA(0, 0, At, B0); PG8_MMA(0, 1, At, B1); PG8_BAR; PG8_SCHED;
;             PG8_LDA(At, 0, 1); PG8_STAGEB(PG8_SB(0, 0), b2, voffB); PG8_STAGEB(PG8_SB(0, 1), b2 + hstep, voffB); PG8_STAGE(PG8_SA(0, 0), a2, voffA);
.LBB0_1067:
	s_add_i32 s81, s29, 2
	s_cmp_lt_u32 s29, 14
	s_cselect_b32 s0, 0, -16
	s_add_i32 s0, s81, s0
	s_ashr_i32 s1, s0, 31
	s_lshl_b64 s[0:1], s[0:1], 7
	s_add_u32 s2, s52, s0
	s_addc_u32 s46, s53, s1
	s_add_u32 s0, s42, s0
	s_addc_u32 s1, s43, s1
	s_cmp_eq_u32 s29, 14
	s_cselect_b32 s59, s15, s46
	s_cselect_b32 s58, s17, s2
	s_cselect_b32 s61, s92, s1
	s_cselect_b32 s60, s93, s0
	s_add_i32 s2, 0, 0x10000
	s_add_i32 s94, s2, s70
	s_add_i32 s46, 0, 0x14000
	s_add_i32 m0, s71, 0xc000
	s_add_i32 s84, s71, 0xe000
	s_add_i32 s95, s94, 0x2000
	s_add_u32 s62, s60, 0x40000
	v_add_u32_e32 v148, s2, v99
	s_addc_u32 s63, s61, 0
	s_add_i32 s96, s46, s70
	ds_read_b128 v[152:155], v148
	ds_read_b128 v[156:159], v148 offset:1024
	ds_read_b128 v[160:163], v148 offset:2048
	ds_read_b128 v[164:167], v148 offset:3072
	v_add_u32_e32 v148, s46, v99
	s_add_i32 s97, s96, 0x2000
	s_add_i32 vcc_lo, 0, 0x18000
	s_add_i32 vcc_hi, 0, 0x1c000
	ds_read_b128 v[180:183], v148
	ds_read_b128 v[184:187], v148 offset:1024
	ds_read_b128 v[188:191], v148 offset:2048
	ds_read_b128 v[192:195], v148 offset:3072
	s_add_u32 s56, s58, 0x40000
	s_addc_u32 s57, s59, 0
	s_add_i32 s1, vcc_lo, s70
	s_add_i32 s0, s1, 0x2000
	s_add_u32 s54, s60, 0x40080
	s_addc_u32 s55, s61, 0
	s_add_i32 s47, vcc_hi, s70
	s_add_i32 s46, s47, 0x2000
	s_cmp_gt_u32 s29, 13
	ds_read_b128 v[196:199], v151
	ds_read_b128 v[200:203], v151 offset:1024
	ds_read_b128 v[222:225], v151 offset:2048
	ds_read_b128 v[226:229], v151 offset:3072
	ds_read_b128 v[230:233], v151 offset:4096
	ds_read_b128 v[234:237], v151 offset:5120
	ds_read_b128 v[238:241], v151 offset:6144
	ds_read_b128 v[242:245], v151 offset:7168
	global_load_lds_dwordx4 v[146:147], off
	s_mov_b32 m0, s84
	s_nop 0
	global_load_lds_dwordx4 v[144:145], off
	s_waitcnt vmcnt(8)
	s_waitcnt lgkmcnt(0)
	s_barrier
	s_setprio 1
	s_waitcnt lgkmcnt(0)
	v_mfma_f32_16x16x32_bf16 v[128:131], v[152:155], v[196:199], v[128:131]
	v_mfma_f32_16x16x32_bf16 v[128:131], v[156:159], v[200:203], v[128:131]
	v_mfma_f32_16x16x32_bf16 v[124:127], v[160:163], v[196:199], v[124:127]
	v_mfma_f32_16x16x32_bf16 v[124:127], v[164:167], v[200:203], v[124:127]
	v_mfma_f32_16x16x32_bf16 v[112:115], v[152:155], v[222:225], v[112:115]
	v_mfma_f32_16x16x32_bf16 v[112:115], v[156:159], v[226:229], v[112:115]
	v_mfma_f32_16x16x32_bf16 v[108:111], v[160:163], v[222:225], v[108:111]
	v_mfma_f32_16x16x32_bf16 v[108:111], v[164:167], v[226:229], v[108:111]
	v_mfma_f32_16x16x32_bf16 v[94:97], v[152:155], v[230:233], v[94:97]
	v_mfma_f32_16x16x32_bf16 v[94:97], v[156:159], v[234:237], v[94:97]
	v_mfma_f32_16x16x32_bf16 v[90:93], v[160:163], v[230:233], v[90:93]
	v_mfma_f32_16x16x32_bf16 v[90:93], v[164:167], v[234:237], v[90:93]
	v_mfma_f32_16x16x32_bf16 v[78:81], v[152:155], v[238:241], v[78:81]
	v_mfma_f32_16x16x32_bf16 v[78:81], v[156:159], v[242:245], v[78:81]
	v_mfma_f32_16x16x32_bf16 v[74:77], v[160:163], v[238:241], v[74:77]
	v_mfma_f32_16x16x32_bf16 v[74:77], v[164:167], v[242:245], v[74:77]
	s_setprio 0
	s_setprio 1
	v_mfma_f32_16x16x32_bf16 v[120:123], v[180:183], v[196:199], v[120:123]
	v_mfma_f32_16x16x32_bf16 v[120:123], v[184:187], v[200:203], v[120:123]
	v_mfma_f32_16x16x32_bf16 v[116:119], v[188:191], v[196:199], v[116:119]
	v_mfma_f32_16x16x32_bf16 v[116:119], v[192:195], v[200:203], v[116:119]
	v_mfma_f32_16x16x32_bf16 v[104:107], v[180:183], v[222:225], v[104:107]
	v_mfma_f32_16x16x32_bf16 v[104:107], v[184:187], v[226:229], v[104:107]
	v_mfma_f32_16x16x32_bf16 v[100:103], v[188:191], v[222:225], v[100:103]
	v_mfma_f32_16x16x32_bf16 v[100:103], v[192:195], v[226:229], v[100:103]
	v_mfma_f32_16x16x32_bf16 v[86:89], v[180:183], v[230:233], v[86:89]
	v_mfma_f32_16x16x32_bf16 v[86:89], v[184:187], v[234:237], v[86:89]
	v_mfma_f32_16x16x32_bf16 v[82:85], v[188:191], v[230:233], v[82:85]
	v_mfma_f32_16x16x32_bf16 v[82:85], v[192:195], v[234:237], v[82:85]
	v_mfma_f32_16x16x32_bf16 v[70:73], v[180:183], v[238:241], v[70:73]
	v_mfma_f32_16x16x32_bf16 v[70:73], v[184:187], v[242:245], v[70:73]
	v_mfma_f32_16x16x32_bf16 v[66:69], v[188:191], v[238:241], v[66:69]
	v_mfma_f32_16x16x32_bf16 v[66:69], v[192:195], v[242:245], v[66:69]
	s_setprio 0
	s_barrier
	s_mov_b32 m0, s94
	v_lshl_add_u64 v[148:149], s[60:61], 0, v[136:137]
	ds_read_b128 v[196:199], v151 offset:16384
	ds_read_b128 v[200:203], v151 offset:17408
	ds_read_b128 v[222:225], v151 offset:18432
	ds_read_b128 v[226:229], v151 offset:19456
	ds_read_b128 v[230:233], v151 offset:20480
	ds_read_b128 v[234:237], v151 offset:21504
	ds_read_b128 v[238:241], v151 offset:22528
	ds_read_b128 v[242:245], v151 offset:23552
	global_load_lds_dwordx4 v[148:149], off
	v_lshl_add_u64 v[168:169], s[60:61], 0, v[132:133]
	s_mov_b32 m0, s95
	v_lshl_add_u64 v[172:173], s[62:63], 0, v[136:137]
	global_load_lds_dwordx4 v[168:169], off
	s_mov_b32 m0, s96
	v_lshl_add_u64 v[212:213], s[58:59], 0, v[134:135]
	global_load_lds_dwordx4 v[172:173], off
	v_lshl_add_u64 v[172:173], s[62:63], 0, v[132:133]
	s_mov_b32 m0, s97
	s_nop 0
	global_load_lds_dwordx4 v[172:173], off
	v_lshl_add_u64 v[172:173], s[58:59], 0, v[138:139]
	s_mov_b32 m0, s71
	s_nop 0
	global_load_lds_dwordx4 v[172:173], off
	s_mov_b32 m0, s75
	s_nop 0
	global_load_lds_dwordx4 v[212:213], off
	s_waitcnt vmcnt(8)
	s_waitcnt lgkmcnt(0)
	s_barrier
; #define PG8_STAGE(bufoff, gbase, voff) do { _Pragma("unroll") for (int _i = 0; _i < 2; ++_i) \
;         __builtin_amdgcn_global_load_lds((const unsigned*)((const char*)(gbase) + (voff)[_i]), (PG8_LAS unsigned*)(lds + (bufoff) + ldsw + _i * 8192), 16, 0, AUX_A); } while (0)
; #define PG8_LDA(dst, b, h) do { _Pragma("unroll") for (int m = 0; m < 4; ++m) _Pragma("unroll") for (int k = 0; k < 2; ++k) dst[m][k] = *(const PG8_LAS bf16x8*)(lds + PG8_SA(b, h) + aoff + m * 2048 + k * 1024); } while (0)
; #define PG8_LDB(dst, b, h) do { _Pragma("unroll") for (int n = 0; n < 2; ++n) _Pragma("unroll") for (int k = 0; k < 2; ++k) dst[n][k] = *(const PG8_LAS bf16x8*)(lds + PG8_SB(b, h) + boff + n * 2048 + k * 1024); } while (0)
; #define PG8_MMA(ai, bj, At, Bt) do { __builtin_amdgcn_s_setprio(1); _Pragma("unroll") for (int m = 0; m < 4; ++m) _Pragma("unroll") for (int n = 0; n < 2; ++n) _Pragma("unroll") for (int k = 0; k < 2; ++k) \
;         acc[ai][bj][m][n] = __builtin_amdgcn_mfma_f32_16x16x32_bf16(Bt[n][k], At[m][k], acc[ai][bj][m][n], 0, 0, 0); __builtin_amdgcn_s_setprio(0); } while (0)
; #define PG8_WAIT_V(n) asm volatile("s_waitcnt vmcnt(" #n ")" ::: "memory")
; #define PG8_WAIT_L(n) asm volatile("s_waitcnt lgkmcnt(" #n ")" ::: "memory")
; #define PG8_BAR __builtin_amdgcn_s_barrier()
; #define PG8_SCHED __builtin_amdgcn_sched_barrier(0)
; template <class Epi, class Sched, bool ALIGN_EPI = false, bool SP2 = false>
; __device__ __forceinline__ void gemm_phase(PG8_LAS unsigned char* lds, const Gemm g, const Sched& S, const Epi& E) {
;     ...
;             PG8_WAIT_V(8); PG8_WAIT_L(0); PG8_BAR; PG8_MMA(1, 0, At, B0); PG8_MMA(1, 1, At, B1); PG8_BAR; PG8_SCHED;
;             PG8_LDB(B0, 1, 0); PG8_LDB(B1, 1, 1); PG8_SCHED; PG8_LDA(At, 1, 0); PG8_STAGE(PG8_SA(0, 1), a2 + hstep, voffA);
;             PG8_WAIT_V(8); PG8_WAIT_L(0); PG8_BAR; PG8_MMA(0, 0, At, B0); PG8_MMA(0, 1, At, B1); PG8_BAR; PG8_SCHED;
	s_setprio 1
	s_waitcnt lgkmcnt(0)
	v_mfma_f32_16x16x32_bf16 v[62:65], v[152:155], v[196:199], v[62:65]
	v_mfma_f32_16x16x32_bf16 v[62:65], v[156:159], v[200:203], v[62:65]
	v_mfma_f32_16x16x32_bf16 v[58:61], v[160:163], v[196:199], v[58:61]
	v_mfma_f32_16x16x32_bf16 v[58:61], v[164:167], v[200:203], v[58:61]
	v_mfma_f32_16x16x32_bf16 v[46:49], v[152:155], v[222:225], v[46:49]
	v_mfma_f32_16x16x32_bf16 v[46:49], v[156:159], v[226:229], v[46:49]
	v_mfma_f32_16x16x32_bf16 v[42:45], v[160:163], v[222:225], v[42:45]
	v_mfma_f32_16x16x32_bf16 v[42:45], v[164:167], v[226:229], v[42:45]
	v_mfma_f32_16x16x32_bf16 v[30:33], v[152:155], v[230:233], v[30:33]
	v_mfma_f32_16x16x32_bf16 v[30:33], v[156:159], v[234:237], v[30:33]
	v_mfma_f32_16x16x32_bf16 v[26:29], v[160:163], v[230:233], v[26:29]
	v_mfma_f32_16x16x32_bf16 v[26:29], v[164:167], v[234:237], v[26:29]
	v_mfma_f32_16x16x32_bf16 v[14:17], v[152:155], v[238:241], v[14:17]
	v_mfma_f32_16x16x32_bf16 v[14:17], v[156:159], v[242:245], v[14:17]
	v_mfma_f32_16x16x32_bf16 v[10:13], v[160:163], v[238:241], v[10:13]
	v_mfma_f32_16x16x32_bf16 v[10:13], v[164:167], v[242:245], v[10:13]
	s_setprio 0
	s_setprio 1
	v_mfma_f32_16x16x32_bf16 v[54:57], v[180:183], v[196:199], v[54:57]
	v_mfma_f32_16x16x32_bf16 v[54:57], v[184:187], v[200:203], v[54:57]
	v_mfma_f32_16x16x32_bf16 v[50:53], v[188:191], v[196:199], v[50:53]
	v_mfma_f32_16x16x32_bf16 v[50:53], v[192:195], v[200:203], v[50:53]
	v_mfma_f32_16x16x32_bf16 v[38:41], v[180:183], v[222:225], v[38:41]
	v_mfma_f32_16x16x32_bf16 v[38:41], v[184:187], v[226:229], v[38:41]
	v_mfma_f32_16x16x32_bf16 v[34:37], v[188:191], v[222:225], v[34:37]
	v_mfma_f32_16x16x32_bf16 v[34:37], v[192:195], v[226:229], v[34:37]
	v_mfma_f32_16x16x32_bf16 v[22:25], v[180:183], v[230:233], v[22:25]
	v_mfma_f32_16x16x32_bf16 v[22:25], v[184:187], v[234:237], v[22:25]
	v_mfma_f32_16x16x32_bf16 v[18:21], v[188:191], v[230:233], v[18:21]
	v_mfma_f32_16x16x32_bf16 v[18:21], v[192:195], v[234:237], v[18:21]
	v_mfma_f32_16x16x32_bf16 v[6:9], v[180:183], v[238:241], v[6:9]
	v_mfma_f32_16x16x32_bf16 v[6:9], v[184:187], v[242:245], v[6:9]
	v_mfma_f32_16x16x32_bf16 v[2:5], v[188:191], v[238:241], v[2:5]
	v_mfma_f32_16x16x32_bf16 v[2:5], v[192:195], v[242:245], v[2:5]
	s_setprio 0
	s_barrier
	v_add_u32_e32 v164, vcc_lo, v99
	v_add_u32_e32 v192, vcc_hi, v99
	ds_read_b128 v[152:155], v164
	ds_read_b128 v[156:159], v164 offset:1024
	ds_read_b128 v[160:163], v164 offset:2048
	ds_read_b128 v[164:167], v164 offset:3072
	ds_read_b128 v[180:183], v192
	ds_read_b128 v[184:187], v192 offset:1024
	ds_read_b128 v[188:191], v192 offset:2048
	ds_read_b128 v[192:195], v192 offset:3072
	s_mov_b32 m0, s78
	v_lshl_add_u64 v[246:247], s[56:57], 0, v[138:139]
	ds_read_b128 v[196:199], v151 offset:32768
	ds_read_b128 v[200:203], v151 offset:33792
	ds_read_b128 v[222:225], v151 offset:34816
	ds_read_b128 v[226:229], v151 offset:35840
	ds_read_b128 v[230:233], v151 offset:36864
	ds_read_b128 v[234:237], v151 offset:37888
	ds_read_b128 v[238:241], v151 offset:38912
	ds_read_b128 v[242:245], v151 offset:39936
	global_load_lds_dwordx4 v[246:247], off
	v_lshl_add_u64 v[246:247], s[56:57], 0, v[134:135]
	s_mov_b32 m0, s82
	s_nop 0
	global_load_lds_dwordx4 v[246:247], off
	s_waitcnt vmcnt(8)
	s_waitcnt lgkmcnt(0)
	s_barrier
	s_setprio 1
	s_waitcnt lgkmcnt(0)
	v_mfma_f32_16x16x32_bf16 v[128:131], v[152:155], v[196:199], v[128:131]
	v_mfma_f32_16x16x32_bf16 v[128:131], v[156:159], v[200:203], v[128:131]
	v_mfma_f32_16x16x32_bf16 v[124:127], v[160:163], v[196:199], v[124:127]
	v_mfma_f32_16x16x32_bf16 v[124:127], v[164:167], v[200:203], v[124:127]
	v_mfma_f32_16x16x32_bf16 v[112:115], v[152:155], v[222:225], v[112:115]
	v_mfma_f32_16x16x32_bf16 v[112:115], v[156:159], v[226:229], v[112:115]
	v_mfma_f32_16x16x32_bf16 v[108:111], v[160:163], v[222:225], v[108:111]
	v_mfma_f32_16x16x32_bf16 v[108:111], v[164:167], v[226:229], v[108:111]
	v_mfma_f32_16x16x32_bf16 v[94:97], v[152:155], v[230:233], v[94:97]
	v_mfma_f32_16x16x32_bf16 v[94:97], v[156:159], v[234:237], v[94:97]
	v_mfma_f32_16x16x32_bf16 v[90:93], v[160:163], v[230:233], v[90:93]
	v_mfma_f32_16x16x32_bf16 v[90:93], v[164:167], v[234:237], v[90:93]
	v_mfma_f32_16x16x32_bf16 v[78:81], v[152:155], v[238:241], v[78:81]
	v_mfma_f32_16x16x32_bf16 v[78:81], v[156:159], v[242:245], v[78:81]
	v_mfma_f32_16x16x32_bf16 v[74:77], v[160:163], v[238:241], v[74:77]
	v_mfma_f32_16x16x32_bf16 v[74:77], v[164:167], v[242:245], v[74:77]
	s_setprio 0
	s_setprio 1
	v_mfma_f32_16x16x32_bf16 v[120:123], v[180:183], v[196:199], v[120:123]
	v_mfma_f32_16x16x32_bf16 v[120:123], v[184:187], v[200:203], v[120:123]
	v_mfma_f32_16x16x32_bf16 v[116:119], v[188:191], v[196:199], v[116:119]
	v_mfma_f32_16x16x32_bf16 v[116:119], v[192:195], v[200:203], v[116:119]
	v_mfma_f32_16x16x32_bf16 v[104:107], v[180:183], v[222:225], v[104:107]
	v_mfma_f32_16x16x32_bf16 v[104:107], v[184:187], v[226:229], v[104:107]
	v_mfma_f32_16x16x32_bf16 v[100:103], v[188:191], v[222:225], v[100:103]
	v_mfma_f32_16x16x32_bf16 v[100:103], v[192:195], v[226:229], v[100:103]
	v_mfma_f32_16x16x32_bf16 v[86:89], v[180:183], v[230:233], v[86:89]
	v_mfma_f32_16x16x32_bf16 v[86:89], v[184:187], v[234:237], v[86:89]
	v_mfma_f32_16x16x32_bf16 v[82:85], v[188:191], v[230:233], v[82:85]
	v_mfma_f32_16x16x32_bf16 v[82:85], v[192:195], v[234:237], v[82:85]
	v_mfma_f32_16x16x32_bf16 v[70:73], v[180:183], v[238:241], v[70:73]
	v_mfma_f32_16x16x32_bf16 v[70:73], v[184:187], v[242:245], v[70:73]
	v_mfma_f32_16x16x32_bf16 v[66:69], v[188:191], v[238:241], v[66:69]
	v_mfma_f32_16x16x32_bf16 v[66:69], v[192:195], v[242:245], v[66:69]
	s_setprio 0
	s_barrier
; #define PG8_STAGE(bufoff, gbase, voff) do { _Pragma("unroll") for (int _i = 0; _i < 2; ++_i) \
;         __builtin_amdgcn_global_load_lds((const unsigned*)((const char*)(gbase) + (voff)[_i]), (PG8_LAS unsigned*)(lds + (bufoff) + ldsw + _i * 8192), 16, 0, AUX_A); } while (0)
; #define PG8_STAGEB(bufoff, gbase, voff) do { _Pragma("unroll") for (int _i = 0; _i < 2; ++_i) \
;         __builtin_amdgcn_global_load_lds((const unsigned*)((const char*)(gbase) + (voff)[_i]), (PG8_LAS unsigned*)(lds + (bufoff) + ldsw + _i * 8192), 16, 0, AUX_B); } while (0)
; template <class Epi, class Sched, bool ALIGN_EPI = false, bool SP2 = false>
; __device__ __forceinline__ void gemm_phase(PG8_LAS unsigned char* lds, const Gemm g, const Sched& S, const Epi& E) {
;     ...
;             PG8_LDA(At, 1, 1); PG8_STAGEB(PG8_SB(1, 0), b3, voffB); PG8_STAGEB(PG8_SB(1, 1), b3 + hstep, voffB); PG8_STAGE(PG8_SA(1, 0), a3, voffA);
;             PG8_WAIT_V(8); PG8_WAIT_L(0); PG8_BAR; PG8_MMA(1, 0, At, B0); PG8_MMA(1, 1, At, B1); PG8_BAR; PG8_SCHED;
;             } else {
;             PG8_LDB(B0, 0, 0); PG8_SCHED; PG8_LDA(At, 0, 0); PG8_STAGE(PG8_SA(1, 1), a1 + hstep, voffA);
;             PG8_WAIT_L(8); PG8_BAR; PG8_WAIT_L(0); PG8_MMA(0, 0, At, B0); PG8_BAR; PG8_SCHED;
;             PG8_LDB(B1, 0, 1); PG8_STAGEB(PG8_SB(0, 0), b2, voffB);
;             PG8_BAR; PG8_WAIT_L(0); PG8_MMA(0, 1, At, B1); PG8_BAR;
;             PG8_LDA(At, 0, 1); PG8_STAGE(PG8_SA(0, 0), a2, voffA);
;             PG8_BAR; PG8_WAIT_L(0); PG8_MMA(1, 0, At, B0); PG8_BAR; PG8_SCHED;
;             PG8_STAGEB(PG8_SB(0, 1), b2 + hstep, voffB);
;             PG8_WAIT_V(6); PG8_BAR; PG8_MMA(1, 1, At, B1); PG8_BAR;
;             PG8_LDB(B0, 1, 0); PG8_SCHED; PG8_LDA(At, 1, 0); PG8_STAGE(PG8_SA(0, 1), a2 + hstep, voffA);
;             PG8_WAIT_L(8); PG8_BAR; PG8_WAIT_L(0); PG8_MMA(0, 0, At, B0); PG8_BAR; PG8_SCHED;
;             PG8_LDB(B1, 1, 1); PG8_STAGEB(PG8_SB(1, 0), b3, voffB);
;             PG8_BAR; PG8_WAIT_L(0); PG8_MMA(0, 1, At, B1); PG8_BAR;
;             PG8_LDA(At, 1, 1); PG8_STAGE(PG8_SA(1, 0), a3, voffA);
;             PG8_BAR; PG8_WAIT_L(0); PG8_MMA(1, 0, At, B0); PG8_BAR; PG8_SCHED;
;             PG8_STAGEB(PG8_SB(1, 1), b3 + hstep, voffB);
;             PG8_WAIT_V(6); PG8_BAR; PG8_MMA(1, 1, At, B1); PG8_BAR;
;             }
;         }
;         if constexpr (ALIGN_EPI) { if (wr == 0) PG8_BAR; }
	s_mov_b32 m0, s1
	v_lshl_add_u64 v[148:149], v[148:149], 0, s[76:77]
	ds_read_b128 v[196:199], v151 offset:49152
	ds_read_b128 v[200:203], v151 offset:50176
	ds_read_b128 v[222:225], v151 offset:51200
	ds_read_b128 v[226:229], v151 offset:52224
	ds_read_b128 v[230:233], v151 offset:53248
	ds_read_b128 v[234:237], v151 offset:54272
	ds_read_b128 v[238:241], v151 offset:55296
	ds_read_b128 v[242:245], v151 offset:56320
	global_load_lds_dwordx4 v[148:149], off
	v_lshl_add_u64 v[148:149], v[168:169], 0, s[76:77]
	s_mov_b32 m0, s0
	s_nop 0
	global_load_lds_dwordx4 v[148:149], off
	v_lshl_add_u64 v[148:149], s[54:55], 0, v[136:137]
	s_mov_b32 m0, s47
	s_nop 0
	global_load_lds_dwordx4 v[148:149], off
	v_lshl_add_u64 v[148:149], s[54:55], 0, v[132:133]
	s_mov_b32 m0, s46
	s_nop 0
	global_load_lds_dwordx4 v[148:149], off
	v_lshl_add_u64 v[148:149], v[172:173], 0, s[76:77]
	s_mov_b32 m0, s83
	s_nop 0
	global_load_lds_dwordx4 v[148:149], off
	v_lshl_add_u64 v[148:149], v[212:213], 0, s[76:77]
	s_mov_b32 m0, s88
	s_nop 0
	global_load_lds_dwordx4 v[148:149], off
	s_waitcnt vmcnt(8)
	s_waitcnt lgkmcnt(0)
	s_barrier
	s_setprio 1
	s_waitcnt lgkmcnt(0)
	v_mfma_f32_16x16x32_bf16 v[62:65], v[152:155], v[196:199], v[62:65]
	v_mfma_f32_16x16x32_bf16 v[62:65], v[156:159], v[200:203], v[62:65]
	v_mfma_f32_16x16x32_bf16 v[58:61], v[160:163], v[196:199], v[58:61]
	v_mfma_f32_16x16x32_bf16 v[58:61], v[164:167], v[200:203], v[58:61]
	v_mfma_f32_16x16x32_bf16 v[46:49], v[152:155], v[222:225], v[46:49]
	v_mfma_f32_16x16x32_bf16 v[46:49], v[156:159], v[226:229], v[46:49]
	v_mfma_f32_16x16x32_bf16 v[42:45], v[160:163], v[222:225], v[42:45]
	v_mfma_f32_16x16x32_bf16 v[42:45], v[164:167], v[226:229], v[42:45]
	v_mfma_f32_16x16x32_bf16 v[30:33], v[152:155], v[230:233], v[30:33]
	v_mfma_f32_16x16x32_bf16 v[30:33], v[156:159], v[234:237], v[30:33]
	v_mfma_f32_16x16x32_bf16 v[26:29], v[160:163], v[230:233], v[26:29]
	v_mfma_f32_16x16x32_bf16 v[26:29], v[164:167], v[234:237], v[26:29]
	v_mfma_f32_16x16x32_bf16 v[14:17], v[152:155], v[238:241], v[14:17]
	v_mfma_f32_16x16x32_bf16 v[14:17], v[156:159], v[242:245], v[14:17]
	v_mfma_f32_16x16x32_bf16 v[10:13], v[160:163], v[238:241], v[10:13]
	v_mfma_f32_16x16x32_bf16 v[10:13], v[164:167], v[242:245], v[10:13]
	s_setprio 0
	s_setprio 1
	v_mfma_f32_16x16x32_bf16 v[54:57], v[180:183], v[196:199], v[54:57]
	v_mfma_f32_16x16x32_bf16 v[54:57], v[184:187], v[200:203], v[54:57]
	v_mfma_f32_16x16x32_bf16 v[50:53], v[188:191], v[196:199], v[50:53]
	v_mfma_f32_16x16x32_bf16 v[50:53], v[192:195], v[200:203], v[50:53]
	v_mfma_f32_16x16x32_bf16 v[38:41], v[180:183], v[222:225], v[38:41]
	v_mfma_f32_16x16x32_bf16 v[38:41], v[184:187], v[226:229], v[38:41]
	v_mfma_f32_16x16x32_bf16 v[34:37], v[188:191], v[222:225], v[34:37]
	v_mfma_f32_16x16x32_bf16 v[34:37], v[192:195], v[226:229], v[34:37]
	v_mfma_f32_16x16x32_bf16 v[22:25], v[180:183], v[230:233], v[22:25]
	v_mfma_f32_16x16x32_bf16 v[22:25], v[184:187], v[234:237], v[22:25]
	v_mfma_f32_16x16x32_bf16 v[18:21], v[188:191], v[230:233], v[18:21]
	v_mfma_f32_16x16x32_bf16 v[18:21], v[192:195], v[234:237], v[18:21]
	v_mfma_f32_16x16x32_bf16 v[6:9], v[180:183], v[238:241], v[6:9]
	v_mfma_f32_16x16x32_bf16 v[6:9], v[184:187], v[242:245], v[6:9]
	v_mfma_f32_16x16x32_bf16 v[2:5], v[188:191], v[238:241], v[2:5]
	v_mfma_f32_16x16x32_bf16 v[2:5], v[192:195], v[242:245], v[2:5]
	s_setprio 0
	s_barrier
	v_lshl_add_u64 v[144:145], v[144:145], 0, s[86:87]
	v_lshl_add_u64 v[146:147], v[146:147], 0, s[86:87]
	s_mov_b32 s29, s81
	s_cbranch_scc0 .LBB0_1067
	s_and_b64 vcc, exec, s[12:13]
	s_cbranch_vccz .LBB0_1070
	s_barrier

; #define PG8_STAGE(bufoff, gbase, voff) do { _Pragma("unroll") for (int _i = 0; _i < 2; ++_i) \
;         __builtin_amdgcn_global_load_lds((const unsigned*)((const char*)(gbase) + (voff)[_i]), (PG8_LAS unsigned*)(lds + (bufoff) + ldsw + _i * 8192), 16, 0, AUX_A); } while (0)
; #define PG8_STAGEB(bufoff, gbase, voff) do { _Pragma("unroll") for (int _i = 0; _i < 2; ++_i) \
;         __builtin_amdgcn_global_load_lds((const unsigned*)((const char*)(gbase) + (voff)[_i]), (PG8_LAS unsigned*)(lds + (bufoff) + ldsw + _i * 8192), 16, 0, AUX_B); } while (0)
; #define PG8_LDA(dst, b, h) do { _Pragma("unroll") for (int m = 0; m < 4; ++m) _Pragma("unroll") for (int k = 0; k < 2; ++k) dst[m][k] = *(const PG8_LAS bf16x8*)(lds + PG8_SA(b, h) + aoff + m * 2048 + k * 1024); } while (0)
; #define PG8_LDB(dst, b, h) do { _Pragma("unroll") for (int n = 0; n < 2; ++n) _Pragma("unroll") for (int k = 0; k < 2; ++k) dst[n][k] = *(const PG8_LAS bf16x8*)(lds + PG8_SB(b, h) + boff + n * 2048 + k * 1024); } while (0)
; #define PG8_WAIT_V(n) asm volatile("s_waitcnt vmcnt(" #n ")" ::: "memory")
; #define PG8_WAIT_L(n) asm volatile("s_waitcnt lgkmcnt(" #n ")" ::: "memory")
; template <class Epi, class Sched, bool ALIGN_EPI = false, bool SP2 = false>
; __device__ __forceinline__ void gemm_phase(PG8_LAS unsigned char* lds, const Gemm g, const Sched& S, const Epi& E) {
;     ...
;         const char* nAr = has_next ? nA + (size_t)nxt.krot * kstep : PG8_KP(cA, 0, rot, nt); const char* nBr = has_next ? nB + (size_t)nxt.krot * kstep : PG8_KP(cB, 0, rot, nt);
;         for (int t = 0; t < nt; t += 2) {
;             const bool last = (t == nt - 2);
;             const char* a1 = PG8_KP(cA, t + 1, rot, nt);
;             const char* a2 = last ? nAr : PG8_KP(cA, t + 2, rot, nt); const char* b2 = last ? nBr : PG8_KP(cB, t + 2, rot, nt);
;             const char* a3 = a2 + kstep; const char* b3 = b2 + kstep;
;             if (last && has_next) S.a_ready(nxt);
;             if constexpr (SP2) {
;             PG8_LDB(B0, 0, 0); PG8_LDB(B1, 0, 1); PG8_SCHED; PG8_LDA(At, 0, 0); PG8_STAGE(PG8_SA(1, 1), a1 + hstep, voffA);
;             PG8_WAIT_V(8); PG8_WAIT_L(0); PG8_BAR; PG8_MMA(0, 0, At, B0); PG8_MMA(0, 1, At, B1); PG8_BAR; PG8_SCHED;
;             PG8_LDA(At, 0, 1); PG8_STAGEB(PG8_SB(0, 0), b2, voffB); PG8_STAGEB(PG8_SB(0, 1), b2 + hstep, voffB); PG8_STAGE(PG8_SA(0, 0), a2, voffA);
.LBB0_1157:
	s_add_i32 s81, s29, 2
	s_cmp_lt_u32 s29, 14
	s_cselect_b32 s0, 0, -16
	s_add_i32 s0, s81, s0
	s_ashr_i32 s1, s0, 31
	s_lshl_b64 s[0:1], s[0:1], 7
	s_add_u32 s2, s52, s0
	s_addc_u32 s46, s53, s1
	s_add_u32 s0, s50, s0
	s_addc_u32 s1, s51, s1
	s_cmp_eq_u32 s29, 14
	s_cselect_b32 s59, s19, s46
	s_cselect_b32 s58, s39, s2
	s_cselect_b32 s61, s92, s1
	s_cselect_b32 s60, s93, s0
	s_add_i32 s2, 0, 0x10000
	s_add_i32 s94, s2, s70
	s_add_i32 s46, 0, 0x14000
	s_add_i32 m0, s71, 0xc000
	s_add_i32 s84, s71, 0xe000
	s_add_i32 s95, s94, 0x2000
	s_add_u32 s62, s60, 0x40000
	s_addc_u32 s63, s61, 0
	s_add_i32 s96, s46, s70
	v_add_u32_e32 v162, s2, v99
	v_add_u32_e32 v166, s46, v99
	s_add_i32 s97, s96, 0x2000
	s_add_i32 vcc_lo, 0, 0x18000
	s_add_i32 vcc_hi, 0, 0x1c000
	ds_read_b128 v[148:151], v162
	ds_read_b128 v[154:157], v162 offset:1024
	ds_read_b128 v[158:161], v162 offset:2048
	ds_read_b128 v[162:165], v162 offset:3072
	ds_read_b128 v[180:183], v166
	ds_read_b128 v[184:187], v166 offset:1024
	ds_read_b128 v[188:191], v166 offset:2048
	ds_read_b128 v[192:195], v166 offset:3072
	s_add_u32 s56, s58, 0x40000
	s_addc_u32 s57, s59, 0
	s_add_i32 s1, vcc_lo, s70
	s_add_i32 s0, s1, 0x2000
	s_add_u32 s54, s60, 0x40080
	s_addc_u32 s55, s61, 0
	s_add_i32 s47, vcc_hi, s70
	s_add_i32 s46, s47, 0x2000
	s_cmp_gt_u32 s29, 13
	ds_read_b128 v[196:199], v153
	ds_read_b128 v[200:203], v153 offset:1024
	ds_read_b128 v[222:225], v153 offset:2048
	ds_read_b128 v[226:229], v153 offset:3072
	ds_read_b128 v[230:233], v153 offset:4096
	ds_read_b128 v[234:237], v153 offset:5120
	ds_read_b128 v[238:241], v153 offset:6144
	ds_read_b128 v[242:245], v153 offset:7168
	global_load_lds_dwordx4 v[146:147], off
	s_mov_b32 m0, s84
	s_nop 0
	global_load_lds_dwordx4 v[144:145], off
	s_waitcnt vmcnt(8)
	s_waitcnt lgkmcnt(0)
	s_barrier
	s_setprio 1
	s_waitcnt lgkmcnt(0)
	v_mfma_f32_16x16x32_bf16 v[128:131], v[148:151], v[196:199], v[128:131]
	v_mfma_f32_16x16x32_bf16 v[128:131], v[154:157], v[200:203], v[128:131]
	v_mfma_f32_16x16x32_bf16 v[124:127], v[158:161], v[196:199], v[124:127]
	v_mfma_f32_16x16x32_bf16 v[124:127], v[162:165], v[200:203], v[124:127]
	v_mfma_f32_16x16x32_bf16 v[112:115], v[148:151], v[222:225], v[112:115]
	v_mfma_f32_16x16x32_bf16 v[112:115], v[154:157], v[226:229], v[112:115]
	v_mfma_f32_16x16x32_bf16 v[108:111], v[158:161], v[222:225], v[108:111]
	v_mfma_f32_16x16x32_bf16 v[108:111], v[162:165], v[226:229], v[108:111]
	v_mfma_f32_16x16x32_bf16 v[94:97], v[148:151], v[230:233], v[94:97]
	v_mfma_f32_16x16x32_bf16 v[94:97], v[154:157], v[234:237], v[94:97]
	v_mfma_f32_16x16x32_bf16 v[90:93], v[158:161], v[230:233], v[90:93]
	v_mfma_f32_16x16x32_bf16 v[90:93], v[162:165], v[234:237], v[90:93]
	v_mfma_f32_16x16x32_bf16 v[78:81], v[148:151], v[238:241], v[78:81]
	v_mfma_f32_16x16x32_bf16 v[78:81], v[154:157], v[242:245], v[78:81]
	v_mfma_f32_16x16x32_bf16 v[74:77], v[158:161], v[238:241], v[74:77]
	v_mfma_f32_16x16x32_bf16 v[74:77], v[162:165], v[242:245], v[74:77]
	s_setprio 0
	s_setprio 1
	v_mfma_f32_16x16x32_bf16 v[120:123], v[180:183], v[196:199], v[120:123]
	v_mfma_f32_16x16x32_bf16 v[120:123], v[184:187], v[200:203], v[120:123]
	v_mfma_f32_16x16x32_bf16 v[116:119], v[188:191], v[196:199], v[116:119]
	v_mfma_f32_16x16x32_bf16 v[116:119], v[192:195], v[200:203], v[116:119]
	v_mfma_f32_16x16x32_bf16 v[104:107], v[180:183], v[222:225], v[104:107]
	v_mfma_f32_16x16x32_bf16 v[104:107], v[184:187], v[226:229], v[104:107]
	v_mfma_f32_16x16x32_bf16 v[100:103], v[188:191], v[222:225], v[100:103]
	v_mfma_f32_16x16x32_bf16 v[100:103], v[192:195], v[226:229], v[100:103]
	v_mfma_f32_16x16x32_bf16 v[86:89], v[180:183], v[230:233], v[86:89]
	v_mfma_f32_16x16x32_bf16 v[86:89], v[184:187], v[234:237], v[86:89]
	v_mfma_f32_16x16x32_bf16 v[82:85], v[188:191], v[230:233], v[82:85]
	v_mfma_f32_16x16x32_bf16 v[82:85], v[192:195], v[234:237], v[82:85]
	v_mfma_f32_16x16x32_bf16 v[70:73], v[180:183], v[238:241], v[70:73]
	v_mfma_f32_16x16x32_bf16 v[70:73], v[184:187], v[242:245], v[70:73]
	v_mfma_f32_16x16x32_bf16 v[66:69], v[188:191], v[238:241], v[66:69]
	v_mfma_f32_16x16x32_bf16 v[66:69], v[192:195], v[242:245], v[66:69]
	s_setprio 0
	s_barrier
	s_mov_b32 m0, s94
	v_lshl_add_u64 v[166:167], s[60:61], 0, v[136:137]
	ds_read_b128 v[196:199], v153 offset:16384
	ds_read_b128 v[200:203], v153 offset:17408
	ds_read_b128 v[222:225], v153 offset:18432
	ds_read_b128 v[226:229], v153 offset:19456
	ds_read_b128 v[230:233], v153 offset:20480
	ds_read_b128 v[234:237], v153 offset:21504
	ds_read_b128 v[238:241], v153 offset:22528
	ds_read_b128 v[242:245], v153 offset:23552
	global_load_lds_dwordx4 v[166:167], off
	v_lshl_add_u64 v[168:169], s[60:61], 0, v[132:133]
	s_mov_b32 m0, s95
	v_lshl_add_u64 v[172:173], s[62:63], 0, v[136:137]
	global_load_lds_dwordx4 v[168:169], off
	s_mov_b32 m0, s96
	v_lshl_add_u64 v[212:213], s[58:59], 0, v[134:135]
	global_load_lds_dwordx4 v[172:173], off
	v_lshl_add_u64 v[172:173], s[62:63], 0, v[132:133]
	s_mov_b32 m0, s97
	s_nop 0
	global_load_lds_dwordx4 v[172:173], off
	v_lshl_add_u64 v[172:173], s[58:59], 0, v[138:139]
	s_mov_b32 m0, s71
	s_nop 0
	global_load_lds_dwordx4 v[172:173], off
	s_mov_b32 m0, s75
	s_nop 0
	global_load_lds_dwordx4 v[212:213], off
	s_waitcnt vmcnt(8)
	s_waitcnt lgkmcnt(0)
	s_barrier
; #define PG8_STAGE(bufoff, gbase, voff) do { _Pragma("unroll") for (int _i = 0; _i < 2; ++_i) \
;         __builtin_amdgcn_global_load_lds((const unsigned*)((const char*)(gbase) + (voff)[_i]), (PG8_LAS unsigned*)(lds + (bufoff) + ldsw + _i * 8192), 16, 0, AUX_A); } while (0)
; #define PG8_LDA(dst, b, h) do { _Pragma("unroll") for (int m = 0; m < 4; ++m) _Pragma("unroll") for (int k = 0; k < 2; ++k) dst[m][k] = *(const PG8_LAS bf16x8*)(lds + PG8_SA(b, h) + aoff + m * 2048 + k * 1024); } while (0)
; #define PG8_LDB(dst, b, h) do { _Pragma("unroll") for (int n = 0; n < 2; ++n) _Pragma("unroll") for (int k = 0; k < 2; ++k) dst[n][k] = *(const PG8_LAS bf16x8*)(lds + PG8_SB(b, h) + boff + n * 2048 + k * 1024); } while (0)
; #define PG8_MMA(ai, bj, At, Bt) do { __builtin_amdgcn_s_setprio(1); _Pragma("unroll") for (int m = 0; m < 4; ++m) _Pragma("unroll") for (int n = 0; n < 2; ++n) _Pragma("unroll") for (int k = 0; k < 2; ++k) \
;         acc[ai][bj][m][n] = __builtin_amdgcn_mfma_f32_16x16x32_bf16(Bt[n][k], At[m][k], acc[ai][bj][m][n], 0, 0, 0); __builtin_amdgcn_s_setprio(0); } while (0)
; #define PG8_WAIT_V(n) asm volatile("s_waitcnt vmcnt(" #n ")" ::: "memory")
; #define PG8_WAIT_L(n) asm volatile("s_waitcnt lgkmcnt(" #n ")" ::: "memory")
; #define PG8_BAR __builtin_amdgcn_s_barrier()
; #define PG8_SCHED __builtin_amdgcn_sched_barrier(0)
; template <class Epi, class Sched, bool ALIGN_EPI = false, bool SP2 = false>
; __device__ __forceinline__ void gemm_phase(PG8_LAS unsigned char* lds, const Gemm g, const Sched& S, const Epi& E) {
;     ...
;             PG8_WAIT_V(8); PG8_WAIT_L(0); PG8_BAR; PG8_MMA(1, 0, At, B0); PG8_MMA(1, 1, At, B1); PG8_BAR; PG8_SCHED;
;             PG8_LDB(B0, 1, 0); PG8_LDB(B1, 1, 1); PG8_SCHED; PG8_LDA(At, 1, 0); PG8_STAGE(PG8_SA(0, 1), a2 + hstep, voffA);
;             PG8_WAIT_V(8); PG8_WAIT_L(0); PG8_BAR; PG8_MMA(0, 0, At, B0); PG8_MMA(0, 1, At, B1); PG8_BAR; PG8_SCHED;
	s_setprio 1
	s_waitcnt lgkmcnt(0)
	v_mfma_f32_16x16x32_bf16 v[62:65], v[148:151], v[196:199], v[62:65]
	v_mfma_f32_16x16x32_bf16 v[62:65], v[154:157], v[200:203], v[62:65]
	v_mfma_f32_16x16x32_bf16 v[58:61], v[158:161], v[196:199], v[58:61]
	v_mfma_f32_16x16x32_bf16 v[58:61], v[162:165], v[200:203], v[58:61]
	v_mfma_f32_16x16x32_bf16 v[46:49], v[148:151], v[222:225], v[46:49]
	v_mfma_f32_16x16x32_bf16 v[46:49], v[154:157], v[226:229], v[46:49]
	v_mfma_f32_16x16x32_bf16 v[42:45], v[158:161], v[222:225], v[42:45]
	v_mfma_f32_16x16x32_bf16 v[42:45], v[162:165], v[226:229], v[42:45]
	v_mfma_f32_16x16x32_bf16 v[30:33], v[148:151], v[230:233], v[30:33]
	v_mfma_f32_16x16x32_bf16 v[30:33], v[154:157], v[234:237], v[30:33]
	v_mfma_f32_16x16x32_bf16 v[26:29], v[158:161], v[230:233], v[26:29]
	v_mfma_f32_16x16x32_bf16 v[26:29], v[162:165], v[234:237], v[26:29]
	v_mfma_f32_16x16x32_bf16 v[14:17], v[148:151], v[238:241], v[14:17]
	v_mfma_f32_16x16x32_bf16 v[14:17], v[154:157], v[242:245], v[14:17]
	v_mfma_f32_16x16x32_bf16 v[10:13], v[158:161], v[238:241], v[10:13]
	v_mfma_f32_16x16x32_bf16 v[10:13], v[162:165], v[242:245], v[10:13]
	s_setprio 0
	s_setprio 1
	v_mfma_f32_16x16x32_bf16 v[54:57], v[180:183], v[196:199], v[54:57]
	v_mfma_f32_16x16x32_bf16 v[54:57], v[184:187], v[200:203], v[54:57]
	v_mfma_f32_16x16x32_bf16 v[50:53], v[188:191], v[196:199], v[50:53]
	v_mfma_f32_16x16x32_bf16 v[50:53], v[192:195], v[200:203], v[50:53]
	v_mfma_f32_16x16x32_bf16 v[38:41], v[180:183], v[222:225], v[38:41]
	v_mfma_f32_16x16x32_bf16 v[38:41], v[184:187], v[226:229], v[38:41]
	v_mfma_f32_16x16x32_bf16 v[34:37], v[188:191], v[222:225], v[34:37]
	v_mfma_f32_16x16x32_bf16 v[34:37], v[192:195], v[226:229], v[34:37]
	v_mfma_f32_16x16x32_bf16 v[22:25], v[180:183], v[230:233], v[22:25]
	v_mfma_f32_16x16x32_bf16 v[22:25], v[184:187], v[234:237], v[22:25]
	v_mfma_f32_16x16x32_bf16 v[18:21], v[188:191], v[230:233], v[18:21]
	v_mfma_f32_16x16x32_bf16 v[18:21], v[192:195], v[234:237], v[18:21]
	v_mfma_f32_16x16x32_bf16 v[6:9], v[180:183], v[238:241], v[6:9]
	v_mfma_f32_16x16x32_bf16 v[6:9], v[184:187], v[242:245], v[6:9]
	v_mfma_f32_16x16x32_bf16 v[2:5], v[188:191], v[238:241], v[2:5]
	v_mfma_f32_16x16x32_bf16 v[2:5], v[192:195], v[242:245], v[2:5]
	s_setprio 0
	s_barrier
	v_add_u32_e32 v162, vcc_lo, v99
	v_add_u32_e32 v192, vcc_hi, v99
	ds_read_b128 v[148:151], v162
	ds_read_b128 v[154:157], v162 offset:1024
	ds_read_b128 v[158:161], v162 offset:2048
	ds_read_b128 v[162:165], v162 offset:3072
	ds_read_b128 v[180:183], v192
	ds_read_b128 v[184:187], v192 offset:1024
	ds_read_b128 v[188:191], v192 offset:2048
	ds_read_b128 v[192:195], v192 offset:3072
	s_mov_b32 m0, s78
	v_lshl_add_u64 v[246:247], s[56:57], 0, v[138:139]
	ds_read_b128 v[196:199], v153 offset:32768
	ds_read_b128 v[200:203], v153 offset:33792
	ds_read_b128 v[222:225], v153 offset:34816
	ds_read_b128 v[226:229], v153 offset:35840
	ds_read_b128 v[230:233], v153 offset:36864
	ds_read_b128 v[234:237], v153 offset:37888
	ds_read_b128 v[238:241], v153 offset:38912
	ds_read_b128 v[242:245], v153 offset:39936
	global_load_lds_dwordx4 v[246:247], off
	v_lshl_add_u64 v[246:247], s[56:57], 0, v[134:135]
	s_mov_b32 m0, s82
	s_nop 0
	global_load_lds_dwordx4 v[246:247], off
	s_waitcnt vmcnt(8)
	s_waitcnt lgkmcnt(0)
	s_barrier
	s_setprio 1
	s_waitcnt lgkmcnt(0)
	v_mfma_f32_16x16x32_bf16 v[128:131], v[148:151], v[196:199], v[128:131]
	v_mfma_f32_16x16x32_bf16 v[128:131], v[154:157], v[200:203], v[128:131]
	v_mfma_f32_16x16x32_bf16 v[124:127], v[158:161], v[196:199], v[124:127]
	v_mfma_f32_16x16x32_bf16 v[124:127], v[162:165], v[200:203], v[124:127]
	v_mfma_f32_16x16x32_bf16 v[112:115], v[148:151], v[222:225], v[112:115]
	v_mfma_f32_16x16x32_bf16 v[112:115], v[154:157], v[226:229], v[112:115]
	v_mfma_f32_16x16x32_bf16 v[108:111], v[158:161], v[222:225], v[108:111]
	v_mfma_f32_16x16x32_bf16 v[108:111], v[162:165], v[226:229], v[108:111]
	v_mfma_f32_16x16x32_bf16 v[94:97], v[148:151], v[230:233], v[94:97]
	v_mfma_f32_16x16x32_bf16 v[94:97], v[154:157], v[234:237], v[94:97]
	v_mfma_f32_16x16x32_bf16 v[90:93], v[158:161], v[230:233], v[90:93]
	v_mfma_f32_16x16x32_bf16 v[90:93], v[162:165], v[234:237], v[90:93]
	v_mfma_f32_16x16x32_bf16 v[78:81], v[148:151], v[238:241], v[78:81]
	v_mfma_f32_16x16x32_bf16 v[78:81], v[154:157], v[242:245], v[78:81]
	v_mfma_f32_16x16x32_bf16 v[74:77], v[158:161], v[238:241], v[74:77]
	v_mfma_f32_16x16x32_bf16 v[74:77], v[162:165], v[242:245], v[74:77]
	s_setprio 0
	s_setprio 1
	v_mfma_f32_16x16x32_bf16 v[120:123], v[180:183], v[196:199], v[120:123]
	v_mfma_f32_16x16x32_bf16 v[120:123], v[184:187], v[200:203], v[120:123]
	v_mfma_f32_16x16x32_bf16 v[116:119], v[188:191], v[196:199], v[116:119]
	v_mfma_f32_16x16x32_bf16 v[116:119], v[192:195], v[200:203], v[116:119]
	v_mfma_f32_16x16x32_bf16 v[104:107], v[180:183], v[222:225], v[104:107]
	v_mfma_f32_16x16x32_bf16 v[104:107], v[184:187], v[226:229], v[104:107]
	v_mfma_f32_16x16x32_bf16 v[100:103], v[188:191], v[222:225], v[100:103]
	v_mfma_f32_16x16x32_bf16 v[100:103], v[192:195], v[226:229], v[100:103]
	v_mfma_f32_16x16x32_bf16 v[86:89], v[180:183], v[230:233], v[86:89]
	v_mfma_f32_16x16x32_bf16 v[86:89], v[184:187], v[234:237], v[86:89]
	v_mfma_f32_16x16x32_bf16 v[82:85], v[188:191], v[230:233], v[82:85]
	v_mfma_f32_16x16x32_bf16 v[82:85], v[192:195], v[234:237], v[82:85]
	v_mfma_f32_16x16x32_bf16 v[70:73], v[180:183], v[238:241], v[70:73]
	v_mfma_f32_16x16x32_bf16 v[70:73], v[184:187], v[242:245], v[70:73]
	v_mfma_f32_16x16x32_bf16 v[66:69], v[188:191], v[238:241], v[66:69]
	v_mfma_f32_16x16x32_bf16 v[66:69], v[192:195], v[242:245], v[66:69]
	s_setprio 0
	s_barrier
; #define PG8_STAGE(bufoff, gbase, voff) do { _Pragma("unroll") for (int _i = 0; _i < 2; ++_i) \
;         __builtin_amdgcn_global_load_lds((const unsigned*)((const char*)(gbase) + (voff)[_i]), (PG8_LAS unsigned*)(lds + (bufoff) + ldsw + _i * 8192), 16, 0, AUX_A); } while (0)
; #define PG8_STAGEB(bufoff, gbase, voff) do { _Pragma("unroll") for (int _i = 0; _i < 2; ++_i) \
;         __builtin_amdgcn_global_load_lds((const unsigned*)((const char*)(gbase) + (voff)[_i]), (PG8_LAS unsigned*)(lds + (bufoff) + ldsw + _i * 8192), 16, 0, AUX_B); } while (0)
; template <class Epi, class Sched, bool ALIGN_EPI = false, bool SP2 = false>
; __device__ __forceinline__ void gemm_phase(PG8_LAS unsigned char* lds, const Gemm g, const Sched& S, const Epi& E) {
;     ...
;             PG8_LDA(At, 1, 1); PG8_STAGEB(PG8_SB(1, 0), b3, voffB); PG8_STAGEB(PG8_SB(1, 1), b3 + hstep, voffB); PG8_STAGE(PG8_SA(1, 0), a3, voffA);
;             PG8_WAIT_V(8); PG8_WAIT_L(0); PG8_BAR; PG8_MMA(1, 0, At, B0); PG8_MMA(1, 1, At, B1); PG8_BAR; PG8_SCHED;
;             } else {
;             PG8_LDB(B0, 0, 0); PG8_SCHED; PG8_LDA(At, 0, 0); PG8_STAGE(PG8_SA(1, 1), a1 + hstep, voffA);
;             PG8_WAIT_L(8); PG8_BAR; PG8_WAIT_L(0); PG8_MMA(0, 0, At, B0); PG8_BAR; PG8_SCHED;
;             PG8_LDB(B1, 0, 1); PG8_STAGEB(PG8_SB(0, 0), b2, voffB);
;             PG8_BAR; PG8_WAIT_L(0); PG8_MMA(0, 1, At, B1); PG8_BAR;
;             PG8_LDA(At, 0, 1); PG8_STAGE(PG8_SA(0, 0), a2, voffA);
;             PG8_BAR; PG8_WAIT_L(0); PG8_MMA(1, 0, At, B0); PG8_BAR; PG8_SCHED;
;             PG8_STAGEB(PG8_SB(0, 1), b2 + hstep, voffB);
;             PG8_WAIT_V(6); PG8_BAR; PG8_MMA(1, 1, At, B1); PG8_BAR;
;             PG8_LDB(B0, 1, 0); PG8_SCHED; PG8_LDA(At, 1, 0); PG8_STAGE(PG8_SA(0, 1), a2 + hstep, voffA);
;             PG8_WAIT_L(8); PG8_BAR; PG8_WAIT_L(0); PG8_MMA(0, 0, At, B0); PG8_BAR; PG8_SCHED;
;             PG8_LDB(B1, 1, 1); PG8_STAGEB(PG8_SB(1, 0), b3, voffB);
;             PG8_BAR; PG8_WAIT_L(0); PG8_MMA(0, 1, At, B1); PG8_BAR;
;             PG8_LDA(At, 1, 1); PG8_STAGE(PG8_SA(1, 0), a3, voffA);
;             PG8_BAR; PG8_WAIT_L(0); PG8_MMA(1, 0, At, B0); PG8_BAR; PG8_SCHED;
;             PG8_STAGEB(PG8_SB(1, 1), b3 + hstep, voffB);
;             PG8_WAIT_V(6); PG8_BAR; PG8_MMA(1, 1, At, B1); PG8_BAR;
;             }
;         }
;         if constexpr (ALIGN_EPI) { if (wr == 0) PG8_BAR; }
	s_mov_b32 m0, s1
	v_lshl_add_u64 v[166:167], v[166:167], 0, s[76:77]
	ds_read_b128 v[196:199], v153 offset:49152
	ds_read_b128 v[200:203], v153 offset:50176
	ds_read_b128 v[222:225], v153 offset:51200
	ds_read_b128 v[226:229], v153 offset:52224
	ds_read_b128 v[230:233], v153 offset:53248
	ds_read_b128 v[234:237], v153 offset:54272
	ds_read_b128 v[238:241], v153 offset:55296
	ds_read_b128 v[242:245], v153 offset:56320
	global_load_lds_dwordx4 v[166:167], off
	v_lshl_add_u64 v[166:167], v[168:169], 0, s[76:77]
	s_mov_b32 m0, s0
	s_nop 0
	global_load_lds_dwordx4 v[166:167], off
	v_lshl_add_u64 v[166:167], s[54:55], 0, v[136:137]
	s_mov_b32 m0, s47
	s_nop 0
	global_load_lds_dwordx4 v[166:167], off
	v_lshl_add_u64 v[166:167], s[54:55], 0, v[132:133]
	s_mov_b32 m0, s46
	s_nop 0
	global_load_lds_dwordx4 v[166:167], off
	v_lshl_add_u64 v[166:167], v[172:173], 0, s[76:77]
	s_mov_b32 m0, s83
	s_nop 0
	global_load_lds_dwordx4 v[166:167], off
	v_lshl_add_u64 v[166:167], v[212:213], 0, s[76:77]
	s_mov_b32 m0, s88
	s_nop 0
	global_load_lds_dwordx4 v[166:167], off
	s_waitcnt vmcnt(8)
	s_waitcnt lgkmcnt(0)
	s_barrier
	s_setprio 1
	s_waitcnt lgkmcnt(0)
	v_mfma_f32_16x16x32_bf16 v[62:65], v[148:151], v[196:199], v[62:65]
	v_mfma_f32_16x16x32_bf16 v[62:65], v[154:157], v[200:203], v[62:65]
	v_mfma_f32_16x16x32_bf16 v[58:61], v[158:161], v[196:199], v[58:61]
	v_mfma_f32_16x16x32_bf16 v[58:61], v[162:165], v[200:203], v[58:61]
	v_mfma_f32_16x16x32_bf16 v[46:49], v[148:151], v[222:225], v[46:49]
	v_mfma_f32_16x16x32_bf16 v[46:49], v[154:157], v[226:229], v[46:49]
	v_mfma_f32_16x16x32_bf16 v[42:45], v[158:161], v[222:225], v[42:45]
	v_mfma_f32_16x16x32_bf16 v[42:45], v[162:165], v[226:229], v[42:45]
	v_mfma_f32_16x16x32_bf16 v[30:33], v[148:151], v[230:233], v[30:33]
	v_mfma_f32_16x16x32_bf16 v[30:33], v[154:157], v[234:237], v[30:33]
	v_mfma_f32_16x16x32_bf16 v[26:29], v[158:161], v[230:233], v[26:29]
	v_mfma_f32_16x16x32_bf16 v[26:29], v[162:165], v[234:237], v[26:29]
	v_mfma_f32_16x16x32_bf16 v[14:17], v[148:151], v[238:241], v[14:17]
	v_mfma_f32_16x16x32_bf16 v[14:17], v[154:157], v[242:245], v[14:17]
	v_mfma_f32_16x16x32_bf16 v[10:13], v[158:161], v[238:241], v[10:13]
	v_mfma_f32_16x16x32_bf16 v[10:13], v[162:165], v[242:245], v[10:13]
	s_setprio 0
	s_setprio 1
	v_mfma_f32_16x16x32_bf16 v[54:57], v[180:183], v[196:199], v[54:57]
	v_mfma_f32_16x16x32_bf16 v[54:57], v[184:187], v[200:203], v[54:57]
	v_mfma_f32_16x16x32_bf16 v[50:53], v[188:191], v[196:199], v[50:53]
	v_mfma_f32_16x16x32_bf16 v[50:53], v[192:195], v[200:203], v[50:53]
	v_mfma_f32_16x16x32_bf16 v[38:41], v[180:183], v[222:225], v[38:41]
	v_mfma_f32_16x16x32_bf16 v[38:41], v[184:187], v[226:229], v[38:41]
	v_mfma_f32_16x16x32_bf16 v[34:37], v[188:191], v[222:225], v[34:37]
	v_mfma_f32_16x16x32_bf16 v[34:37], v[192:195], v[226:229], v[34:37]
	v_mfma_f32_16x16x32_bf16 v[22:25], v[180:183], v[230:233], v[22:25]
	v_mfma_f32_16x16x32_bf16 v[22:25], v[184:187], v[234:237], v[22:25]
	v_mfma_f32_16x16x32_bf16 v[18:21], v[188:191], v[230:233], v[18:21]
	v_mfma_f32_16x16x32_bf16 v[18:21], v[192:195], v[234:237], v[18:21]
	v_mfma_f32_16x16x32_bf16 v[6:9], v[180:183], v[238:241], v[6:9]
	v_mfma_f32_16x16x32_bf16 v[6:9], v[184:187], v[242:245], v[6:9]
	v_mfma_f32_16x16x32_bf16 v[2:5], v[188:191], v[238:241], v[2:5]
	v_mfma_f32_16x16x32_bf16 v[2:5], v[192:195], v[242:245], v[2:5]
	s_setprio 0
	s_barrier
	v_lshl_add_u64 v[144:145], v[144:145], 0, s[86:87]
	v_lshl_add_u64 v[146:147], v[146:147], 0, s[86:87]
	s_mov_b32 s29, s81
	s_cbranch_scc0 .LBB0_1157
	s_and_b64 vcc, exec, s[16:17]
	s_cbranch_vccz .LBB0_1160
	s_barrier

; #define PG8_STAGE(bufoff, gbase, voff) do { _Pragma("unroll") for (int _i = 0; _i < 2; ++_i) \
;         __builtin_amdgcn_global_load_lds((const unsigned*)((const char*)(gbase) + (voff)[_i]), (PG8_LAS unsigned*)(lds + (bufoff) + ldsw + _i * 8192), 16, 0, AUX_A); } while (0)
; #define PG8_STAGEB(bufoff, gbase, voff) do { _Pragma("unroll") for (int _i = 0; _i < 2; ++_i) \
;         __builtin_amdgcn_global_load_lds((const unsigned*)((const char*)(gbase) + (voff)[_i]), (PG8_LAS unsigned*)(lds + (bufoff) + ldsw + _i * 8192), 16, 0, AUX_B); } while (0)
; #define PG8_LDA(dst, b, h) do { _Pragma("unroll") for (int m = 0; m < 4; ++m) _Pragma("unroll") for (int k = 0; k < 2; ++k) dst[m][k] = *(const PG8_LAS bf16x8*)(lds + PG8_SA(b, h) + aoff + m * 2048 + k * 1024); } while (0)
; #define PG8_LDB(dst, b, h) do { _Pragma("unroll") for (int n = 0; n < 2; ++n) _Pragma("unroll") for (int k = 0; k < 2; ++k) dst[n][k] = *(const PG8_LAS bf16x8*)(lds + PG8_SB(b, h) + boff + n * 2048 + k * 1024); } while (0)
; #define PG8_WAIT_V(n) asm volatile("s_waitcnt vmcnt(" #n ")" ::: "memory")
; #define PG8_WAIT_L(n) asm volatile("s_waitcnt lgkmcnt(" #n ")" ::: "memory")
; template <class Epi, class Sched, bool ALIGN_EPI = false, bool SP2 = false>
; __device__ __forceinline__ void gemm_phase(PG8_LAS unsigned char* lds, const Gemm g, const Sched& S, const Epi& E) {
;     ...
;         const char* nAr = has_next ? nA + (size_t)nxt.krot * kstep : PG8_KP(cA, 0, rot, nt); const char* nBr = has_next ? nB + (size_t)nxt.krot * kstep : PG8_KP(cB, 0, rot, nt);
;         for (int t = 0; t < nt; t += 2) {
;             const bool last = (t == nt - 2);
;             const char* a1 = PG8_KP(cA, t + 1, rot, nt);
;             const char* a2 = last ? nAr : PG8_KP(cA, t + 2, rot, nt); const char* b2 = last ? nBr : PG8_KP(cB, t + 2, rot, nt);
;             const char* a3 = a2 + kstep; const char* b3 = b2 + kstep;
;             if (last && has_next) S.a_ready(nxt);
;             if constexpr (SP2) {
;             PG8_LDB(B0, 0, 0); PG8_LDB(B1, 0, 1); PG8_SCHED; PG8_LDA(At, 0, 0); PG8_STAGE(PG8_SA(1, 1), a1 + hstep, voffA);
;             PG8_WAIT_V(8); PG8_WAIT_L(0); PG8_BAR; PG8_MMA(0, 0, At, B0); PG8_MMA(0, 1, At, B1); PG8_BAR; PG8_SCHED;
;             PG8_LDA(At, 0, 1); PG8_STAGEB(PG8_SB(0, 0), b2, voffB); PG8_STAGEB(PG8_SB(0, 1), b2 + hstep, voffB); PG8_STAGE(PG8_SA(0, 0), a2, voffA);
.LBB0_1308:
	s_or_b32 s0, s11, 1
	s_cmp_ge_i32 s0, s71
	s_cselect_b32 s2, s71, 0
	s_add_i32 s11, s11, 2
	s_cmp_ge_i32 s11, s71
	s_cselect_b32 s0, s71, 0
	s_sub_i32 s0, s13, s0
	s_ashr_i32 s1, s0, 31
	s_lshl_b64 s[0:1], s[0:1], 7
	s_add_u32 s15, s40, s0
	s_addc_u32 s29, s41, s1
	s_add_u32 s0, s34, s0
	s_addc_u32 s1, s35, s1
	s_cmp_eq_u32 s71, s13
	s_cselect_b32 s45, s43, s29
	s_cselect_b32 s44, s42, s15
	s_cselect_b32 s37, s19, s1
	s_cselect_b32 s36, s18, s0
	s_add_i32 s15, 0, 0x10000
	s_add_i32 s29, 0, 0x14000
	v_add_u32_e32 v148, s15, v99
	v_add_u32_e32 v168, s29, v99
	ds_read_b128 v[136:139], v148
	ds_read_b128 v[140:143], v148 offset:1024
	ds_read_b128 v[144:147], v148 offset:2048
	ds_read_b128 v[148:151], v148 offset:3072
	ds_read_b128 v[164:167], v168
	ds_read_b128 v[182:185], v168 offset:1024
	ds_read_b128 v[186:189], v168 offset:2048
	ds_read_b128 v[190:193], v168 offset:3072
	v_mad_i64_i32 v[168:169], s[0:1], s2, v220, v[134:135]
	s_add_i32 m0, s50, 0xc000
	ds_read_b128 v[194:197], v181
	ds_read_b128 v[198:201], v181 offset:1024
	ds_read_b128 v[222:225], v181 offset:2048
	ds_read_b128 v[226:229], v181 offset:3072
	ds_read_b128 v[230:233], v181 offset:4096
	ds_read_b128 v[234:237], v181 offset:5120
	ds_read_b128 v[238:241], v181 offset:6144
	ds_read_b128 v[242:245], v181 offset:7168
	global_load_lds_dwordx4 v[168:169], off
	v_mad_i64_i32 v[168:169], s[0:1], s2, v220, v[132:133]
	s_add_i32 m0, s50, 0xe000
	s_nop 0
	global_load_lds_dwordx4 v[168:169], off
	s_waitcnt vmcnt(8)
	s_waitcnt lgkmcnt(0)
	s_barrier
	s_setprio 1
	s_waitcnt lgkmcnt(0)
	v_mfma_f32_16x16x32_bf16 v[128:131], v[136:139], v[194:197], v[128:131]
	v_mfma_f32_16x16x32_bf16 v[128:131], v[140:143], v[198:201], v[128:131]
	v_mfma_f32_16x16x32_bf16 v[124:127], v[144:147], v[194:197], v[124:127]
	v_mfma_f32_16x16x32_bf16 v[124:127], v[148:151], v[198:201], v[124:127]
	v_mfma_f32_16x16x32_bf16 v[120:123], v[136:139], v[222:225], v[120:123]
	v_mfma_f32_16x16x32_bf16 v[120:123], v[140:143], v[226:229], v[120:123]
	v_mfma_f32_16x16x32_bf16 v[112:115], v[144:147], v[222:225], v[112:115]
	v_mfma_f32_16x16x32_bf16 v[112:115], v[148:151], v[226:229], v[112:115]
	v_mfma_f32_16x16x32_bf16 v[104:107], v[136:139], v[230:233], v[104:107]
	v_mfma_f32_16x16x32_bf16 v[104:107], v[140:143], v[234:237], v[104:107]
	v_mfma_f32_16x16x32_bf16 v[94:97], v[144:147], v[230:233], v[94:97]
	v_mfma_f32_16x16x32_bf16 v[94:97], v[148:151], v[234:237], v[94:97]
	v_mfma_f32_16x16x32_bf16 v[86:89], v[136:139], v[238:241], v[86:89]
	v_mfma_f32_16x16x32_bf16 v[86:89], v[140:143], v[242:245], v[86:89]
	v_mfma_f32_16x16x32_bf16 v[78:81], v[144:147], v[238:241], v[78:81]
	v_mfma_f32_16x16x32_bf16 v[78:81], v[148:151], v[242:245], v[78:81]
	s_setprio 0
	s_setprio 1
	v_mfma_f32_16x16x32_bf16 v[116:119], v[164:167], v[194:197], v[116:119]
	v_mfma_f32_16x16x32_bf16 v[116:119], v[182:185], v[198:201], v[116:119]
	v_mfma_f32_16x16x32_bf16 v[108:111], v[186:189], v[194:197], v[108:111]
	v_mfma_f32_16x16x32_bf16 v[108:111], v[190:193], v[198:201], v[108:111]
	v_mfma_f32_16x16x32_bf16 v[100:103], v[164:167], v[222:225], v[100:103]
	v_mfma_f32_16x16x32_bf16 v[100:103], v[182:185], v[226:229], v[100:103]
	v_mfma_f32_16x16x32_bf16 v[90:93], v[186:189], v[222:225], v[90:93]
	v_mfma_f32_16x16x32_bf16 v[90:93], v[190:193], v[226:229], v[90:93]
	v_mfma_f32_16x16x32_bf16 v[82:85], v[164:167], v[230:233], v[82:85]
	v_mfma_f32_16x16x32_bf16 v[82:85], v[182:185], v[234:237], v[82:85]
	v_mfma_f32_16x16x32_bf16 v[74:77], v[186:189], v[230:233], v[74:77]
	v_mfma_f32_16x16x32_bf16 v[74:77], v[190:193], v[234:237], v[74:77]
	v_mfma_f32_16x16x32_bf16 v[70:73], v[164:167], v[238:241], v[70:73]
	v_mfma_f32_16x16x32_bf16 v[70:73], v[182:185], v[242:245], v[70:73]
	v_mfma_f32_16x16x32_bf16 v[66:69], v[186:189], v[238:241], v[66:69]
	v_mfma_f32_16x16x32_bf16 v[66:69], v[190:193], v[242:245], v[66:69]
	s_setprio 0
	s_barrier
	s_add_i32 s0, s15, s49
	v_lshl_add_u64 v[168:169], s[36:37], 0, v[156:157]
	s_mov_b32 m0, s0
	ds_read_b128 v[194:197], v181 offset:16384
	ds_read_b128 v[198:201], v181 offset:17408
	ds_read_b128 v[222:225], v181 offset:18432
	ds_read_b128 v[226:229], v181 offset:19456
	ds_read_b128 v[230:233], v181 offset:20480
	ds_read_b128 v[234:237], v181 offset:21504
	ds_read_b128 v[238:241], v181 offset:22528
	ds_read_b128 v[242:245], v181 offset:23552
	global_load_lds_dwordx4 v[168:169], off
	s_add_i32 m0, s0, 0x2000
	s_add_u32 s0, s36, 0x80000
	v_lshl_add_u64 v[172:173], s[36:37], 0, v[152:153]
	s_addc_u32 s1, s37, 0
	s_add_i32 s2, s29, s49
	global_load_lds_dwordx4 v[172:173], off
	v_lshl_add_u64 v[202:203], s[0:1], 0, v[156:157]
	s_mov_b32 m0, s2
	v_lshl_add_u64 v[212:213], s[44:45], 0, v[154:155]
	global_load_lds_dwordx4 v[202:203], off
	v_lshl_add_u64 v[202:203], s[0:1], 0, v[152:153]
	s_add_i32 m0, s2, 0x2000
	s_nop 0
	global_load_lds_dwordx4 v[202:203], off
	v_lshl_add_u64 v[202:203], s[44:45], 0, v[158:159]
	s_mov_b32 m0, s50
	s_nop 0
	global_load_lds_dwordx4 v[202:203], off
	s_mov_b32 m0, s51
	s_nop 0
	global_load_lds_dwordx4 v[212:213], off
	s_waitcnt vmcnt(8)
	s_waitcnt lgkmcnt(0)
	s_barrier
; #define PG8_STAGE(bufoff, gbase, voff) do { _Pragma("unroll") for (int _i = 0; _i < 2; ++_i) \
;         __builtin_amdgcn_global_load_lds((const unsigned*)((const char*)(gbase) + (voff)[_i]), (PG8_LAS unsigned*)(lds + (bufoff) + ldsw + _i * 8192), 16, 0, AUX_A); } while (0)
; #define PG8_LDA(dst, b, h) do { _Pragma("unroll") for (int m = 0; m < 4; ++m) _Pragma("unroll") for (int k = 0; k < 2; ++k) dst[m][k] = *(const PG8_LAS bf16x8*)(lds + PG8_SA(b, h) + aoff + m * 2048 + k * 1024); } while (0)
; #define PG8_LDB(dst, b, h) do { _Pragma("unroll") for (int n = 0; n < 2; ++n) _Pragma("unroll") for (int k = 0; k < 2; ++k) dst[n][k] = *(const PG8_LAS bf16x8*)(lds + PG8_SB(b, h) + boff + n * 2048 + k * 1024); } while (0)
; #define PG8_MMA(ai, bj, At, Bt) do { __builtin_amdgcn_s_setprio(1); _Pragma("unroll") for (int m = 0; m < 4; ++m) _Pragma("unroll") for (int n = 0; n < 2; ++n) _Pragma("unroll") for (int k = 0; k < 2; ++k) \
;         acc[ai][bj][m][n] = __builtin_amdgcn_mfma_f32_16x16x32_bf16(Bt[n][k], At[m][k], acc[ai][bj][m][n], 0, 0, 0); __builtin_amdgcn_s_setprio(0); } while (0)
; #define PG8_WAIT_V(n) asm volatile("s_waitcnt vmcnt(" #n ")" ::: "memory")
; #define PG8_WAIT_L(n) asm volatile("s_waitcnt lgkmcnt(" #n ")" ::: "memory")
; #define PG8_BAR __builtin_amdgcn_s_barrier()
; #define PG8_SCHED __builtin_amdgcn_sched_barrier(0)
; template <class Epi, class Sched, bool ALIGN_EPI = false, bool SP2 = false>
; __device__ __forceinline__ void gemm_phase(PG8_LAS unsigned char* lds, const Gemm g, const Sched& S, const Epi& E) {
;     ...
;             PG8_WAIT_V(8); PG8_WAIT_L(0); PG8_BAR; PG8_MMA(1, 0, At, B0); PG8_MMA(1, 1, At, B1); PG8_BAR; PG8_SCHED;
;             PG8_LDB(B0, 1, 0); PG8_LDB(B1, 1, 1); PG8_SCHED; PG8_LDA(At, 1, 0); PG8_STAGE(PG8_SA(0, 1), a2 + hstep, voffA);
;             PG8_WAIT_V(8); PG8_WAIT_L(0); PG8_BAR; PG8_MMA(0, 0, At, B0); PG8_MMA(0, 1, At, B1); PG8_BAR; PG8_SCHED;
	s_setprio 1
	s_waitcnt lgkmcnt(0)
	v_mfma_f32_16x16x32_bf16 v[62:65], v[136:139], v[194:197], v[62:65]
	v_mfma_f32_16x16x32_bf16 v[62:65], v[140:143], v[198:201], v[62:65]
	v_mfma_f32_16x16x32_bf16 v[58:61], v[144:147], v[194:197], v[58:61]
	v_mfma_f32_16x16x32_bf16 v[58:61], v[148:151], v[198:201], v[58:61]
	v_mfma_f32_16x16x32_bf16 v[54:57], v[136:139], v[222:225], v[54:57]
	v_mfma_f32_16x16x32_bf16 v[54:57], v[140:143], v[226:229], v[54:57]
	v_mfma_f32_16x16x32_bf16 v[46:49], v[144:147], v[222:225], v[46:49]
	v_mfma_f32_16x16x32_bf16 v[46:49], v[148:151], v[226:229], v[46:49]
	v_mfma_f32_16x16x32_bf16 v[38:41], v[136:139], v[230:233], v[38:41]
	v_mfma_f32_16x16x32_bf16 v[38:41], v[140:143], v[234:237], v[38:41]
	v_mfma_f32_16x16x32_bf16 v[30:33], v[144:147], v[230:233], v[30:33]
	v_mfma_f32_16x16x32_bf16 v[30:33], v[148:151], v[234:237], v[30:33]
	v_mfma_f32_16x16x32_bf16 v[22:25], v[136:139], v[238:241], v[22:25]
	v_mfma_f32_16x16x32_bf16 v[22:25], v[140:143], v[242:245], v[22:25]
	v_mfma_f32_16x16x32_bf16 v[14:17], v[144:147], v[238:241], v[14:17]
	v_mfma_f32_16x16x32_bf16 v[14:17], v[148:151], v[242:245], v[14:17]
	s_setprio 0
	s_setprio 1
	v_mfma_f32_16x16x32_bf16 v[50:53], v[164:167], v[194:197], v[50:53]
	v_mfma_f32_16x16x32_bf16 v[50:53], v[182:185], v[198:201], v[50:53]
	v_mfma_f32_16x16x32_bf16 v[42:45], v[186:189], v[194:197], v[42:45]
	v_mfma_f32_16x16x32_bf16 v[42:45], v[190:193], v[198:201], v[42:45]
	v_mfma_f32_16x16x32_bf16 v[34:37], v[164:167], v[222:225], v[34:37]
	v_mfma_f32_16x16x32_bf16 v[34:37], v[182:185], v[226:229], v[34:37]
	v_mfma_f32_16x16x32_bf16 v[26:29], v[186:189], v[222:225], v[26:29]
	v_mfma_f32_16x16x32_bf16 v[26:29], v[190:193], v[226:229], v[26:29]
	v_mfma_f32_16x16x32_bf16 v[18:21], v[164:167], v[230:233], v[18:21]
	v_mfma_f32_16x16x32_bf16 v[18:21], v[182:185], v[234:237], v[18:21]
	v_mfma_f32_16x16x32_bf16 v[10:13], v[186:189], v[230:233], v[10:13]
	v_mfma_f32_16x16x32_bf16 v[10:13], v[190:193], v[234:237], v[10:13]
	v_mfma_f32_16x16x32_bf16 v[6:9], v[164:167], v[238:241], v[6:9]
	v_mfma_f32_16x16x32_bf16 v[6:9], v[182:185], v[242:245], v[6:9]
	v_mfma_f32_16x16x32_bf16 v[2:5], v[186:189], v[238:241], v[2:5]
	v_mfma_f32_16x16x32_bf16 v[2:5], v[190:193], v[242:245], v[2:5]
	s_setprio 0
	s_barrier
	s_add_i32 s2, 0, 0x18000
	s_add_i32 s15, 0, 0x1c000
	v_add_u32_e32 v148, s2, v99
	v_add_u32_e32 v190, s15, v99
	ds_read_b128 v[136:139], v148
	ds_read_b128 v[140:143], v148 offset:1024
	ds_read_b128 v[144:147], v148 offset:2048
	ds_read_b128 v[148:151], v148 offset:3072
	ds_read_b128 v[164:167], v190
	ds_read_b128 v[182:185], v190 offset:1024
	ds_read_b128 v[186:189], v190 offset:2048
	ds_read_b128 v[190:193], v190 offset:3072
	s_add_u32 s0, s44, 0x80000
	s_addc_u32 s1, s45, 0
	s_mov_b32 m0, s52
	v_lshl_add_u64 v[246:247], s[0:1], 0, v[158:159]
	ds_read_b128 v[194:197], v181 offset:32768
	ds_read_b128 v[198:201], v181 offset:33792
	ds_read_b128 v[222:225], v181 offset:34816
	ds_read_b128 v[226:229], v181 offset:35840
	ds_read_b128 v[230:233], v181 offset:36864
	ds_read_b128 v[234:237], v181 offset:37888
	ds_read_b128 v[238:241], v181 offset:38912
	ds_read_b128 v[242:245], v181 offset:39936
	global_load_lds_dwordx4 v[246:247], off
	v_lshl_add_u64 v[246:247], s[0:1], 0, v[154:155]
	s_mov_b32 m0, s53
	s_nop 0
	global_load_lds_dwordx4 v[246:247], off
	s_waitcnt vmcnt(8)
	s_waitcnt lgkmcnt(0)
	s_barrier
	s_setprio 1
	s_waitcnt lgkmcnt(0)
	v_mfma_f32_16x16x32_bf16 v[128:131], v[136:139], v[194:197], v[128:131]
	v_mfma_f32_16x16x32_bf16 v[128:131], v[140:143], v[198:201], v[128:131]
	v_mfma_f32_16x16x32_bf16 v[124:127], v[144:147], v[194:197], v[124:127]
	v_mfma_f32_16x16x32_bf16 v[124:127], v[148:151], v[198:201], v[124:127]
	v_mfma_f32_16x16x32_bf16 v[120:123], v[136:139], v[222:225], v[120:123]
	v_mfma_f32_16x16x32_bf16 v[120:123], v[140:143], v[226:229], v[120:123]
	v_mfma_f32_16x16x32_bf16 v[112:115], v[144:147], v[222:225], v[112:115]
	v_mfma_f32_16x16x32_bf16 v[112:115], v[148:151], v[226:229], v[112:115]
	v_mfma_f32_16x16x32_bf16 v[104:107], v[136:139], v[230:233], v[104:107]
	v_mfma_f32_16x16x32_bf16 v[104:107], v[140:143], v[234:237], v[104:107]
	v_mfma_f32_16x16x32_bf16 v[94:97], v[144:147], v[230:233], v[94:97]
	v_mfma_f32_16x16x32_bf16 v[94:97], v[148:151], v[234:237], v[94:97]
	v_mfma_f32_16x16x32_bf16 v[86:89], v[136:139], v[238:241], v[86:89]
	v_mfma_f32_16x16x32_bf16 v[86:89], v[140:143], v[242:245], v[86:89]
	v_mfma_f32_16x16x32_bf16 v[78:81], v[144:147], v[238:241], v[78:81]
	v_mfma_f32_16x16x32_bf16 v[78:81], v[148:151], v[242:245], v[78:81]
	s_setprio 0
	s_setprio 1
	v_mfma_f32_16x16x32_bf16 v[116:119], v[164:167], v[194:197], v[116:119]
	v_mfma_f32_16x16x32_bf16 v[116:119], v[182:185], v[198:201], v[116:119]
	v_mfma_f32_16x16x32_bf16 v[108:111], v[186:189], v[194:197], v[108:111]
	v_mfma_f32_16x16x32_bf16 v[108:111], v[190:193], v[198:201], v[108:111]
	v_mfma_f32_16x16x32_bf16 v[100:103], v[164:167], v[222:225], v[100:103]
	v_mfma_f32_16x16x32_bf16 v[100:103], v[182:185], v[226:229], v[100:103]
	v_mfma_f32_16x16x32_bf16 v[90:93], v[186:189], v[222:225], v[90:93]
	v_mfma_f32_16x16x32_bf16 v[90:93], v[190:193], v[226:229], v[90:93]
	v_mfma_f32_16x16x32_bf16 v[82:85], v[164:167], v[230:233], v[82:85]
	v_mfma_f32_16x16x32_bf16 v[82:85], v[182:185], v[234:237], v[82:85]
	v_mfma_f32_16x16x32_bf16 v[74:77], v[186:189], v[230:233], v[74:77]
	v_mfma_f32_16x16x32_bf16 v[74:77], v[190:193], v[234:237], v[74:77]
	v_mfma_f32_16x16x32_bf16 v[70:73], v[164:167], v[238:241], v[70:73]
	v_mfma_f32_16x16x32_bf16 v[70:73], v[182:185], v[242:245], v[70:73]
	v_mfma_f32_16x16x32_bf16 v[66:69], v[186:189], v[238:241], v[66:69]
	v_mfma_f32_16x16x32_bf16 v[66:69], v[190:193], v[242:245], v[66:69]
	s_setprio 0
	s_barrier
; #define PG8_STAGE(bufoff, gbase, voff) do { _Pragma("unroll") for (int _i = 0; _i < 2; ++_i) \
;         __builtin_amdgcn_global_load_lds((const unsigned*)((const char*)(gbase) + (voff)[_i]), (PG8_LAS unsigned*)(lds + (bufoff) + ldsw + _i * 8192), 16, 0, AUX_A); } while (0)
; #define PG8_STAGEB(bufoff, gbase, voff) do { _Pragma("unroll") for (int _i = 0; _i < 2; ++_i) \
;         __builtin_amdgcn_global_load_lds((const unsigned*)((const char*)(gbase) + (voff)[_i]), (PG8_LAS unsigned*)(lds + (bufoff) + ldsw + _i * 8192), 16, 0, AUX_B); } while (0)
; template <class Epi, class Sched, bool ALIGN_EPI = false, bool SP2 = false>
; __device__ __forceinline__ void gemm_phase(PG8_LAS unsigned char* lds, const Gemm g, const Sched& S, const Epi& E) {
;     ...
;             PG8_LDA(At, 1, 1); PG8_STAGEB(PG8_SB(1, 0), b3, voffB); PG8_STAGEB(PG8_SB(1, 1), b3 + hstep, voffB); PG8_STAGE(PG8_SA(1, 0), a3, voffA);
;             PG8_WAIT_V(8); PG8_WAIT_L(0); PG8_BAR; PG8_MMA(1, 0, At, B0); PG8_MMA(1, 1, At, B1); PG8_BAR; PG8_SCHED;
;             } else {
;             PG8_LDB(B0, 0, 0); PG8_SCHED; PG8_LDA(At, 0, 0); PG8_STAGE(PG8_SA(1, 1), a1 + hstep, voffA);
;             PG8_WAIT_L(8); PG8_BAR; PG8_WAIT_L(0); PG8_MMA(0, 0, At, B0); PG8_BAR; PG8_SCHED;
;             PG8_LDB(B1, 0, 1); PG8_STAGEB(PG8_SB(0, 0), b2, voffB);
;             PG8_BAR; PG8_WAIT_L(0); PG8_MMA(0, 1, At, B1); PG8_BAR;
;             PG8_LDA(At, 0, 1); PG8_STAGE(PG8_SA(0, 0), a2, voffA);
;             PG8_BAR; PG8_WAIT_L(0); PG8_MMA(1, 0, At, B0); PG8_BAR; PG8_SCHED;
;             PG8_STAGEB(PG8_SB(0, 1), b2 + hstep, voffB);
;             PG8_WAIT_V(6); PG8_BAR; PG8_MMA(1, 1, At, B1); PG8_BAR;
;             PG8_LDB(B0, 1, 0); PG8_SCHED; PG8_LDA(At, 1, 0); PG8_STAGE(PG8_SA(0, 1), a2 + hstep, voffA);
;             PG8_WAIT_L(8); PG8_BAR; PG8_WAIT_L(0); PG8_MMA(0, 0, At, B0); PG8_BAR; PG8_SCHED;
;             PG8_LDB(B1, 1, 1); PG8_STAGEB(PG8_SB(1, 0), b3, voffB);
;             PG8_BAR; PG8_WAIT_L(0); PG8_MMA(0, 1, At, B1); PG8_BAR;
;             PG8_LDA(At, 1, 1); PG8_STAGE(PG8_SA(1, 0), a3, voffA);
;             PG8_BAR; PG8_WAIT_L(0); PG8_MMA(1, 0, At, B0); PG8_BAR; PG8_SCHED;
;             PG8_STAGEB(PG8_SB(1, 1), b3 + hstep, voffB);
;             PG8_WAIT_V(6); PG8_BAR; PG8_MMA(1, 1, At, B1); PG8_BAR;
;             }
;         }
;         if constexpr (ALIGN_EPI) { if (wr == 0) PG8_BAR; }
	s_add_i32 s0, s2, s49
	v_lshl_add_u64 v[168:169], v[168:169], 0, s[76:77]
	s_mov_b32 m0, s0
	ds_read_b128 v[194:197], v181 offset:49152
	ds_read_b128 v[198:201], v181 offset:50176
	ds_read_b128 v[222:225], v181 offset:51200
	ds_read_b128 v[226:229], v181 offset:52224
	ds_read_b128 v[230:233], v181 offset:53248
	ds_read_b128 v[234:237], v181 offset:54272
	ds_read_b128 v[238:241], v181 offset:55296
	ds_read_b128 v[242:245], v181 offset:56320
	global_load_lds_dwordx4 v[168:169], off
	s_add_i32 m0, s0, 0x2000
	s_add_u32 s0, s36, 0x80080
	v_lshl_add_u64 v[168:169], v[172:173], 0, s[76:77]
	s_addc_u32 s1, s37, 0
	s_add_i32 s2, s15, s49
	global_load_lds_dwordx4 v[168:169], off
	v_lshl_add_u64 v[168:169], s[0:1], 0, v[156:157]
	s_mov_b32 m0, s2
	s_nop 0
	global_load_lds_dwordx4 v[168:169], off
	v_lshl_add_u64 v[168:169], s[0:1], 0, v[152:153]
	s_add_i32 m0, s2, 0x2000
	s_nop 0
	global_load_lds_dwordx4 v[168:169], off
	v_lshl_add_u64 v[168:169], v[202:203], 0, s[76:77]
	s_mov_b32 m0, s59
	s_nop 0
	global_load_lds_dwordx4 v[168:169], off
	v_lshl_add_u64 v[168:169], v[212:213], 0, s[76:77]
	s_mov_b32 m0, s60
	s_nop 0
	global_load_lds_dwordx4 v[168:169], off
	s_waitcnt vmcnt(8)
	s_waitcnt lgkmcnt(0)
	s_barrier
	s_setprio 1
	s_waitcnt lgkmcnt(0)
	v_mfma_f32_16x16x32_bf16 v[62:65], v[136:139], v[194:197], v[62:65]
	v_mfma_f32_16x16x32_bf16 v[62:65], v[140:143], v[198:201], v[62:65]
	v_mfma_f32_16x16x32_bf16 v[58:61], v[144:147], v[194:197], v[58:61]
	v_mfma_f32_16x16x32_bf16 v[58:61], v[148:151], v[198:201], v[58:61]
	v_mfma_f32_16x16x32_bf16 v[54:57], v[136:139], v[222:225], v[54:57]
	v_mfma_f32_16x16x32_bf16 v[54:57], v[140:143], v[226:229], v[54:57]
	v_mfma_f32_16x16x32_bf16 v[46:49], v[144:147], v[222:225], v[46:49]
	v_mfma_f32_16x16x32_bf16 v[46:49], v[148:151], v[226:229], v[46:49]
	v_mfma_f32_16x16x32_bf16 v[38:41], v[136:139], v[230:233], v[38:41]
	v_mfma_f32_16x16x32_bf16 v[38:41], v[140:143], v[234:237], v[38:41]
	v_mfma_f32_16x16x32_bf16 v[30:33], v[144:147], v[230:233], v[30:33]
	v_mfma_f32_16x16x32_bf16 v[30:33], v[148:151], v[234:237], v[30:33]
	v_mfma_f32_16x16x32_bf16 v[22:25], v[136:139], v[238:241], v[22:25]
	v_mfma_f32_16x16x32_bf16 v[22:25], v[140:143], v[242:245], v[22:25]
	v_mfma_f32_16x16x32_bf16 v[14:17], v[144:147], v[238:241], v[14:17]
	v_mfma_f32_16x16x32_bf16 v[14:17], v[148:151], v[242:245], v[14:17]
	s_setprio 0
	s_setprio 1
	v_mfma_f32_16x16x32_bf16 v[50:53], v[164:167], v[194:197], v[50:53]
	v_mfma_f32_16x16x32_bf16 v[50:53], v[182:185], v[198:201], v[50:53]
	v_mfma_f32_16x16x32_bf16 v[42:45], v[186:189], v[194:197], v[42:45]
	v_mfma_f32_16x16x32_bf16 v[42:45], v[190:193], v[198:201], v[42:45]
	v_mfma_f32_16x16x32_bf16 v[34:37], v[164:167], v[222:225], v[34:37]
	v_mfma_f32_16x16x32_bf16 v[34:37], v[182:185], v[226:229], v[34:37]
	v_mfma_f32_16x16x32_bf16 v[26:29], v[186:189], v[222:225], v[26:29]
	v_mfma_f32_16x16x32_bf16 v[26:29], v[190:193], v[226:229], v[26:29]
	v_mfma_f32_16x16x32_bf16 v[18:21], v[164:167], v[230:233], v[18:21]
	v_mfma_f32_16x16x32_bf16 v[18:21], v[182:185], v[234:237], v[18:21]
	v_mfma_f32_16x16x32_bf16 v[10:13], v[186:189], v[230:233], v[10:13]
	v_mfma_f32_16x16x32_bf16 v[10:13], v[190:193], v[234:237], v[10:13]
	v_mfma_f32_16x16x32_bf16 v[6:9], v[164:167], v[238:241], v[6:9]
	v_mfma_f32_16x16x32_bf16 v[6:9], v[182:185], v[242:245], v[6:9]
	v_mfma_f32_16x16x32_bf16 v[2:5], v[186:189], v[238:241], v[2:5]
	v_mfma_f32_16x16x32_bf16 v[2:5], v[190:193], v[242:245], v[2:5]
	s_setprio 0
	s_barrier
	s_add_i32 s0, s13, 2
	v_lshl_add_u64 v[132:133], v[132:133], 0, s[86:87]
	v_lshl_add_u64 v[134:135], v[134:135], 0, s[86:87]
	s_cmp_ge_i32 s13, s71
	s_mov_b32 s13, s0
	s_cbranch_scc0 .LBB0_1308
	s_and_b64 vcc, exec, s[8:9]
	s_cbranch_vccz .LBB0_1311
	s_barrier

; #define PG8_STAGE(bufoff, gbase, voff) do { _Pragma("unroll") for (int _i = 0; _i < 2; ++_i) \
;         __builtin_amdgcn_global_load_lds((const unsigned*)((const char*)(gbase) + (voff)[_i]), (PG8_LAS unsigned*)(lds + (bufoff) + ldsw + _i * 8192), 16, 0, AUX_A); } while (0)
; #define PG8_STAGEB(bufoff, gbase, voff) do { _Pragma("unroll") for (int _i = 0; _i < 2; ++_i) \
;         __builtin_amdgcn_global_load_lds((const unsigned*)((const char*)(gbase) + (voff)[_i]), (PG8_LAS unsigned*)(lds + (bufoff) + ldsw + _i * 8192), 16, 0, AUX_B); } while (0)
; #define PG8_LDA(dst, b, h) do { _Pragma("unroll") for (int m = 0; m < 4; ++m) _Pragma("unroll") for (int k = 0; k < 2; ++k) dst[m][k] = *(const PG8_LAS bf16x8*)(lds + PG8_SA(b, h) + aoff + m * 2048 + k * 1024); } while (0)
; #define PG8_LDB(dst, b, h) do { _Pragma("unroll") for (int n = 0; n < 2; ++n) _Pragma("unroll") for (int k = 0; k < 2; ++k) dst[n][k] = *(const PG8_LAS bf16x8*)(lds + PG8_SB(b, h) + boff + n * 2048 + k * 1024); } while (0)
; #define PG8_WAIT_V(n) asm volatile("s_waitcnt vmcnt(" #n ")" ::: "memory")
; #define PG8_WAIT_L(n) asm volatile("s_waitcnt lgkmcnt(" #n ")" ::: "memory")
; template <class Epi, class Sched, bool ALIGN_EPI = false, bool SP2 = false>
; __device__ __forceinline__ void gemm_phase(PG8_LAS unsigned char* lds, const Gemm g, const Sched& S, const Epi& E) {
;     ...
;         const char* nAr = has_next ? nA + (size_t)nxt.krot * kstep : PG8_KP(cA, 0, rot, nt); const char* nBr = has_next ? nB + (size_t)nxt.krot * kstep : PG8_KP(cB, 0, rot, nt);
;         for (int t = 0; t < nt; t += 2) {
;             const bool last = (t == nt - 2);
;             const char* a1 = PG8_KP(cA, t + 1, rot, nt);
;             const char* a2 = last ? nAr : PG8_KP(cA, t + 2, rot, nt); const char* b2 = last ? nBr : PG8_KP(cB, t + 2, rot, nt);
;             const char* a3 = a2 + kstep; const char* b3 = b2 + kstep;
;             if (last && has_next) S.a_ready(nxt);
;             if constexpr (SP2) {
;             PG8_LDB(B0, 0, 0); PG8_LDB(B1, 0, 1); PG8_SCHED; PG8_LDA(At, 0, 0); PG8_STAGE(PG8_SA(1, 1), a1 + hstep, voffA);
;             PG8_WAIT_V(8); PG8_WAIT_L(0); PG8_BAR; PG8_MMA(0, 0, At, B0); PG8_MMA(0, 1, At, B1); PG8_BAR; PG8_SCHED;
;             PG8_LDA(At, 0, 1); PG8_STAGEB(PG8_SB(0, 0), b2, voffB); PG8_STAGEB(PG8_SB(0, 1), b2 + hstep, voffB); PG8_STAGE(PG8_SA(0, 0), a2, voffA);
.LBB0_1458:
	s_add_i32 s30, s29, 2
	s_cmp_lt_u32 s29, 30
	s_cselect_b32 s0, 0, 0xffffffe0
	s_add_i32 s0, s30, s0
	s_ashr_i32 s1, s0, 31
	s_lshl_b64 s[0:1], s[0:1], 7
	s_add_u32 s2, s40, s0
	s_addc_u32 s31, s41, s1
	s_add_u32 s0, s34, s0
	s_addc_u32 s1, s35, s1
	s_cmp_eq_u32 s29, 30
	s_cselect_b32 s45, s13, s31
	s_cselect_b32 s44, s15, s2
	s_cselect_b32 s49, s71, s1
	s_cselect_b32 s48, s75, s0
	s_add_i32 s2, 0, 0x10000
	s_add_i32 s78, s2, s56
	s_add_i32 s31, 0, 0x14000
	s_add_i32 m0, s57, 0xc000
	s_add_i32 s47, s57, 0xe000
	s_add_i32 s81, s78, 0x2000
	s_add_u32 s50, s48, 0x80000
	s_addc_u32 s51, s49, 0
	s_add_i32 s82, s31, s56
	v_add_u32_e32 v162, s2, v99
	v_add_u32_e32 v166, s31, v99
	s_add_i32 s83, s82, 0x2000
	s_add_i32 s84, 0, 0x18000
	s_add_i32 s88, 0, 0x1c000
	ds_read_b128 v[150:153], v162
	ds_read_b128 v[154:157], v162 offset:1024
	ds_read_b128 v[158:161], v162 offset:2048
	ds_read_b128 v[162:165], v162 offset:3072
	ds_read_b128 v[180:183], v166
	ds_read_b128 v[184:187], v166 offset:1024
	ds_read_b128 v[188:191], v166 offset:2048
	ds_read_b128 v[192:195], v166 offset:3072
	s_add_u32 s42, s44, 0x80000
	s_addc_u32 s43, s45, 0
	s_add_i32 s1, s84, s56
	s_add_i32 s0, s1, 0x2000
	s_add_u32 s36, s48, 0x80080
	s_addc_u32 s37, s49, 0
	s_add_i32 s46, s88, s56
	s_add_i32 s31, s46, 0x2000
	s_cmp_gt_u32 s29, 29
	ds_read_b128 v[196:199], v149
	ds_read_b128 v[200:203], v149 offset:1024
	ds_read_b128 v[222:225], v149 offset:2048
	ds_read_b128 v[226:229], v149 offset:3072
	ds_read_b128 v[230:233], v149 offset:4096
	ds_read_b128 v[234:237], v149 offset:5120
	ds_read_b128 v[238:241], v149 offset:6144
	ds_read_b128 v[242:245], v149 offset:7168
	global_load_lds_dwordx4 v[146:147], off
	s_mov_b32 m0, s47
	s_nop 0
	global_load_lds_dwordx4 v[144:145], off
	s_waitcnt vmcnt(8)
	s_waitcnt lgkmcnt(0)
	s_barrier
	s_setprio 1
	s_waitcnt lgkmcnt(0)
	v_mfma_f32_16x16x32_bf16 v[128:131], v[150:153], v[196:199], v[128:131]
	v_mfma_f32_16x16x32_bf16 v[128:131], v[154:157], v[200:203], v[128:131]
	v_mfma_f32_16x16x32_bf16 v[120:123], v[158:161], v[196:199], v[120:123]
	v_mfma_f32_16x16x32_bf16 v[120:123], v[162:165], v[200:203], v[120:123]
	v_mfma_f32_16x16x32_bf16 v[112:115], v[150:153], v[222:225], v[112:115]
	v_mfma_f32_16x16x32_bf16 v[112:115], v[154:157], v[226:229], v[112:115]
	v_mfma_f32_16x16x32_bf16 v[104:107], v[158:161], v[222:225], v[104:107]
	v_mfma_f32_16x16x32_bf16 v[104:107], v[162:165], v[226:229], v[104:107]
	v_mfma_f32_16x16x32_bf16 v[94:97], v[150:153], v[230:233], v[94:97]
	v_mfma_f32_16x16x32_bf16 v[94:97], v[154:157], v[234:237], v[94:97]
	v_mfma_f32_16x16x32_bf16 v[86:89], v[158:161], v[230:233], v[86:89]
	v_mfma_f32_16x16x32_bf16 v[86:89], v[162:165], v[234:237], v[86:89]
	v_mfma_f32_16x16x32_bf16 v[78:81], v[150:153], v[238:241], v[78:81]
	v_mfma_f32_16x16x32_bf16 v[78:81], v[154:157], v[242:245], v[78:81]
	v_mfma_f32_16x16x32_bf16 v[70:73], v[158:161], v[238:241], v[70:73]
	v_mfma_f32_16x16x32_bf16 v[70:73], v[162:165], v[242:245], v[70:73]
	s_setprio 0
	s_setprio 1
	v_mfma_f32_16x16x32_bf16 v[124:127], v[180:183], v[196:199], v[124:127]
	v_mfma_f32_16x16x32_bf16 v[124:127], v[184:187], v[200:203], v[124:127]
	v_mfma_f32_16x16x32_bf16 v[116:119], v[188:191], v[196:199], v[116:119]
	v_mfma_f32_16x16x32_bf16 v[116:119], v[192:195], v[200:203], v[116:119]
	v_mfma_f32_16x16x32_bf16 v[108:111], v[180:183], v[222:225], v[108:111]
	v_mfma_f32_16x16x32_bf16 v[108:111], v[184:187], v[226:229], v[108:111]
	v_mfma_f32_16x16x32_bf16 v[100:103], v[188:191], v[222:225], v[100:103]
	v_mfma_f32_16x16x32_bf16 v[100:103], v[192:195], v[226:229], v[100:103]
	v_mfma_f32_16x16x32_bf16 v[90:93], v[180:183], v[230:233], v[90:93]
	v_mfma_f32_16x16x32_bf16 v[90:93], v[184:187], v[234:237], v[90:93]
	v_mfma_f32_16x16x32_bf16 v[82:85], v[188:191], v[230:233], v[82:85]
	v_mfma_f32_16x16x32_bf16 v[82:85], v[192:195], v[234:237], v[82:85]
	v_mfma_f32_16x16x32_bf16 v[74:77], v[180:183], v[238:241], v[74:77]
	v_mfma_f32_16x16x32_bf16 v[74:77], v[184:187], v[242:245], v[74:77]
	v_mfma_f32_16x16x32_bf16 v[66:69], v[188:191], v[238:241], v[66:69]
	v_mfma_f32_16x16x32_bf16 v[66:69], v[192:195], v[242:245], v[66:69]
	s_setprio 0
	s_barrier
	s_mov_b32 m0, s78
	v_lshl_add_u64 v[166:167], s[48:49], 0, v[136:137]
	ds_read_b128 v[196:199], v149 offset:16384
	ds_read_b128 v[200:203], v149 offset:17408
	ds_read_b128 v[222:225], v149 offset:18432
	ds_read_b128 v[226:229], v149 offset:19456
	ds_read_b128 v[230:233], v149 offset:20480
	ds_read_b128 v[234:237], v149 offset:21504
	ds_read_b128 v[238:241], v149 offset:22528
	ds_read_b128 v[242:245], v149 offset:23552
	global_load_lds_dwordx4 v[166:167], off
	v_lshl_add_u64 v[168:169], s[48:49], 0, v[132:133]
	s_mov_b32 m0, s81
	v_lshl_add_u64 v[172:173], s[50:51], 0, v[136:137]
	global_load_lds_dwordx4 v[168:169], off
	s_mov_b32 m0, s82
	v_lshl_add_u64 v[212:213], s[44:45], 0, v[134:135]
	global_load_lds_dwordx4 v[172:173], off
	v_lshl_add_u64 v[172:173], s[50:51], 0, v[132:133]
	s_mov_b32 m0, s83
	s_nop 0
	global_load_lds_dwordx4 v[172:173], off
	v_lshl_add_u64 v[172:173], s[44:45], 0, v[138:139]
	s_mov_b32 m0, s57
	s_nop 0
	global_load_lds_dwordx4 v[172:173], off
	s_mov_b32 m0, s58
	s_nop 0
	global_load_lds_dwordx4 v[212:213], off
	s_waitcnt vmcnt(8)
	s_waitcnt lgkmcnt(0)
	s_barrier
; #define PG8_STAGE(bufoff, gbase, voff) do { _Pragma("unroll") for (int _i = 0; _i < 2; ++_i) \
;         __builtin_amdgcn_global_load_lds((const unsigned*)((const char*)(gbase) + (voff)[_i]), (PG8_LAS unsigned*)(lds + (bufoff) + ldsw + _i * 8192), 16, 0, AUX_A); } while (0)
; #define PG8_LDA(dst, b, h) do { _Pragma("unroll") for (int m = 0; m < 4; ++m) _Pragma("unroll") for (int k = 0; k < 2; ++k) dst[m][k] = *(const PG8_LAS bf16x8*)(lds + PG8_SA(b, h) + aoff + m * 2048 + k * 1024); } while (0)
; #define PG8_LDB(dst, b, h) do { _Pragma("unroll") for (int n = 0; n < 2; ++n) _Pragma("unroll") for (int k = 0; k < 2; ++k) dst[n][k] = *(const PG8_LAS bf16x8*)(lds + PG8_SB(b, h) + boff + n * 2048 + k * 1024); } while (0)
; #define PG8_MMA(ai, bj, At, Bt) do { __builtin_amdgcn_s_setprio(1); _Pragma("unroll") for (int m = 0; m < 4; ++m) _Pragma("unroll") for (int n = 0; n < 2; ++n) _Pragma("unroll") for (int k = 0; k < 2; ++k) \
;         acc[ai][bj][m][n] = __builtin_amdgcn_mfma_f32_16x16x32_bf16(Bt[n][k], At[m][k], acc[ai][bj][m][n], 0, 0, 0); __builtin_amdgcn_s_setprio(0); } while (0)
; #define PG8_WAIT_V(n) asm volatile("s_waitcnt vmcnt(" #n ")" ::: "memory")
; #define PG8_WAIT_L(n) asm volatile("s_waitcnt lgkmcnt(" #n ")" ::: "memory")
; #define PG8_BAR __builtin_amdgcn_s_barrier()
; #define PG8_SCHED __builtin_amdgcn_sched_barrier(0)
; template <class Epi, class Sched, bool ALIGN_EPI = false, bool SP2 = false>
; __device__ __forceinline__ void gemm_phase(PG8_LAS unsigned char* lds, const Gemm g, const Sched& S, const Epi& E) {
;     ...
;             PG8_WAIT_V(8); PG8_WAIT_L(0); PG8_BAR; PG8_MMA(1, 0, At, B0); PG8_MMA(1, 1, At, B1); PG8_BAR; PG8_SCHED;
;             PG8_LDB(B0, 1, 0); PG8_LDB(B1, 1, 1); PG8_SCHED; PG8_LDA(At, 1, 0); PG8_STAGE(PG8_SA(0, 1), a2 + hstep, voffA);
;             PG8_WAIT_V(8); PG8_WAIT_L(0); PG8_BAR; PG8_MMA(0, 0, At, B0); PG8_MMA(0, 1, At, B1); PG8_BAR; PG8_SCHED;
	s_setprio 1
	s_waitcnt lgkmcnt(0)
	v_mfma_f32_16x16x32_bf16 v[62:65], v[150:153], v[196:199], v[62:65]
	v_mfma_f32_16x16x32_bf16 v[62:65], v[154:157], v[200:203], v[62:65]
	v_mfma_f32_16x16x32_bf16 v[54:57], v[158:161], v[196:199], v[54:57]
	v_mfma_f32_16x16x32_bf16 v[54:57], v[162:165], v[200:203], v[54:57]
	v_mfma_f32_16x16x32_bf16 v[46:49], v[150:153], v[222:225], v[46:49]
	v_mfma_f32_16x16x32_bf16 v[46:49], v[154:157], v[226:229], v[46:49]
	v_mfma_f32_16x16x32_bf16 v[38:41], v[158:161], v[222:225], v[38:41]
	v_mfma_f32_16x16x32_bf16 v[38:41], v[162:165], v[226:229], v[38:41]
	v_mfma_f32_16x16x32_bf16 v[30:33], v[150:153], v[230:233], v[30:33]
	v_mfma_f32_16x16x32_bf16 v[30:33], v[154:157], v[234:237], v[30:33]
	v_mfma_f32_16x16x32_bf16 v[22:25], v[158:161], v[230:233], v[22:25]
	v_mfma_f32_16x16x32_bf16 v[22:25], v[162:165], v[234:237], v[22:25]
	v_mfma_f32_16x16x32_bf16 v[14:17], v[150:153], v[238:241], v[14:17]
	v_mfma_f32_16x16x32_bf16 v[14:17], v[154:157], v[242:245], v[14:17]
	v_mfma_f32_16x16x32_bf16 v[6:9], v[158:161], v[238:241], v[6:9]
	v_mfma_f32_16x16x32_bf16 v[6:9], v[162:165], v[242:245], v[6:9]
	s_setprio 0
	s_setprio 1
	v_mfma_f32_16x16x32_bf16 v[58:61], v[180:183], v[196:199], v[58:61]
	v_mfma_f32_16x16x32_bf16 v[58:61], v[184:187], v[200:203], v[58:61]
	v_mfma_f32_16x16x32_bf16 v[50:53], v[188:191], v[196:199], v[50:53]
	v_mfma_f32_16x16x32_bf16 v[50:53], v[192:195], v[200:203], v[50:53]
	v_mfma_f32_16x16x32_bf16 v[42:45], v[180:183], v[222:225], v[42:45]
	v_mfma_f32_16x16x32_bf16 v[42:45], v[184:187], v[226:229], v[42:45]
	v_mfma_f32_16x16x32_bf16 v[34:37], v[188:191], v[222:225], v[34:37]
	v_mfma_f32_16x16x32_bf16 v[34:37], v[192:195], v[226:229], v[34:37]
	v_mfma_f32_16x16x32_bf16 v[26:29], v[180:183], v[230:233], v[26:29]
	v_mfma_f32_16x16x32_bf16 v[26:29], v[184:187], v[234:237], v[26:29]
	v_mfma_f32_16x16x32_bf16 v[18:21], v[188:191], v[230:233], v[18:21]
	v_mfma_f32_16x16x32_bf16 v[18:21], v[192:195], v[234:237], v[18:21]
	v_mfma_f32_16x16x32_bf16 v[10:13], v[180:183], v[238:241], v[10:13]
	v_mfma_f32_16x16x32_bf16 v[10:13], v[184:187], v[242:245], v[10:13]
	v_mfma_f32_16x16x32_bf16 v[2:5], v[188:191], v[238:241], v[2:5]
	v_mfma_f32_16x16x32_bf16 v[2:5], v[192:195], v[242:245], v[2:5]
	s_setprio 0
	s_barrier
	v_add_u32_e32 v162, s84, v99
	v_add_u32_e32 v192, s88, v99
	ds_read_b128 v[150:153], v162
	ds_read_b128 v[154:157], v162 offset:1024
	ds_read_b128 v[158:161], v162 offset:2048
	ds_read_b128 v[162:165], v162 offset:3072
	ds_read_b128 v[180:183], v192
	ds_read_b128 v[184:187], v192 offset:1024
	ds_read_b128 v[188:191], v192 offset:2048
	ds_read_b128 v[192:195], v192 offset:3072
	s_mov_b32 m0, s59
	v_lshl_add_u64 v[246:247], s[42:43], 0, v[138:139]
	ds_read_b128 v[196:199], v149 offset:32768
	ds_read_b128 v[200:203], v149 offset:33792
	ds_read_b128 v[222:225], v149 offset:34816
	ds_read_b128 v[226:229], v149 offset:35840
	ds_read_b128 v[230:233], v149 offset:36864
	ds_read_b128 v[234:237], v149 offset:37888
	ds_read_b128 v[238:241], v149 offset:38912
	ds_read_b128 v[242:245], v149 offset:39936
	global_load_lds_dwordx4 v[246:247], off
	v_lshl_add_u64 v[246:247], s[42:43], 0, v[134:135]
	s_mov_b32 m0, s60
	s_nop 0
	global_load_lds_dwordx4 v[246:247], off
	s_waitcnt vmcnt(8)
	s_waitcnt lgkmcnt(0)
	s_barrier
	s_setprio 1
	s_waitcnt lgkmcnt(0)
	v_mfma_f32_16x16x32_bf16 v[128:131], v[150:153], v[196:199], v[128:131]
	v_mfma_f32_16x16x32_bf16 v[128:131], v[154:157], v[200:203], v[128:131]
	v_mfma_f32_16x16x32_bf16 v[120:123], v[158:161], v[196:199], v[120:123]
	v_mfma_f32_16x16x32_bf16 v[120:123], v[162:165], v[200:203], v[120:123]
	v_mfma_f32_16x16x32_bf16 v[112:115], v[150:153], v[222:225], v[112:115]
	v_mfma_f32_16x16x32_bf16 v[112:115], v[154:157], v[226:229], v[112:115]
	v_mfma_f32_16x16x32_bf16 v[104:107], v[158:161], v[222:225], v[104:107]
	v_mfma_f32_16x16x32_bf16 v[104:107], v[162:165], v[226:229], v[104:107]
	v_mfma_f32_16x16x32_bf16 v[94:97], v[150:153], v[230:233], v[94:97]
	v_mfma_f32_16x16x32_bf16 v[94:97], v[154:157], v[234:237], v[94:97]
	v_mfma_f32_16x16x32_bf16 v[86:89], v[158:161], v[230:233], v[86:89]
	v_mfma_f32_16x16x32_bf16 v[86:89], v[162:165], v[234:237], v[86:89]
	v_mfma_f32_16x16x32_bf16 v[78:81], v[150:153], v[238:241], v[78:81]
	v_mfma_f32_16x16x32_bf16 v[78:81], v[154:157], v[242:245], v[78:81]
	v_mfma_f32_16x16x32_bf16 v[70:73], v[158:161], v[238:241], v[70:73]
	v_mfma_f32_16x16x32_bf16 v[70:73], v[162:165], v[242:245], v[70:73]
	s_setprio 0
	s_setprio 1
	v_mfma_f32_16x16x32_bf16 v[124:127], v[180:183], v[196:199], v[124:127]
	v_mfma_f32_16x16x32_bf16 v[124:127], v[184:187], v[200:203], v[124:127]
	v_mfma_f32_16x16x32_bf16 v[116:119], v[188:191], v[196:199], v[116:119]
	v_mfma_f32_16x16x32_bf16 v[116:119], v[192:195], v[200:203], v[116:119]
	v_mfma_f32_16x16x32_bf16 v[108:111], v[180:183], v[222:225], v[108:111]
	v_mfma_f32_16x16x32_bf16 v[108:111], v[184:187], v[226:229], v[108:111]
	v_mfma_f32_16x16x32_bf16 v[100:103], v[188:191], v[222:225], v[100:103]
	v_mfma_f32_16x16x32_bf16 v[100:103], v[192:195], v[226:229], v[100:103]
	v_mfma_f32_16x16x32_bf16 v[90:93], v[180:183], v[230:233], v[90:93]
	v_mfma_f32_16x16x32_bf16 v[90:93], v[184:187], v[234:237], v[90:93]
	v_mfma_f32_16x16x32_bf16 v[82:85], v[188:191], v[230:233], v[82:85]
	v_mfma_f32_16x16x32_bf16 v[82:85], v[192:195], v[234:237], v[82:85]
	v_mfma_f32_16x16x32_bf16 v[74:77], v[180:183], v[238:241], v[74:77]
	v_mfma_f32_16x16x32_bf16 v[74:77], v[184:187], v[242:245], v[74:77]
	v_mfma_f32_16x16x32_bf16 v[66:69], v[188:191], v[238:241], v[66:69]
	v_mfma_f32_16x16x32_bf16 v[66:69], v[192:195], v[242:245], v[66:69]
	s_setprio 0
	s_barrier
; #define PG8_STAGE(bufoff, gbase, voff) do { _Pragma("unroll") for (int _i = 0; _i < 2; ++_i) \
;         __builtin_amdgcn_global_load_lds((const unsigned*)((const char*)(gbase) + (voff)[_i]), (PG8_LAS unsigned*)(lds + (bufoff) + ldsw + _i * 8192), 16, 0, AUX_A); } while (0)
; #define PG8_STAGEB(bufoff, gbase, voff) do { _Pragma("unroll") for (int _i = 0; _i < 2; ++_i) \
;         __builtin_amdgcn_global_load_lds((const unsigned*)((const char*)(gbase) + (voff)[_i]), (PG8_LAS unsigned*)(lds + (bufoff) + ldsw + _i * 8192), 16, 0, AUX_B); } while (0)
; template <class Epi, class Sched, bool ALIGN_EPI = false, bool SP2 = false>
; __device__ __forceinline__ void gemm_phase(PG8_LAS unsigned char* lds, const Gemm g, const Sched& S, const Epi& E) {
;     ...
;             PG8_LDA(At, 1, 1); PG8_STAGEB(PG8_SB(1, 0), b3, voffB); PG8_STAGEB(PG8_SB(1, 1), b3 + hstep, voffB); PG8_STAGE(PG8_SA(1, 0), a3, voffA);
;             PG8_WAIT_V(8); PG8_WAIT_L(0); PG8_BAR; PG8_MMA(1, 0, At, B0); PG8_MMA(1, 1, At, B1); PG8_BAR; PG8_SCHED;
;             } else {
;             PG8_LDB(B0, 0, 0); PG8_SCHED; PG8_LDA(At, 0, 0); PG8_STAGE(PG8_SA(1, 1), a1 + hstep, voffA);
;             PG8_WAIT_L(8); PG8_BAR; PG8_WAIT_L(0); PG8_MMA(0, 0, At, B0); PG8_BAR; PG8_SCHED;
;             PG8_LDB(B1, 0, 1); PG8_STAGEB(PG8_SB(0, 0), b2, voffB);
;             PG8_BAR; PG8_WAIT_L(0); PG8_MMA(0, 1, At, B1); PG8_BAR;
;             PG8_LDA(At, 0, 1); PG8_STAGE(PG8_SA(0, 0), a2, voffA);
;             PG8_BAR; PG8_WAIT_L(0); PG8_MMA(1, 0, At, B0); PG8_BAR; PG8_SCHED;
;             PG8_STAGEB(PG8_SB(0, 1), b2 + hstep, voffB);
;             PG8_WAIT_V(6); PG8_BAR; PG8_MMA(1, 1, At, B1); PG8_BAR;
;             PG8_LDB(B0, 1, 0); PG8_SCHED; PG8_LDA(At, 1, 0); PG8_STAGE(PG8_SA(0, 1), a2 + hstep, voffA);
;             PG8_WAIT_L(8); PG8_BAR; PG8_WAIT_L(0); PG8_MMA(0, 0, At, B0); PG8_BAR; PG8_SCHED;
;             PG8_LDB(B1, 1, 1); PG8_STAGEB(PG8_SB(1, 0), b3, voffB);
;             PG8_BAR; PG8_WAIT_L(0); PG8_MMA(0, 1, At, B1); PG8_BAR;
;             PG8_LDA(At, 1, 1); PG8_STAGE(PG8_SA(1, 0), a3, voffA);
;             PG8_BAR; PG8_WAIT_L(0); PG8_MMA(1, 0, At, B0); PG8_BAR; PG8_SCHED;
;             PG8_STAGEB(PG8_SB(1, 1), b3 + hstep, voffB);
;             PG8_WAIT_V(6); PG8_BAR; PG8_MMA(1, 1, At, B1); PG8_BAR;
;             }
;         }
;         if constexpr (ALIGN_EPI) { if (wr == 0) PG8_BAR; }
	s_mov_b32 m0, s1
	v_lshl_add_u64 v[166:167], v[166:167], 0, s[76:77]
	ds_read_b128 v[196:199], v149 offset:49152
	ds_read_b128 v[200:203], v149 offset:50176
	ds_read_b128 v[222:225], v149 offset:51200
	ds_read_b128 v[226:229], v149 offset:52224
	ds_read_b128 v[230:233], v149 offset:53248
	ds_read_b128 v[234:237], v149 offset:54272
	ds_read_b128 v[238:241], v149 offset:55296
	ds_read_b128 v[242:245], v149 offset:56320
	global_load_lds_dwordx4 v[166:167], off
	v_lshl_add_u64 v[166:167], v[168:169], 0, s[76:77]
	s_mov_b32 m0, s0
	s_nop 0
	global_load_lds_dwordx4 v[166:167], off
	v_lshl_add_u64 v[166:167], s[36:37], 0, v[136:137]
	s_mov_b32 m0, s46
	s_nop 0
	global_load_lds_dwordx4 v[166:167], off
	v_lshl_add_u64 v[166:167], s[36:37], 0, v[132:133]
	s_mov_b32 m0, s31
	s_nop 0
	global_load_lds_dwordx4 v[166:167], off
	v_lshl_add_u64 v[166:167], v[172:173], 0, s[76:77]
	s_mov_b32 m0, s61
	s_nop 0
	global_load_lds_dwordx4 v[166:167], off
	v_lshl_add_u64 v[166:167], v[212:213], 0, s[76:77]
	s_mov_b32 m0, s62
	s_nop 0
	global_load_lds_dwordx4 v[166:167], off
	s_waitcnt vmcnt(8)
	s_waitcnt lgkmcnt(0)
	s_barrier
	s_setprio 1
	s_waitcnt lgkmcnt(0)
	v_mfma_f32_16x16x32_bf16 v[62:65], v[150:153], v[196:199], v[62:65]
	v_mfma_f32_16x16x32_bf16 v[62:65], v[154:157], v[200:203], v[62:65]
	v_mfma_f32_16x16x32_bf16 v[54:57], v[158:161], v[196:199], v[54:57]
	v_mfma_f32_16x16x32_bf16 v[54:57], v[162:165], v[200:203], v[54:57]
	v_mfma_f32_16x16x32_bf16 v[46:49], v[150:153], v[222:225], v[46:49]
	v_mfma_f32_16x16x32_bf16 v[46:49], v[154:157], v[226:229], v[46:49]
	v_mfma_f32_16x16x32_bf16 v[38:41], v[158:161], v[222:225], v[38:41]
	v_mfma_f32_16x16x32_bf16 v[38:41], v[162:165], v[226:229], v[38:41]
	v_mfma_f32_16x16x32_bf16 v[30:33], v[150:153], v[230:233], v[30:33]
	v_mfma_f32_16x16x32_bf16 v[30:33], v[154:157], v[234:237], v[30:33]
	v_mfma_f32_16x16x32_bf16 v[22:25], v[158:161], v[230:233], v[22:25]
	v_mfma_f32_16x16x32_bf16 v[22:25], v[162:165], v[234:237], v[22:25]
	v_mfma_f32_16x16x32_bf16 v[14:17], v[150:153], v[238:241], v[14:17]
	v_mfma_f32_16x16x32_bf16 v[14:17], v[154:157], v[242:245], v[14:17]
	v_mfma_f32_16x16x32_bf16 v[6:9], v[158:161], v[238:241], v[6:9]
	v_mfma_f32_16x16x32_bf16 v[6:9], v[162:165], v[242:245], v[6:9]
	s_setprio 0
	s_setprio 1
	v_mfma_f32_16x16x32_bf16 v[58:61], v[180:183], v[196:199], v[58:61]
	v_mfma_f32_16x16x32_bf16 v[58:61], v[184:187], v[200:203], v[58:61]
	v_mfma_f32_16x16x32_bf16 v[50:53], v[188:191], v[196:199], v[50:53]
	v_mfma_f32_16x16x32_bf16 v[50:53], v[192:195], v[200:203], v[50:53]
	v_mfma_f32_16x16x32_bf16 v[42:45], v[180:183], v[222:225], v[42:45]
	v_mfma_f32_16x16x32_bf16 v[42:45], v[184:187], v[226:229], v[42:45]
	v_mfma_f32_16x16x32_bf16 v[34:37], v[188:191], v[222:225], v[34:37]
	v_mfma_f32_16x16x32_bf16 v[34:37], v[192:195], v[226:229], v[34:37]
	v_mfma_f32_16x16x32_bf16 v[26:29], v[180:183], v[230:233], v[26:29]
	v_mfma_f32_16x16x32_bf16 v[26:29], v[184:187], v[234:237], v[26:29]
	v_mfma_f32_16x16x32_bf16 v[18:21], v[188:191], v[230:233], v[18:21]
	v_mfma_f32_16x16x32_bf16 v[18:21], v[192:195], v[234:237], v[18:21]
	v_mfma_f32_16x16x32_bf16 v[10:13], v[180:183], v[238:241], v[10:13]
	v_mfma_f32_16x16x32_bf16 v[10:13], v[184:187], v[242:245], v[10:13]
	v_mfma_f32_16x16x32_bf16 v[2:5], v[188:191], v[238:241], v[2:5]
	v_mfma_f32_16x16x32_bf16 v[2:5], v[192:195], v[242:245], v[2:5]
	s_setprio 0
	s_barrier
	v_lshl_add_u64 v[144:145], v[144:145], 0, s[86:87]
	v_lshl_add_u64 v[146:147], v[146:147], 0, s[86:87]
	s_mov_b32 s29, s30
	s_cbranch_scc0 .LBB0_1458
	s_and_b64 vcc, exec, s[10:11]
	s_cbranch_vccz .LBB0_1461
	s_barrier

; #define PG8_STAGE(bufoff, gbase, voff) do { _Pragma("unroll") for (int _i = 0; _i < 2; ++_i) \
;         __builtin_amdgcn_global_load_lds((const unsigned*)((const char*)(gbase) + (voff)[_i]), (PG8_LAS unsigned*)(lds + (bufoff) + ldsw + _i * 8192), 16, 0, AUX_A); } while (0)
; #define PG8_STAGEB(bufoff, gbase, voff) do { _Pragma("unroll") for (int _i = 0; _i < 2; ++_i) \
;         __builtin_amdgcn_global_load_lds((const unsigned*)((const char*)(gbase) + (voff)[_i]), (PG8_LAS unsigned*)(lds + (bufoff) + ldsw + _i * 8192), 16, 0, AUX_B); } while (0)
; #define PG8_LDA(dst, b, h) do { _Pragma("unroll") for (int m = 0; m < 4; ++m) _Pragma("unroll") for (int k = 0; k < 2; ++k) dst[m][k] = *(const PG8_LAS bf16x8*)(lds + PG8_SA(b, h) + aoff + m * 2048 + k * 1024); } while (0)
; #define PG8_LDB(dst, b, h) do { _Pragma("unroll") for (int n = 0; n < 2; ++n) _Pragma("unroll") for (int k = 0; k < 2; ++k) dst[n][k] = *(const PG8_LAS bf16x8*)(lds + PG8_SB(b, h) + boff + n * 2048 + k * 1024); } while (0)
; #define PG8_WAIT_V(n) asm volatile("s_waitcnt vmcnt(" #n ")" ::: "memory")
; #define PG8_WAIT_L(n) asm volatile("s_waitcnt lgkmcnt(" #n ")" ::: "memory")
; template <class Epi, class Sched, bool ALIGN_EPI = false, bool SP2 = false>
; __device__ __forceinline__ void gemm_phase(PG8_LAS unsigned char* lds, const Gemm g, const Sched& S, const Epi& E) {
;     ...
;         const char* nAr = has_next ? nA + (size_t)nxt.krot * kstep : PG8_KP(cA, 0, rot, nt); const char* nBr = has_next ? nB + (size_t)nxt.krot * kstep : PG8_KP(cB, 0, rot, nt);
;         for (int t = 0; t < nt; t += 2) {
;             const bool last = (t == nt - 2);
;             const char* a1 = PG8_KP(cA, t + 1, rot, nt);
;             const char* a2 = last ? nAr : PG8_KP(cA, t + 2, rot, nt); const char* b2 = last ? nBr : PG8_KP(cB, t + 2, rot, nt);
;             const char* a3 = a2 + kstep; const char* b3 = b2 + kstep;
;             if (last && has_next) S.a_ready(nxt);
;             if constexpr (SP2) {
;             PG8_LDB(B0, 0, 0); PG8_LDB(B1, 0, 1); PG8_SCHED; PG8_LDA(At, 0, 0); PG8_STAGE(PG8_SA(1, 1), a1 + hstep, voffA);
;             PG8_WAIT_V(8); PG8_WAIT_L(0); PG8_BAR; PG8_MMA(0, 0, At, B0); PG8_MMA(0, 1, At, B1); PG8_BAR; PG8_SCHED;
;             PG8_LDA(At, 0, 1); PG8_STAGEB(PG8_SB(0, 0), b2, voffB); PG8_STAGEB(PG8_SB(0, 1), b2 + hstep, voffB); PG8_STAGE(PG8_SA(0, 0), a2, voffA);
.LBB0_1654:
	s_or_b32 s0, s15, 1
	s_cmp_ge_i32 s0, s82
	s_cselect_b32 s2, s82, 0
	s_add_i32 s15, s15, 2
	s_cmp_ge_i32 s15, s82
	s_cselect_b32 s0, s82, 0
	s_sub_i32 s0, s83, s0
	s_ashr_i32 s1, s0, 31
	s_lshl_b64 s[0:1], s[0:1], 7
	s_add_u32 s29, s38, s0
	s_addc_u32 s42, s39, s1
	s_add_u32 s0, s34, s0
	s_addc_u32 s1, s35, s1
	s_cmp_eq_u32 s82, s83
	s_cselect_b32 s45, s41, s42
	s_cselect_b32 s44, s40, s29
	s_cselect_b32 s43, s19, s1
	s_cselect_b32 s42, s18, s0
	s_add_i32 s29, 0, 0x10000
	s_add_i32 s46, 0, 0x14000
	v_add_u32_e32 v148, s29, v99
	v_add_u32_e32 v168, s46, v99
	ds_read_b128 v[136:139], v148
	ds_read_b128 v[140:143], v148 offset:1024
	ds_read_b128 v[144:147], v148 offset:2048
	ds_read_b128 v[148:151], v148 offset:3072
	ds_read_b128 v[152:155], v168
	ds_read_b128 v[180:183], v168 offset:1024
	ds_read_b128 v[184:187], v168 offset:2048
	ds_read_b128 v[190:193], v168 offset:3072
	v_mad_i64_i32 v[168:169], s[0:1], s2, v220, v[134:135]
	s_add_i32 m0, s50, 0xc000
	ds_read_b128 v[194:197], v189
	ds_read_b128 v[198:201], v189 offset:1024
	ds_read_b128 v[222:225], v189 offset:2048
	ds_read_b128 v[226:229], v189 offset:3072
	ds_read_b128 v[230:233], v189 offset:4096
	ds_read_b128 v[234:237], v189 offset:5120
	ds_read_b128 v[238:241], v189 offset:6144
	ds_read_b128 v[242:245], v189 offset:7168
	global_load_lds_dwordx4 v[168:169], off
	v_mad_i64_i32 v[168:169], s[0:1], s2, v220, v[132:133]
	s_add_i32 m0, s50, 0xe000
	s_nop 0
	global_load_lds_dwordx4 v[168:169], off
	s_waitcnt vmcnt(8)
	s_waitcnt lgkmcnt(0)
	s_barrier
	s_setprio 1
	s_waitcnt lgkmcnt(0)
	v_mfma_f32_16x16x32_bf16 v[128:131], v[136:139], v[194:197], v[128:131]
	v_mfma_f32_16x16x32_bf16 v[128:131], v[140:143], v[198:201], v[128:131]
	v_mfma_f32_16x16x32_bf16 v[124:127], v[144:147], v[194:197], v[124:127]
	v_mfma_f32_16x16x32_bf16 v[124:127], v[148:151], v[198:201], v[124:127]
	v_mfma_f32_16x16x32_bf16 v[120:123], v[136:139], v[222:225], v[120:123]
	v_mfma_f32_16x16x32_bf16 v[120:123], v[140:143], v[226:229], v[120:123]
	v_mfma_f32_16x16x32_bf16 v[112:115], v[144:147], v[222:225], v[112:115]
	v_mfma_f32_16x16x32_bf16 v[112:115], v[148:151], v[226:229], v[112:115]
	v_mfma_f32_16x16x32_bf16 v[104:107], v[136:139], v[230:233], v[104:107]
	v_mfma_f32_16x16x32_bf16 v[104:107], v[140:143], v[234:237], v[104:107]
	v_mfma_f32_16x16x32_bf16 v[94:97], v[144:147], v[230:233], v[94:97]
	v_mfma_f32_16x16x32_bf16 v[94:97], v[148:151], v[234:237], v[94:97]
	v_mfma_f32_16x16x32_bf16 v[86:89], v[136:139], v[238:241], v[86:89]
	v_mfma_f32_16x16x32_bf16 v[86:89], v[140:143], v[242:245], v[86:89]
	v_mfma_f32_16x16x32_bf16 v[78:81], v[144:147], v[238:241], v[78:81]
	v_mfma_f32_16x16x32_bf16 v[78:81], v[148:151], v[242:245], v[78:81]
	s_setprio 0
	s_setprio 1
	v_mfma_f32_16x16x32_bf16 v[116:119], v[152:155], v[194:197], v[116:119]
	v_mfma_f32_16x16x32_bf16 v[116:119], v[180:183], v[198:201], v[116:119]
	v_mfma_f32_16x16x32_bf16 v[108:111], v[184:187], v[194:197], v[108:111]
	v_mfma_f32_16x16x32_bf16 v[108:111], v[190:193], v[198:201], v[108:111]
	v_mfma_f32_16x16x32_bf16 v[100:103], v[152:155], v[222:225], v[100:103]
	v_mfma_f32_16x16x32_bf16 v[100:103], v[180:183], v[226:229], v[100:103]
	v_mfma_f32_16x16x32_bf16 v[90:93], v[184:187], v[222:225], v[90:93]
	v_mfma_f32_16x16x32_bf16 v[90:93], v[190:193], v[226:229], v[90:93]
	v_mfma_f32_16x16x32_bf16 v[82:85], v[152:155], v[230:233], v[82:85]
	v_mfma_f32_16x16x32_bf16 v[82:85], v[180:183], v[234:237], v[82:85]
	v_mfma_f32_16x16x32_bf16 v[74:77], v[184:187], v[230:233], v[74:77]
	v_mfma_f32_16x16x32_bf16 v[74:77], v[190:193], v[234:237], v[74:77]
	v_mfma_f32_16x16x32_bf16 v[70:73], v[152:155], v[238:241], v[70:73]
	v_mfma_f32_16x16x32_bf16 v[70:73], v[180:183], v[242:245], v[70:73]
	v_mfma_f32_16x16x32_bf16 v[66:69], v[184:187], v[238:241], v[66:69]
	v_mfma_f32_16x16x32_bf16 v[66:69], v[190:193], v[242:245], v[66:69]
	s_setprio 0
	s_barrier
	s_add_i32 s0, s29, s49
	v_lshl_add_u64 v[168:169], s[42:43], 0, v[160:161]
	s_mov_b32 m0, s0
	ds_read_b128 v[194:197], v189 offset:16384
	ds_read_b128 v[198:201], v189 offset:17408
	ds_read_b128 v[222:225], v189 offset:18432
	ds_read_b128 v[226:229], v189 offset:19456
	ds_read_b128 v[230:233], v189 offset:20480
	ds_read_b128 v[234:237], v189 offset:21504
	ds_read_b128 v[238:241], v189 offset:22528
	ds_read_b128 v[242:245], v189 offset:23552
	global_load_lds_dwordx4 v[168:169], off
	s_add_i32 m0, s0, 0x2000
	s_add_u32 s0, s42, 0x160000
	v_lshl_add_u64 v[172:173], s[42:43], 0, v[156:157]
	s_addc_u32 s1, s43, 0
	s_add_i32 s2, s46, s49
	global_load_lds_dwordx4 v[172:173], off
	v_lshl_add_u64 v[202:203], s[0:1], 0, v[160:161]
	s_mov_b32 m0, s2
	v_lshl_add_u64 v[212:213], s[44:45], 0, v[158:159]
	global_load_lds_dwordx4 v[202:203], off
	v_lshl_add_u64 v[202:203], s[0:1], 0, v[156:157]
	s_add_i32 m0, s2, 0x2000
	s_nop 0
	global_load_lds_dwordx4 v[202:203], off
	v_lshl_add_u64 v[202:203], s[44:45], 0, v[162:163]
	s_mov_b32 m0, s50
	s_nop 0
	global_load_lds_dwordx4 v[202:203], off
	s_mov_b32 m0, s51
	s_nop 0
	global_load_lds_dwordx4 v[212:213], off
	s_waitcnt vmcnt(8)
	s_waitcnt lgkmcnt(0)
	s_barrier
; #define PG8_STAGE(bufoff, gbase, voff) do { _Pragma("unroll") for (int _i = 0; _i < 2; ++_i) \
;         __builtin_amdgcn_global_load_lds((const unsigned*)((const char*)(gbase) + (voff)[_i]), (PG8_LAS unsigned*)(lds + (bufoff) + ldsw + _i * 8192), 16, 0, AUX_A); } while (0)
; #define PG8_LDA(dst, b, h) do { _Pragma("unroll") for (int m = 0; m < 4; ++m) _Pragma("unroll") for (int k = 0; k < 2; ++k) dst[m][k] = *(const PG8_LAS bf16x8*)(lds + PG8_SA(b, h) + aoff + m * 2048 + k * 1024); } while (0)
; #define PG8_LDB(dst, b, h) do { _Pragma("unroll") for (int n = 0; n < 2; ++n) _Pragma("unroll") for (int k = 0; k < 2; ++k) dst[n][k] = *(const PG8_LAS bf16x8*)(lds + PG8_SB(b, h) + boff + n * 2048 + k * 1024); } while (0)
; #define PG8_MMA(ai, bj, At, Bt) do { __builtin_amdgcn_s_setprio(1); _Pragma("unroll") for (int m = 0; m < 4; ++m) _Pragma("unroll") for (int n = 0; n < 2; ++n) _Pragma("unroll") for (int k = 0; k < 2; ++k) \
;         acc[ai][bj][m][n] = __builtin_amdgcn_mfma_f32_16x16x32_bf16(Bt[n][k], At[m][k], acc[ai][bj][m][n], 0, 0, 0); __builtin_amdgcn_s_setprio(0); } while (0)
; #define PG8_WAIT_V(n) asm volatile("s_waitcnt vmcnt(" #n ")" ::: "memory")
; #define PG8_WAIT_L(n) asm volatile("s_waitcnt lgkmcnt(" #n ")" ::: "memory")
; #define PG8_BAR __builtin_amdgcn_s_barrier()
; #define PG8_SCHED __builtin_amdgcn_sched_barrier(0)
; template <class Epi, class Sched, bool ALIGN_EPI = false, bool SP2 = false>
; __device__ __forceinline__ void gemm_phase(PG8_LAS unsigned char* lds, const Gemm g, const Sched& S, const Epi& E) {
;     ...
;             PG8_WAIT_V(8); PG8_WAIT_L(0); PG8_BAR; PG8_MMA(1, 0, At, B0); PG8_MMA(1, 1, At, B1); PG8_BAR; PG8_SCHED;
;             PG8_LDB(B0, 1, 0); PG8_LDB(B1, 1, 1); PG8_SCHED; PG8_LDA(At, 1, 0); PG8_STAGE(PG8_SA(0, 1), a2 + hstep, voffA);
;             PG8_WAIT_V(8); PG8_WAIT_L(0); PG8_BAR; PG8_MMA(0, 0, At, B0); PG8_MMA(0, 1, At, B1); PG8_BAR; PG8_SCHED;
	s_setprio 1
	s_waitcnt lgkmcnt(0)
	v_mfma_f32_16x16x32_bf16 v[62:65], v[136:139], v[194:197], v[62:65]
	v_mfma_f32_16x16x32_bf16 v[62:65], v[140:143], v[198:201], v[62:65]
	v_mfma_f32_16x16x32_bf16 v[58:61], v[144:147], v[194:197], v[58:61]
	v_mfma_f32_16x16x32_bf16 v[58:61], v[148:151], v[198:201], v[58:61]
	v_mfma_f32_16x16x32_bf16 v[54:57], v[136:139], v[222:225], v[54:57]
	v_mfma_f32_16x16x32_bf16 v[54:57], v[140:143], v[226:229], v[54:57]
	v_mfma_f32_16x16x32_bf16 v[46:49], v[144:147], v[222:225], v[46:49]
	v_mfma_f32_16x16x32_bf16 v[46:49], v[148:151], v[226:229], v[46:49]
	v_mfma_f32_16x16x32_bf16 v[38:41], v[136:139], v[230:233], v[38:41]
	v_mfma_f32_16x16x32_bf16 v[38:41], v[140:143], v[234:237], v[38:41]
	v_mfma_f32_16x16x32_bf16 v[30:33], v[144:147], v[230:233], v[30:33]
	v_mfma_f32_16x16x32_bf16 v[30:33], v[148:151], v[234:237], v[30:33]
	v_mfma_f32_16x16x32_bf16 v[22:25], v[136:139], v[238:241], v[22:25]
	v_mfma_f32_16x16x32_bf16 v[22:25], v[140:143], v[242:245], v[22:25]
	v_mfma_f32_16x16x32_bf16 v[14:17], v[144:147], v[238:241], v[14:17]
	v_mfma_f32_16x16x32_bf16 v[14:17], v[148:151], v[242:245], v[14:17]
	s_setprio 0
	s_setprio 1
	v_mfma_f32_16x16x32_bf16 v[50:53], v[152:155], v[194:197], v[50:53]
	v_mfma_f32_16x16x32_bf16 v[50:53], v[180:183], v[198:201], v[50:53]
	v_mfma_f32_16x16x32_bf16 v[42:45], v[184:187], v[194:197], v[42:45]
	v_mfma_f32_16x16x32_bf16 v[42:45], v[190:193], v[198:201], v[42:45]
	v_mfma_f32_16x16x32_bf16 v[34:37], v[152:155], v[222:225], v[34:37]
	v_mfma_f32_16x16x32_bf16 v[34:37], v[180:183], v[226:229], v[34:37]
	v_mfma_f32_16x16x32_bf16 v[26:29], v[184:187], v[222:225], v[26:29]
	v_mfma_f32_16x16x32_bf16 v[26:29], v[190:193], v[226:229], v[26:29]
	v_mfma_f32_16x16x32_bf16 v[18:21], v[152:155], v[230:233], v[18:21]
	v_mfma_f32_16x16x32_bf16 v[18:21], v[180:183], v[234:237], v[18:21]
	v_mfma_f32_16x16x32_bf16 v[10:13], v[184:187], v[230:233], v[10:13]
	v_mfma_f32_16x16x32_bf16 v[10:13], v[190:193], v[234:237], v[10:13]
	v_mfma_f32_16x16x32_bf16 v[6:9], v[152:155], v[238:241], v[6:9]
	v_mfma_f32_16x16x32_bf16 v[6:9], v[180:183], v[242:245], v[6:9]
	v_mfma_f32_16x16x32_bf16 v[2:5], v[184:187], v[238:241], v[2:5]
	v_mfma_f32_16x16x32_bf16 v[2:5], v[190:193], v[242:245], v[2:5]
	s_setprio 0
	s_barrier
	s_add_i32 s2, 0, 0x18000
	s_add_i32 s29, 0, 0x1c000
	v_add_u32_e32 v148, s2, v99
	v_add_u32_e32 v190, s29, v99
	ds_read_b128 v[136:139], v148
	ds_read_b128 v[140:143], v148 offset:1024
	ds_read_b128 v[144:147], v148 offset:2048
	ds_read_b128 v[148:151], v148 offset:3072
	ds_read_b128 v[152:155], v190
	ds_read_b128 v[180:183], v190 offset:1024
	ds_read_b128 v[184:187], v190 offset:2048
	ds_read_b128 v[190:193], v190 offset:3072
	s_add_u32 s0, s44, 0x160000
	s_addc_u32 s1, s45, 0
	s_mov_b32 m0, s52
	v_lshl_add_u64 v[246:247], s[0:1], 0, v[162:163]
	ds_read_b128 v[194:197], v189 offset:32768
	ds_read_b128 v[198:201], v189 offset:33792
	ds_read_b128 v[222:225], v189 offset:34816
	ds_read_b128 v[226:229], v189 offset:35840
	ds_read_b128 v[230:233], v189 offset:36864
	ds_read_b128 v[234:237], v189 offset:37888
	ds_read_b128 v[238:241], v189 offset:38912
	ds_read_b128 v[242:245], v189 offset:39936
	global_load_lds_dwordx4 v[246:247], off
	v_lshl_add_u64 v[246:247], s[0:1], 0, v[158:159]
	s_mov_b32 m0, s53
	s_nop 0
	global_load_lds_dwordx4 v[246:247], off
	s_waitcnt vmcnt(8)
	s_waitcnt lgkmcnt(0)
	s_barrier
	s_setprio 1
	s_waitcnt lgkmcnt(0)
	v_mfma_f32_16x16x32_bf16 v[128:131], v[136:139], v[194:197], v[128:131]
	v_mfma_f32_16x16x32_bf16 v[128:131], v[140:143], v[198:201], v[128:131]
	v_mfma_f32_16x16x32_bf16 v[124:127], v[144:147], v[194:197], v[124:127]
	v_mfma_f32_16x16x32_bf16 v[124:127], v[148:151], v[198:201], v[124:127]
	v_mfma_f32_16x16x32_bf16 v[120:123], v[136:139], v[222:225], v[120:123]
	v_mfma_f32_16x16x32_bf16 v[120:123], v[140:143], v[226:229], v[120:123]
	v_mfma_f32_16x16x32_bf16 v[112:115], v[144:147], v[222:225], v[112:115]
	v_mfma_f32_16x16x32_bf16 v[112:115], v[148:151], v[226:229], v[112:115]
	v_mfma_f32_16x16x32_bf16 v[104:107], v[136:139], v[230:233], v[104:107]
	v_mfma_f32_16x16x32_bf16 v[104:107], v[140:143], v[234:237], v[104:107]
	v_mfma_f32_16x16x32_bf16 v[94:97], v[144:147], v[230:233], v[94:97]
	v_mfma_f32_16x16x32_bf16 v[94:97], v[148:151], v[234:237], v[94:97]
	v_mfma_f32_16x16x32_bf16 v[86:89], v[136:139], v[238:241], v[86:89]
	v_mfma_f32_16x16x32_bf16 v[86:89], v[140:143], v[242:245], v[86:89]
	v_mfma_f32_16x16x32_bf16 v[78:81], v[144:147], v[238:241], v[78:81]
	v_mfma_f32_16x16x32_bf16 v[78:81], v[148:151], v[242:245], v[78:81]
	s_setprio 0
	s_setprio 1
	v_mfma_f32_16x16x32_bf16 v[116:119], v[152:155], v[194:197], v[116:119]
	v_mfma_f32_16x16x32_bf16 v[116:119], v[180:183], v[198:201], v[116:119]
	v_mfma_f32_16x16x32_bf16 v[108:111], v[184:187], v[194:197], v[108:111]
	v_mfma_f32_16x16x32_bf16 v[108:111], v[190:193], v[198:201], v[108:111]
	v_mfma_f32_16x16x32_bf16 v[100:103], v[152:155], v[222:225], v[100:103]
	v_mfma_f32_16x16x32_bf16 v[100:103], v[180:183], v[226:229], v[100:103]
	v_mfma_f32_16x16x32_bf16 v[90:93], v[184:187], v[222:225], v[90:93]
	v_mfma_f32_16x16x32_bf16 v[90:93], v[190:193], v[226:229], v[90:93]
	v_mfma_f32_16x16x32_bf16 v[82:85], v[152:155], v[230:233], v[82:85]
	v_mfma_f32_16x16x32_bf16 v[82:85], v[180:183], v[234:237], v[82:85]
	v_mfma_f32_16x16x32_bf16 v[74:77], v[184:187], v[230:233], v[74:77]
	v_mfma_f32_16x16x32_bf16 v[74:77], v[190:193], v[234:237], v[74:77]
	v_mfma_f32_16x16x32_bf16 v[70:73], v[152:155], v[238:241], v[70:73]
	v_mfma_f32_16x16x32_bf16 v[70:73], v[180:183], v[242:245], v[70:73]
	v_mfma_f32_16x16x32_bf16 v[66:69], v[184:187], v[238:241], v[66:69]
	v_mfma_f32_16x16x32_bf16 v[66:69], v[190:193], v[242:245], v[66:69]
	s_setprio 0
	s_barrier
; #define PG8_STAGE(bufoff, gbase, voff) do { _Pragma("unroll") for (int _i = 0; _i < 2; ++_i) \
;         __builtin_amdgcn_global_load_lds((const unsigned*)((const char*)(gbase) + (voff)[_i]), (PG8_LAS unsigned*)(lds + (bufoff) + ldsw + _i * 8192), 16, 0, AUX_A); } while (0)
; #define PG8_STAGEB(bufoff, gbase, voff) do { _Pragma("unroll") for (int _i = 0; _i < 2; ++_i) \
;         __builtin_amdgcn_global_load_lds((const unsigned*)((const char*)(gbase) + (voff)[_i]), (PG8_LAS unsigned*)(lds + (bufoff) + ldsw + _i * 8192), 16, 0, AUX_B); } while (0)
; #define PG8_LDA(dst, b, h) do { _Pragma("unroll") for (int m = 0; m < 4; ++m) _Pragma("unroll") for (int k = 0; k < 2; ++k) dst[m][k] = *(const PG8_LAS bf16x8*)(lds + PG8_SA(b, h) + aoff + m * 2048 + k * 1024); } while (0)
; #define PG8_MMA(ai, bj, At, Bt) do { __builtin_amdgcn_s_setprio(1); _Pragma("unroll") for (int m = 0; m < 4; ++m) _Pragma("unroll") for (int n = 0; n < 2; ++n) _Pragma("unroll") for (int k = 0; k < 2; ++k) \
;         acc[ai][bj][m][n] = __builtin_amdgcn_mfma_f32_16x16x32_bf16(Bt[n][k], At[m][k], acc[ai][bj][m][n], 0, 0, 0); __builtin_amdgcn_s_setprio(0); } while (0)
; #define PG8_WAIT_V(n) asm volatile("s_waitcnt vmcnt(" #n ")" ::: "memory")
; #define PG8_WAIT_L(n) asm volatile("s_waitcnt lgkmcnt(" #n ")" ::: "memory")
; #define PG8_BAR __builtin_amdgcn_s_barrier()
; #define PG8_SCHED __builtin_amdgcn_sched_barrier(0)
; template <class Epi, class Sched, bool ALIGN_EPI = false, bool SP2 = false>
; __device__ __forceinline__ void gemm_phase(PG8_LAS unsigned char* lds, const Gemm g, const Sched& S, const Epi& E) {
;     ...
;             PG8_LDA(At, 1, 1); PG8_STAGEB(PG8_SB(1, 0), b3, voffB); PG8_STAGEB(PG8_SB(1, 1), b3 + hstep, voffB); PG8_STAGE(PG8_SA(1, 0), a3, voffA);
;             PG8_WAIT_V(8); PG8_WAIT_L(0); PG8_BAR; PG8_MMA(1, 0, At, B0); PG8_MMA(1, 1, At, B1); PG8_BAR; PG8_SCHED;
	s_add_i32 s0, s2, s49
	v_lshl_add_u64 v[168:169], v[168:169], 0, s[76:77]
	s_mov_b32 m0, s0
	ds_read_b128 v[194:197], v189 offset:49152
	ds_read_b128 v[198:201], v189 offset:50176
	ds_read_b128 v[222:225], v189 offset:51200
	ds_read_b128 v[226:229], v189 offset:52224
	ds_read_b128 v[230:233], v189 offset:53248
	ds_read_b128 v[234:237], v189 offset:54272
	ds_read_b128 v[238:241], v189 offset:55296
	ds_read_b128 v[242:245], v189 offset:56320
	global_load_lds_dwordx4 v[168:169], off
	s_add_i32 m0, s0, 0x2000
	s_add_u32 s0, s42, 0x160080
	v_lshl_add_u64 v[168:169], v[172:173], 0, s[76:77]
	s_addc_u32 s1, s43, 0
	s_add_i32 s2, s29, s49
	global_load_lds_dwordx4 v[168:169], off
	v_lshl_add_u64 v[168:169], s[0:1], 0, v[160:161]
	s_mov_b32 m0, s2
	s_nop 0
	global_load_lds_dwordx4 v[168:169], off
	v_lshl_add_u64 v[168:169], s[0:1], 0, v[156:157]
	s_add_i32 m0, s2, 0x2000
	s_nop 0
	global_load_lds_dwordx4 v[168:169], off
	v_lshl_add_u64 v[168:169], v[202:203], 0, s[76:77]
	s_mov_b32 m0, s60
	s_nop 0
	global_load_lds_dwordx4 v[168:169], off
	v_lshl_add_u64 v[168:169], v[212:213], 0, s[76:77]
	s_mov_b32 m0, s61
	s_nop 0
	global_load_lds_dwordx4 v[168:169], off
	s_waitcnt vmcnt(8)
	s_waitcnt lgkmcnt(0)
	s_barrier
	s_setprio 1
	s_waitcnt lgkmcnt(0)
	v_mfma_f32_16x16x32_bf16 v[62:65], v[136:139], v[194:197], v[62:65]
	v_mfma_f32_16x16x32_bf16 v[62:65], v[140:143], v[198:201], v[62:65]
	v_mfma_f32_16x16x32_bf16 v[58:61], v[144:147], v[194:197], v[58:61]
	v_mfma_f32_16x16x32_bf16 v[58:61], v[148:151], v[198:201], v[58:61]
	v_mfma_f32_16x16x32_bf16 v[54:57], v[136:139], v[222:225], v[54:57]
	v_mfma_f32_16x16x32_bf16 v[54:57], v[140:143], v[226:229], v[54:57]
	v_mfma_f32_16x16x32_bf16 v[46:49], v[144:147], v[222:225], v[46:49]
	v_mfma_f32_16x16x32_bf16 v[46:49], v[148:151], v[226:229], v[46:49]
	v_mfma_f32_16x16x32_bf16 v[38:41], v[136:139], v[230:233], v[38:41]
	v_mfma_f32_16x16x32_bf16 v[38:41], v[140:143], v[234:237], v[38:41]
	v_mfma_f32_16x16x32_bf16 v[30:33], v[144:147], v[230:233], v[30:33]
	v_mfma_f32_16x16x32_bf16 v[30:33], v[148:151], v[234:237], v[30:33]
	v_mfma_f32_16x16x32_bf16 v[22:25], v[136:139], v[238:241], v[22:25]
	v_mfma_f32_16x16x32_bf16 v[22:25], v[140:143], v[242:245], v[22:25]
	v_mfma_f32_16x16x32_bf16 v[14:17], v[144:147], v[238:241], v[14:17]
	v_mfma_f32_16x16x32_bf16 v[14:17], v[148:151], v[242:245], v[14:17]
	s_setprio 0
	s_setprio 1
	v_mfma_f32_16x16x32_bf16 v[50:53], v[152:155], v[194:197], v[50:53]
	v_mfma_f32_16x16x32_bf16 v[50:53], v[180:183], v[198:201], v[50:53]
	v_mfma_f32_16x16x32_bf16 v[42:45], v[184:187], v[194:197], v[42:45]
	v_mfma_f32_16x16x32_bf16 v[42:45], v[190:193], v[198:201], v[42:45]
	v_mfma_f32_16x16x32_bf16 v[34:37], v[152:155], v[222:225], v[34:37]
	v_mfma_f32_16x16x32_bf16 v[34:37], v[180:183], v[226:229], v[34:37]
	v_mfma_f32_16x16x32_bf16 v[26:29], v[184:187], v[222:225], v[26:29]
	v_mfma_f32_16x16x32_bf16 v[26:29], v[190:193], v[226:229], v[26:29]
	v_mfma_f32_16x16x32_bf16 v[18:21], v[152:155], v[230:233], v[18:21]
	v_mfma_f32_16x16x32_bf16 v[18:21], v[180:183], v[234:237], v[18:21]
	v_mfma_f32_16x16x32_bf16 v[10:13], v[184:187], v[230:233], v[10:13]
	v_mfma_f32_16x16x32_bf16 v[10:13], v[190:193], v[234:237], v[10:13]
	v_mfma_f32_16x16x32_bf16 v[6:9], v[152:155], v[238:241], v[6:9]
	v_mfma_f32_16x16x32_bf16 v[6:9], v[180:183], v[242:245], v[6:9]
	v_mfma_f32_16x16x32_bf16 v[2:5], v[184:187], v[238:241], v[2:5]
	v_mfma_f32_16x16x32_bf16 v[2:5], v[190:193], v[242:245], v[2:5]
	s_setprio 0
	s_barrier
	s_add_i32 s0, s83, 2
	v_lshl_add_u64 v[132:133], v[132:133], 0, s[86:87]
	v_lshl_add_u64 v[134:135], v[134:135], 0, s[86:87]
	s_cmp_ge_i32 s83, s82
	s_mov_b32 s83, s0
	s_cbranch_scc0 .LBB0_1654
	s_and_b64 vcc, exec, s[12:13]
	s_cbranch_vccz .LBB0_1657
	s_barrier
